# GEMM K loops: first iteration peeled, first MFMA into each accumulator takes C = inline 0; the 128 accumulator-zeroing v_mov per tile removed
# speedup vs baseline: 1.0082x; 1.0082x over previous
.LBB0_219:
	s_ashr_i32 s17, s16, 31
	s_lshl_b64 s[18:19], s[16:17], 19
	s_add_u32 s18, s42, s18
	s_addc_u32 s19, s43, s19
	s_and_b64 s[20:21], s[2:3], exec
	s_cselect_b32 s17, s19, s25
	s_cselect_b32 s65, s18, s24
	s_ashr_i32 s15, s14, 31
	s_lshl_b64 s[20:21], s[14:15], 19
	s_add_u32 s20, s40, s20
	s_addc_u32 s21, s41, s21
	s_and_b64 s[34:35], s[2:3], exec
	s_cselect_b32 s15, s21, s27
	s_cselect_b32 s66, s20, s26
	s_add_u32 s24, s24, 0x40080
	s_addc_u32 s25, s25, 0
	s_add_u32 s67, s26, 0x100
	s_addc_u32 s68, s27, 0
	s_mov_b32 s69, -2
	s_waitcnt lgkmcnt(0)
	ds_read_b128 v[104:107], v171
	ds_read_b128 v[108:111], v171 offset:1024
	ds_read_b128 v[112:115], v171 offset:2048
	ds_read_b128 v[116:119], v171 offset:3072
	ds_read_b128 v[160:163], v172
	ds_read_b128 v[164:167], v172 offset:1024
	ds_read_b128 v[178:181], v172 offset:2048
	ds_read_b128 v[182:185], v172 offset:3072
	s_add_u32 s26, s24, 0xfffc0080
	s_addc_u32 s27, s25, -1
	s_cmp_eq_u32 s69, 12
	s_cselect_b32 s35, s17, s27
	s_cselect_b32 s34, s65, s26
	s_cselect_b32 s27, s15, s68
	s_cselect_b32 s26, s66, s67
	v_lshl_add_u64 v[202:203], s[24:25], 0, v[152:153]
	s_add_i32 m0, s23, 0xc000
	ds_read_b128 v[186:189], v173
	ds_read_b128 v[190:193], v173 offset:1024
	ds_read_b128 v[194:197], v173 offset:2048
	ds_read_b128 v[198:201], v173 offset:3072
	ds_read_b128 v[206:209], v173 offset:4096
	ds_read_b128 v[210:213], v173 offset:5120
	ds_read_b128 v[214:217], v173 offset:6144
	ds_read_b128 v[218:221], v173 offset:7168
	global_load_lds_dwordx4 v[202:203], off
	v_lshl_add_u64 v[202:203], s[24:25], 0, v[154:155]
	s_add_i32 m0, s23, 0xe000
	s_nop 0
	global_load_lds_dwordx4 v[202:203], off
	s_waitcnt vmcnt(8)
	s_waitcnt lgkmcnt(0)
	s_barrier
	s_waitcnt lgkmcnt(0)
	v_mfma_f32_16x16x32_f16 v[140:143], v[104:107], v[186:189], 0
	v_mfma_f32_16x16x32_f16 v[136:139], v[112:115], v[186:189], 0
	v_mfma_f32_16x16x32_f16 v[124:127], v[104:107], v[194:197], 0
	v_mfma_f32_16x16x32_f16 v[120:123], v[112:115], v[194:197], 0
	v_mfma_f32_16x16x32_f16 v[92:95], v[104:107], v[206:209], 0
	v_mfma_f32_16x16x32_f16 v[88:91], v[112:115], v[206:209], 0
	v_mfma_f32_16x16x32_f16 v[76:79], v[104:107], v[214:217], 0
	v_mfma_f32_16x16x32_f16 v[72:75], v[112:115], v[214:217], 0
	v_mfma_f32_16x16x32_f16 v[140:143], v[108:111], v[190:193], v[140:143]
	v_mfma_f32_16x16x32_f16 v[136:139], v[116:119], v[190:193], v[136:139]
	v_mfma_f32_16x16x32_f16 v[124:127], v[108:111], v[198:201], v[124:127]
	v_mfma_f32_16x16x32_f16 v[120:123], v[116:119], v[198:201], v[120:123]
	v_mfma_f32_16x16x32_f16 v[92:95], v[108:111], v[210:213], v[92:95]
	v_mfma_f32_16x16x32_f16 v[88:91], v[116:119], v[210:213], v[88:91]
	v_mfma_f32_16x16x32_f16 v[76:79], v[108:111], v[218:221], v[76:79]
	v_mfma_f32_16x16x32_f16 v[72:75], v[116:119], v[218:221], v[72:75]
	v_mfma_f32_16x16x32_f16 v[132:135], v[160:163], v[186:189], 0
	v_mfma_f32_16x16x32_f16 v[128:131], v[178:181], v[186:189], 0
	v_mfma_f32_16x16x32_f16 v[100:103], v[160:163], v[194:197], 0
	v_mfma_f32_16x16x32_f16 v[96:99], v[178:181], v[194:197], 0
	v_mfma_f32_16x16x32_f16 v[84:87], v[160:163], v[206:209], 0
	v_mfma_f32_16x16x32_f16 v[80:83], v[178:181], v[206:209], 0
	v_mfma_f32_16x16x32_f16 v[68:71], v[160:163], v[214:217], 0
	v_mfma_f32_16x16x32_f16 v[64:67], v[178:181], v[214:217], 0
	v_mfma_f32_16x16x32_f16 v[132:135], v[164:167], v[190:193], v[132:135]
	v_mfma_f32_16x16x32_f16 v[128:131], v[182:185], v[190:193], v[128:131]
	v_mfma_f32_16x16x32_f16 v[100:103], v[164:167], v[198:201], v[100:103]
	v_mfma_f32_16x16x32_f16 v[96:99], v[182:185], v[198:201], v[96:99]
	v_mfma_f32_16x16x32_f16 v[84:87], v[164:167], v[210:213], v[84:87]
	v_mfma_f32_16x16x32_f16 v[80:83], v[182:185], v[210:213], v[80:83]
	v_mfma_f32_16x16x32_f16 v[68:71], v[164:167], v[218:221], v[68:71]
	v_mfma_f32_16x16x32_f16 v[64:67], v[182:185], v[218:221], v[64:67]
	s_barrier
	s_add_i32 s70, s60, s44
	v_lshl_add_u64 v[202:203], s[26:27], 0, v[146:147]
	s_mov_b32 m0, s70
	ds_read_b128 v[186:189], v173 offset:16384
	ds_read_b128 v[190:193], v173 offset:17408
	ds_read_b128 v[194:197], v173 offset:18432
	ds_read_b128 v[198:201], v173 offset:19456
	ds_read_b128 v[206:209], v173 offset:20480
	ds_read_b128 v[210:213], v173 offset:21504
	ds_read_b128 v[214:217], v173 offset:22528
	ds_read_b128 v[218:221], v173 offset:23552
	global_load_lds_dwordx4 v[202:203], off
	s_add_i32 m0, s70, 0x2000
	s_add_u32 s70, s26, 0x40000
	v_lshl_add_u64 v[222:223], s[26:27], 0, v[150:151]
	s_addc_u32 s71, s27, 0
	s_add_i32 s72, s61, s44
	global_load_lds_dwordx4 v[222:223], off
	v_lshl_add_u64 v[224:225], s[70:71], 0, v[146:147]
	s_mov_b32 m0, s72
	v_lshl_add_u64 v[226:227], s[34:35], 0, v[148:149]
	global_load_lds_dwordx4 v[224:225], off
	v_lshl_add_u64 v[224:225], s[70:71], 0, v[150:151]
	s_add_i32 m0, s72, 0x2000
	s_nop 0
	global_load_lds_dwordx4 v[224:225], off
	v_lshl_add_u64 v[224:225], s[34:35], 0, v[144:145]
	s_mov_b32 m0, s23
	s_nop 0
	global_load_lds_dwordx4 v[224:225], off
	s_mov_b32 m0, s45
	s_nop 0
	global_load_lds_dwordx4 v[226:227], off
	s_waitcnt vmcnt(8)
	s_waitcnt lgkmcnt(0)
	s_barrier
	s_waitcnt lgkmcnt(0)
	v_mfma_f32_16x16x32_f16 v[60:63], v[104:107], v[186:189], 0
	v_mfma_f32_16x16x32_f16 v[56:59], v[112:115], v[186:189], 0
	v_mfma_f32_16x16x32_f16 v[44:47], v[104:107], v[194:197], 0
	v_mfma_f32_16x16x32_f16 v[40:43], v[112:115], v[194:197], 0
	v_mfma_f32_16x16x32_f16 v[28:31], v[104:107], v[206:209], 0
	v_mfma_f32_16x16x32_f16 v[24:27], v[112:115], v[206:209], 0
	v_mfma_f32_16x16x32_f16 v[12:15], v[104:107], v[214:217], 0
	v_mfma_f32_16x16x32_f16 v[8:11], v[112:115], v[214:217], 0
	v_mfma_f32_16x16x32_f16 v[60:63], v[108:111], v[190:193], v[60:63]
	v_mfma_f32_16x16x32_f16 v[56:59], v[116:119], v[190:193], v[56:59]
	v_mfma_f32_16x16x32_f16 v[44:47], v[108:111], v[198:201], v[44:47]
	v_mfma_f32_16x16x32_f16 v[40:43], v[116:119], v[198:201], v[40:43]
	v_mfma_f32_16x16x32_f16 v[28:31], v[108:111], v[210:213], v[28:31]
	v_mfma_f32_16x16x32_f16 v[24:27], v[116:119], v[210:213], v[24:27]
	v_mfma_f32_16x16x32_f16 v[12:15], v[108:111], v[218:221], v[12:15]
	v_mfma_f32_16x16x32_f16 v[8:11], v[116:119], v[218:221], v[8:11]
	v_mfma_f32_16x16x32_f16 v[52:55], v[160:163], v[186:189], 0
	v_mfma_f32_16x16x32_f16 v[48:51], v[178:181], v[186:189], 0
	v_mfma_f32_16x16x32_f16 v[36:39], v[160:163], v[194:197], 0
	v_mfma_f32_16x16x32_f16 v[32:35], v[178:181], v[194:197], 0
	v_mfma_f32_16x16x32_f16 v[20:23], v[160:163], v[206:209], 0
	v_mfma_f32_16x16x32_f16 v[16:19], v[178:181], v[206:209], 0
	v_mfma_f32_16x16x32_f16 v[4:7], v[160:163], v[214:217], 0
	v_mfma_f32_16x16x32_f16 v[0:3], v[178:181], v[214:217], 0
	v_mfma_f32_16x16x32_f16 v[52:55], v[164:167], v[190:193], v[52:55]
	v_mfma_f32_16x16x32_f16 v[48:51], v[182:185], v[190:193], v[48:51]
	v_mfma_f32_16x16x32_f16 v[36:39], v[164:167], v[198:201], v[36:39]
	v_mfma_f32_16x16x32_f16 v[32:35], v[182:185], v[198:201], v[32:35]
	v_mfma_f32_16x16x32_f16 v[20:23], v[164:167], v[210:213], v[20:23]
	v_mfma_f32_16x16x32_f16 v[16:19], v[182:185], v[210:213], v[16:19]
	v_mfma_f32_16x16x32_f16 v[4:7], v[164:167], v[218:221], v[4:7]
	v_mfma_f32_16x16x32_f16 v[0:3], v[182:185], v[218:221], v[0:3]
	s_barrier
	s_add_i32 s70, 0, 0x18000
	s_add_i32 s71, 0, 0x1c000
	v_add_u32_e32 v116, s70, v169
	v_add_u32_e32 v177, s71, v169
	ds_read_b128 v[104:107], v116
	ds_read_b128 v[108:111], v116 offset:1024
	ds_read_b128 v[112:115], v116 offset:2048
	ds_read_b128 v[116:119], v116 offset:3072
	ds_read_b128 v[160:163], v177
	ds_read_b128 v[164:167], v177 offset:1024
	ds_read_b128 v[178:181], v177 offset:2048
	ds_read_b128 v[182:185], v177 offset:3072
	s_add_u32 s34, s34, 0x40000
	s_addc_u32 s35, s35, 0
	s_mov_b32 m0, s46
	v_lshl_add_u64 v[228:229], s[34:35], 0, v[144:145]
	ds_read_b128 v[186:189], v173 offset:32768
	ds_read_b128 v[190:193], v173 offset:33792
	ds_read_b128 v[194:197], v173 offset:34816
	ds_read_b128 v[198:201], v173 offset:35840
	ds_read_b128 v[206:209], v173 offset:36864
	ds_read_b128 v[210:213], v173 offset:37888
	ds_read_b128 v[214:217], v173 offset:38912
	ds_read_b128 v[218:221], v173 offset:39936
	global_load_lds_dwordx4 v[228:229], off
	v_lshl_add_u64 v[228:229], s[34:35], 0, v[148:149]
	s_mov_b32 m0, s47
	s_nop 0
	global_load_lds_dwordx4 v[228:229], off
	s_waitcnt vmcnt(8)
	s_waitcnt lgkmcnt(0)
	s_barrier
	s_waitcnt lgkmcnt(0)
	v_mfma_f32_16x16x32_f16 v[140:143], v[104:107], v[186:189], v[140:143]
	v_mfma_f32_16x16x32_f16 v[136:139], v[112:115], v[186:189], v[136:139]
	v_mfma_f32_16x16x32_f16 v[124:127], v[104:107], v[194:197], v[124:127]
	v_mfma_f32_16x16x32_f16 v[120:123], v[112:115], v[194:197], v[120:123]
	v_mfma_f32_16x16x32_f16 v[92:95], v[104:107], v[206:209], v[92:95]
	v_mfma_f32_16x16x32_f16 v[88:91], v[112:115], v[206:209], v[88:91]
	v_mfma_f32_16x16x32_f16 v[76:79], v[104:107], v[214:217], v[76:79]
	v_mfma_f32_16x16x32_f16 v[72:75], v[112:115], v[214:217], v[72:75]
	v_mfma_f32_16x16x32_f16 v[140:143], v[108:111], v[190:193], v[140:143]
	v_mfma_f32_16x16x32_f16 v[136:139], v[116:119], v[190:193], v[136:139]
	v_mfma_f32_16x16x32_f16 v[124:127], v[108:111], v[198:201], v[124:127]
	v_mfma_f32_16x16x32_f16 v[120:123], v[116:119], v[198:201], v[120:123]
	v_mfma_f32_16x16x32_f16 v[92:95], v[108:111], v[210:213], v[92:95]
	v_mfma_f32_16x16x32_f16 v[88:91], v[116:119], v[210:213], v[88:91]
	v_mfma_f32_16x16x32_f16 v[76:79], v[108:111], v[218:221], v[76:79]
	v_mfma_f32_16x16x32_f16 v[72:75], v[116:119], v[218:221], v[72:75]
	v_mfma_f32_16x16x32_f16 v[132:135], v[160:163], v[186:189], v[132:135]
	v_mfma_f32_16x16x32_f16 v[128:131], v[178:181], v[186:189], v[128:131]
	v_mfma_f32_16x16x32_f16 v[100:103], v[160:163], v[194:197], v[100:103]
	v_mfma_f32_16x16x32_f16 v[96:99], v[178:181], v[194:197], v[96:99]
	v_mfma_f32_16x16x32_f16 v[84:87], v[160:163], v[206:209], v[84:87]
	v_mfma_f32_16x16x32_f16 v[80:83], v[178:181], v[206:209], v[80:83]
	v_mfma_f32_16x16x32_f16 v[68:71], v[160:163], v[214:217], v[68:71]
	v_mfma_f32_16x16x32_f16 v[64:67], v[178:181], v[214:217], v[64:67]
	v_mfma_f32_16x16x32_f16 v[132:135], v[164:167], v[190:193], v[132:135]
	v_mfma_f32_16x16x32_f16 v[128:131], v[182:185], v[190:193], v[128:131]
	v_mfma_f32_16x16x32_f16 v[100:103], v[164:167], v[198:201], v[100:103]
	v_mfma_f32_16x16x32_f16 v[96:99], v[182:185], v[198:201], v[96:99]
	v_mfma_f32_16x16x32_f16 v[84:87], v[164:167], v[210:213], v[84:87]
	v_mfma_f32_16x16x32_f16 v[80:83], v[182:185], v[210:213], v[80:83]
	v_mfma_f32_16x16x32_f16 v[68:71], v[164:167], v[218:221], v[68:71]
	v_mfma_f32_16x16x32_f16 v[64:67], v[182:185], v[218:221], v[64:67]
	s_barrier
	s_add_i32 s34, s70, s44
	v_lshl_add_u64 v[202:203], v[202:203], 0, s[10:11]
	s_mov_b32 m0, s34
	ds_read_b128 v[186:189], v173 offset:49152
	ds_read_b128 v[190:193], v173 offset:50176
	ds_read_b128 v[194:197], v173 offset:51200
	ds_read_b128 v[198:201], v173 offset:52224
	ds_read_b128 v[206:209], v173 offset:53248
	ds_read_b128 v[210:213], v173 offset:54272
	ds_read_b128 v[214:217], v173 offset:55296
	ds_read_b128 v[218:221], v173 offset:56320
	global_load_lds_dwordx4 v[202:203], off
	s_add_i32 m0, s34, 0x2000
	s_add_u32 s26, s26, 0x40080
	v_lshl_add_u64 v[202:203], v[222:223], 0, s[10:11]
	s_addc_u32 s27, s27, 0
	s_add_i32 s34, s71, s44
	global_load_lds_dwordx4 v[202:203], off
	v_lshl_add_u64 v[202:203], s[26:27], 0, v[146:147]
	s_mov_b32 m0, s34
	s_nop 0
	global_load_lds_dwordx4 v[202:203], off
	v_lshl_add_u64 v[202:203], s[26:27], 0, v[150:151]
	s_add_i32 m0, s34, 0x2000
	s_nop 0
	global_load_lds_dwordx4 v[202:203], off
	v_lshl_add_u64 v[202:203], v[224:225], 0, s[10:11]
	s_mov_b32 m0, s57
	s_nop 0
	global_load_lds_dwordx4 v[202:203], off
	v_lshl_add_u64 v[202:203], v[226:227], 0, s[10:11]
	s_mov_b32 m0, s58
	s_nop 0
	global_load_lds_dwordx4 v[202:203], off
	s_waitcnt vmcnt(8)
	s_waitcnt lgkmcnt(0)
	s_barrier
	s_waitcnt lgkmcnt(0)
	v_mfma_f32_16x16x32_f16 v[60:63], v[104:107], v[186:189], v[60:63]
	v_mfma_f32_16x16x32_f16 v[56:59], v[112:115], v[186:189], v[56:59]
	v_mfma_f32_16x16x32_f16 v[44:47], v[104:107], v[194:197], v[44:47]
	v_mfma_f32_16x16x32_f16 v[40:43], v[112:115], v[194:197], v[40:43]
	v_mfma_f32_16x16x32_f16 v[28:31], v[104:107], v[206:209], v[28:31]
	v_mfma_f32_16x16x32_f16 v[24:27], v[112:115], v[206:209], v[24:27]
	v_mfma_f32_16x16x32_f16 v[12:15], v[104:107], v[214:217], v[12:15]
	v_mfma_f32_16x16x32_f16 v[8:11], v[112:115], v[214:217], v[8:11]
	v_mfma_f32_16x16x32_f16 v[60:63], v[108:111], v[190:193], v[60:63]
	v_mfma_f32_16x16x32_f16 v[56:59], v[116:119], v[190:193], v[56:59]
	v_mfma_f32_16x16x32_f16 v[44:47], v[108:111], v[198:201], v[44:47]
	v_mfma_f32_16x16x32_f16 v[40:43], v[116:119], v[198:201], v[40:43]
	v_mfma_f32_16x16x32_f16 v[28:31], v[108:111], v[210:213], v[28:31]
	v_mfma_f32_16x16x32_f16 v[24:27], v[116:119], v[210:213], v[24:27]
	v_mfma_f32_16x16x32_f16 v[12:15], v[108:111], v[218:221], v[12:15]
	v_mfma_f32_16x16x32_f16 v[8:11], v[116:119], v[218:221], v[8:11]
	v_mfma_f32_16x16x32_f16 v[52:55], v[160:163], v[186:189], v[52:55]
	v_mfma_f32_16x16x32_f16 v[48:51], v[178:181], v[186:189], v[48:51]
	v_mfma_f32_16x16x32_f16 v[36:39], v[160:163], v[194:197], v[36:39]
	v_mfma_f32_16x16x32_f16 v[32:35], v[178:181], v[194:197], v[32:35]
	v_mfma_f32_16x16x32_f16 v[20:23], v[160:163], v[206:209], v[20:23]
	v_mfma_f32_16x16x32_f16 v[16:19], v[178:181], v[206:209], v[16:19]
	v_mfma_f32_16x16x32_f16 v[4:7], v[160:163], v[214:217], v[4:7]
	v_mfma_f32_16x16x32_f16 v[0:3], v[178:181], v[214:217], v[0:3]
	v_mfma_f32_16x16x32_f16 v[52:55], v[164:167], v[190:193], v[52:55]
	v_mfma_f32_16x16x32_f16 v[48:51], v[182:185], v[190:193], v[48:51]
	v_mfma_f32_16x16x32_f16 v[36:39], v[164:167], v[198:201], v[36:39]
	v_mfma_f32_16x16x32_f16 v[32:35], v[182:185], v[198:201], v[32:35]
	v_mfma_f32_16x16x32_f16 v[20:23], v[164:167], v[210:213], v[20:23]
	v_mfma_f32_16x16x32_f16 v[16:19], v[182:185], v[210:213], v[16:19]
	v_mfma_f32_16x16x32_f16 v[4:7], v[164:167], v[218:221], v[4:7]
	v_mfma_f32_16x16x32_f16 v[0:3], v[182:185], v[218:221], v[0:3]
	s_barrier
	s_add_i32 s69, s69, 2
	s_add_u32 s24, s24, 0x100
	s_addc_u32 s25, s25, 0
	s_add_u32 s67, s67, 0x100
	s_addc_u32 s68, s68, 0
	s_cmp_gt_u32 s69, 13

.LBB0_340:
	s_add_u32 s65, s24, 0x100
	s_addc_u32 s66, s25, 0
	s_mov_b32 s67, -2
	s_waitcnt lgkmcnt(0)
	s_waitcnt lgkmcnt(0)
	ds_read_b128 v[80:83], v208
	ds_read_b128 v[84:87], v208 offset:1024
	ds_read_b128 v[92:95], v208 offset:2048
	ds_read_b128 v[96:99], v208 offset:3072
	ds_read_b128 v[144:147], v209
	ds_read_b128 v[148:151], v209 offset:1024
	ds_read_b128 v[152:155], v209 offset:2048
	ds_read_b128 v[156:159], v209 offset:3072
	s_add_u32 s24, s22, 0x100
	s_addc_u32 s25, s23, 0
	s_cmp_eq_u32 s67, 40
	s_cselect_b32 s35, s1, s25
	s_cselect_b32 s34, s0, s24
	s_cselect_b32 s27, s21, s66
	s_cselect_b32 s26, s20, s65
	v_lshl_add_u64 v[202:203], s[22:23], 0, v[168:169]
	s_add_i32 m0, s40, 0xc000
	ds_read_b128 v[178:181], v210
	ds_read_b128 v[182:185], v210 offset:1024
	ds_read_b128 v[186:189], v210 offset:2048
	ds_read_b128 v[190:193], v210 offset:3072
	ds_read_b128 v[194:197], v210 offset:4096
	ds_read_b128 v[198:201], v210 offset:5120
	ds_read_b128 v[212:215], v210 offset:6144
	ds_read_b128 v[216:219], v210 offset:7168
	global_load_lds_dwordx4 v[202:203], off
	v_lshl_add_u64 v[202:203], s[22:23], 0, v[170:171]
	s_add_i32 m0, s40, 0xe000
	s_nop 0
	global_load_lds_dwordx4 v[202:203], off
	s_waitcnt vmcnt(8)
	s_waitcnt lgkmcnt(0)
	s_barrier
	s_waitcnt lgkmcnt(0)
	v_mfma_f32_16x16x32_f16 v[140:143], v[80:83], v[178:181], 0
	v_mfma_f32_16x16x32_f16 v[136:139], v[92:95], v[178:181], 0
	v_mfma_f32_16x16x32_f16 v[124:127], v[80:83], v[186:189], 0
	v_mfma_f32_16x16x32_f16 v[120:123], v[92:95], v[186:189], 0
	v_mfma_f32_16x16x32_f16 v[108:111], v[80:83], v[194:197], 0
	v_mfma_f32_16x16x32_f16 v[104:107], v[92:95], v[194:197], 0
	v_mfma_f32_16x16x32_f16 v[76:79], v[80:83], v[212:215], 0
	v_mfma_f32_16x16x32_f16 v[72:75], v[92:95], v[212:215], 0
	v_mfma_f32_16x16x32_f16 v[140:143], v[84:87], v[182:185], v[140:143]
	v_mfma_f32_16x16x32_f16 v[136:139], v[96:99], v[182:185], v[136:139]
	v_mfma_f32_16x16x32_f16 v[124:127], v[84:87], v[190:193], v[124:127]
	v_mfma_f32_16x16x32_f16 v[120:123], v[96:99], v[190:193], v[120:123]
	v_mfma_f32_16x16x32_f16 v[108:111], v[84:87], v[198:201], v[108:111]
	v_mfma_f32_16x16x32_f16 v[104:107], v[96:99], v[198:201], v[104:107]
	v_mfma_f32_16x16x32_f16 v[76:79], v[84:87], v[216:219], v[76:79]
	v_mfma_f32_16x16x32_f16 v[72:75], v[96:99], v[216:219], v[72:75]
	v_mfma_f32_16x16x32_f16 v[132:135], v[144:147], v[178:181], 0
	v_mfma_f32_16x16x32_f16 v[128:131], v[152:155], v[178:181], 0
	v_mfma_f32_16x16x32_f16 v[116:119], v[144:147], v[186:189], 0
	v_mfma_f32_16x16x32_f16 v[112:115], v[152:155], v[186:189], 0
	v_mfma_f32_16x16x32_f16 v[100:103], v[144:147], v[194:197], 0
	v_mfma_f32_16x16x32_f16 v[88:91], v[152:155], v[194:197], 0
	v_mfma_f32_16x16x32_f16 v[68:71], v[144:147], v[212:215], 0
	v_mfma_f32_16x16x32_f16 v[64:67], v[152:155], v[212:215], 0
	v_mfma_f32_16x16x32_f16 v[132:135], v[148:151], v[182:185], v[132:135]
	v_mfma_f32_16x16x32_f16 v[128:131], v[156:159], v[182:185], v[128:131]
	v_mfma_f32_16x16x32_f16 v[116:119], v[148:151], v[190:193], v[116:119]
	v_mfma_f32_16x16x32_f16 v[112:115], v[156:159], v[190:193], v[112:115]
	v_mfma_f32_16x16x32_f16 v[100:103], v[148:151], v[198:201], v[100:103]
	v_mfma_f32_16x16x32_f16 v[88:91], v[156:159], v[198:201], v[88:91]
	v_mfma_f32_16x16x32_f16 v[68:71], v[148:151], v[216:219], v[68:71]
	v_mfma_f32_16x16x32_f16 v[64:67], v[156:159], v[216:219], v[64:67]
	s_barrier
	s_add_i32 s22, s59, s33
	v_lshl_add_u64 v[202:203], s[26:27], 0, v[162:163]
	s_mov_b32 m0, s22
	ds_read_b128 v[178:181], v210 offset:16384
	ds_read_b128 v[182:185], v210 offset:17408
	ds_read_b128 v[186:189], v210 offset:18432
	ds_read_b128 v[190:193], v210 offset:19456
	ds_read_b128 v[194:197], v210 offset:20480
	ds_read_b128 v[198:201], v210 offset:21504
	ds_read_b128 v[212:215], v210 offset:22528
	ds_read_b128 v[216:219], v210 offset:23552
	global_load_lds_dwordx4 v[202:203], off
	s_add_i32 m0, s22, 0x2000
	s_add_u32 s22, s26, 0xb0000
	v_lshl_add_u64 v[220:221], s[26:27], 0, v[166:167]
	s_addc_u32 s23, s27, 0
	s_add_i32 s68, s60, s33
	global_load_lds_dwordx4 v[220:221], off
	v_lshl_add_u64 v[222:223], s[22:23], 0, v[162:163]
	s_mov_b32 m0, s68
	v_lshl_add_u64 v[224:225], s[34:35], 0, v[164:165]
	global_load_lds_dwordx4 v[222:223], off
	v_lshl_add_u64 v[222:223], s[22:23], 0, v[166:167]
	s_add_i32 m0, s68, 0x2000
	s_nop 0
	global_load_lds_dwordx4 v[222:223], off
	v_lshl_add_u64 v[222:223], s[34:35], 0, v[160:161]
	s_mov_b32 m0, s40
	s_nop 0
	global_load_lds_dwordx4 v[222:223], off
	s_mov_b32 m0, s41
	s_nop 0
	global_load_lds_dwordx4 v[224:225], off
	s_waitcnt vmcnt(8)
	s_waitcnt lgkmcnt(0)
	s_barrier
	s_waitcnt lgkmcnt(0)
	v_mfma_f32_16x16x32_f16 v[60:63], v[80:83], v[178:181], 0
	v_mfma_f32_16x16x32_f16 v[56:59], v[92:95], v[178:181], 0
	v_mfma_f32_16x16x32_f16 v[44:47], v[80:83], v[186:189], 0
	v_mfma_f32_16x16x32_f16 v[40:43], v[92:95], v[186:189], 0
	v_mfma_f32_16x16x32_f16 v[28:31], v[80:83], v[194:197], 0
	v_mfma_f32_16x16x32_f16 v[24:27], v[92:95], v[194:197], 0
	v_mfma_f32_16x16x32_f16 v[12:15], v[80:83], v[212:215], 0
	v_mfma_f32_16x16x32_f16 v[8:11], v[92:95], v[212:215], 0
	v_mfma_f32_16x16x32_f16 v[60:63], v[84:87], v[182:185], v[60:63]
	v_mfma_f32_16x16x32_f16 v[56:59], v[96:99], v[182:185], v[56:59]
	v_mfma_f32_16x16x32_f16 v[44:47], v[84:87], v[190:193], v[44:47]
	v_mfma_f32_16x16x32_f16 v[40:43], v[96:99], v[190:193], v[40:43]
	v_mfma_f32_16x16x32_f16 v[28:31], v[84:87], v[198:201], v[28:31]
	v_mfma_f32_16x16x32_f16 v[24:27], v[96:99], v[198:201], v[24:27]
	v_mfma_f32_16x16x32_f16 v[12:15], v[84:87], v[216:219], v[12:15]
	v_mfma_f32_16x16x32_f16 v[8:11], v[96:99], v[216:219], v[8:11]
	v_mfma_f32_16x16x32_f16 v[52:55], v[144:147], v[178:181], 0
	v_mfma_f32_16x16x32_f16 v[48:51], v[152:155], v[178:181], 0
	v_mfma_f32_16x16x32_f16 v[36:39], v[144:147], v[186:189], 0
	v_mfma_f32_16x16x32_f16 v[32:35], v[152:155], v[186:189], 0
	v_mfma_f32_16x16x32_f16 v[20:23], v[144:147], v[194:197], 0
	v_mfma_f32_16x16x32_f16 v[16:19], v[152:155], v[194:197], 0
	v_mfma_f32_16x16x32_f16 v[4:7], v[144:147], v[212:215], 0
	v_mfma_f32_16x16x32_f16 v[0:3], v[152:155], v[212:215], 0
	v_mfma_f32_16x16x32_f16 v[52:55], v[148:151], v[182:185], v[52:55]
	v_mfma_f32_16x16x32_f16 v[48:51], v[156:159], v[182:185], v[48:51]
	v_mfma_f32_16x16x32_f16 v[36:39], v[148:151], v[190:193], v[36:39]
	v_mfma_f32_16x16x32_f16 v[32:35], v[156:159], v[190:193], v[32:35]
	v_mfma_f32_16x16x32_f16 v[20:23], v[148:151], v[198:201], v[20:23]
	v_mfma_f32_16x16x32_f16 v[16:19], v[156:159], v[198:201], v[16:19]
	v_mfma_f32_16x16x32_f16 v[4:7], v[148:151], v[216:219], v[4:7]
	v_mfma_f32_16x16x32_f16 v[0:3], v[156:159], v[216:219], v[0:3]
	s_barrier
	s_add_i32 s68, 0, 0x18000
	s_add_i32 s69, 0, 0x1c000
	v_add_u32_e32 v96, s68, v206
	v_add_u32_e32 v156, s69, v206
	ds_read_b128 v[80:83], v96
	ds_read_b128 v[84:87], v96 offset:1024
	ds_read_b128 v[92:95], v96 offset:2048
	ds_read_b128 v[96:99], v96 offset:3072
	ds_read_b128 v[144:147], v156
	ds_read_b128 v[148:151], v156 offset:1024
	ds_read_b128 v[152:155], v156 offset:2048
	ds_read_b128 v[156:159], v156 offset:3072
	s_add_u32 s22, s34, 0xb0000
	s_addc_u32 s23, s35, 0
	s_mov_b32 m0, s44
	v_lshl_add_u64 v[226:227], s[22:23], 0, v[160:161]
	ds_read_b128 v[178:181], v210 offset:32768
	ds_read_b128 v[182:185], v210 offset:33792
	ds_read_b128 v[186:189], v210 offset:34816
	ds_read_b128 v[190:193], v210 offset:35840
	ds_read_b128 v[194:197], v210 offset:36864
	ds_read_b128 v[198:201], v210 offset:37888
	ds_read_b128 v[212:215], v210 offset:38912
	ds_read_b128 v[216:219], v210 offset:39936
	global_load_lds_dwordx4 v[226:227], off
	v_lshl_add_u64 v[226:227], s[22:23], 0, v[164:165]
	s_mov_b32 m0, s45
	s_nop 0
	global_load_lds_dwordx4 v[226:227], off
	s_waitcnt vmcnt(8)
	s_waitcnt lgkmcnt(0)
	s_barrier
	s_waitcnt lgkmcnt(0)
	v_mfma_f32_16x16x32_f16 v[140:143], v[80:83], v[178:181], v[140:143]
	v_mfma_f32_16x16x32_f16 v[136:139], v[92:95], v[178:181], v[136:139]
	v_mfma_f32_16x16x32_f16 v[124:127], v[80:83], v[186:189], v[124:127]
	v_mfma_f32_16x16x32_f16 v[120:123], v[92:95], v[186:189], v[120:123]
	v_mfma_f32_16x16x32_f16 v[108:111], v[80:83], v[194:197], v[108:111]
	v_mfma_f32_16x16x32_f16 v[104:107], v[92:95], v[194:197], v[104:107]
	v_mfma_f32_16x16x32_f16 v[76:79], v[80:83], v[212:215], v[76:79]
	v_mfma_f32_16x16x32_f16 v[72:75], v[92:95], v[212:215], v[72:75]
	v_mfma_f32_16x16x32_f16 v[140:143], v[84:87], v[182:185], v[140:143]
	v_mfma_f32_16x16x32_f16 v[136:139], v[96:99], v[182:185], v[136:139]
	v_mfma_f32_16x16x32_f16 v[124:127], v[84:87], v[190:193], v[124:127]
	v_mfma_f32_16x16x32_f16 v[120:123], v[96:99], v[190:193], v[120:123]
	v_mfma_f32_16x16x32_f16 v[108:111], v[84:87], v[198:201], v[108:111]
	v_mfma_f32_16x16x32_f16 v[104:107], v[96:99], v[198:201], v[104:107]
	v_mfma_f32_16x16x32_f16 v[76:79], v[84:87], v[216:219], v[76:79]
	v_mfma_f32_16x16x32_f16 v[72:75], v[96:99], v[216:219], v[72:75]
	v_mfma_f32_16x16x32_f16 v[132:135], v[144:147], v[178:181], v[132:135]
	v_mfma_f32_16x16x32_f16 v[128:131], v[152:155], v[178:181], v[128:131]
	v_mfma_f32_16x16x32_f16 v[116:119], v[144:147], v[186:189], v[116:119]
	v_mfma_f32_16x16x32_f16 v[112:115], v[152:155], v[186:189], v[112:115]
	v_mfma_f32_16x16x32_f16 v[100:103], v[144:147], v[194:197], v[100:103]
	v_mfma_f32_16x16x32_f16 v[88:91], v[152:155], v[194:197], v[88:91]
	v_mfma_f32_16x16x32_f16 v[68:71], v[144:147], v[212:215], v[68:71]
	v_mfma_f32_16x16x32_f16 v[64:67], v[152:155], v[212:215], v[64:67]
	v_mfma_f32_16x16x32_f16 v[132:135], v[148:151], v[182:185], v[132:135]
	v_mfma_f32_16x16x32_f16 v[128:131], v[156:159], v[182:185], v[128:131]
	v_mfma_f32_16x16x32_f16 v[116:119], v[148:151], v[190:193], v[116:119]
	v_mfma_f32_16x16x32_f16 v[112:115], v[156:159], v[190:193], v[112:115]
	v_mfma_f32_16x16x32_f16 v[100:103], v[148:151], v[198:201], v[100:103]
	v_mfma_f32_16x16x32_f16 v[88:91], v[156:159], v[198:201], v[88:91]
	v_mfma_f32_16x16x32_f16 v[68:71], v[148:151], v[216:219], v[68:71]
	v_mfma_f32_16x16x32_f16 v[64:67], v[156:159], v[216:219], v[64:67]
	s_barrier
	s_add_i32 s22, s68, s33
	v_lshl_add_u64 v[202:203], v[202:203], 0, s[16:17]
	s_mov_b32 m0, s22
	ds_read_b128 v[178:181], v210 offset:49152
	ds_read_b128 v[182:185], v210 offset:50176
	ds_read_b128 v[186:189], v210 offset:51200
	ds_read_b128 v[190:193], v210 offset:52224
	ds_read_b128 v[194:197], v210 offset:53248
	ds_read_b128 v[198:201], v210 offset:54272
	ds_read_b128 v[212:215], v210 offset:55296
	ds_read_b128 v[216:219], v210 offset:56320
	global_load_lds_dwordx4 v[202:203], off
	s_add_i32 m0, s22, 0x2000
	s_add_u32 s22, s26, 0xb0080
	v_lshl_add_u64 v[202:203], v[220:221], 0, s[16:17]
	s_addc_u32 s23, s27, 0
	s_add_i32 s26, s69, s33
	global_load_lds_dwordx4 v[202:203], off
	v_lshl_add_u64 v[202:203], s[22:23], 0, v[162:163]
	s_mov_b32 m0, s26
	s_nop 0
	global_load_lds_dwordx4 v[202:203], off
	v_lshl_add_u64 v[202:203], s[22:23], 0, v[166:167]
	s_add_i32 m0, s26, 0x2000
	s_nop 0
	global_load_lds_dwordx4 v[202:203], off
	v_lshl_add_u64 v[202:203], v[222:223], 0, s[16:17]
	s_mov_b32 m0, s55
	s_nop 0
	global_load_lds_dwordx4 v[202:203], off
	v_lshl_add_u64 v[202:203], v[224:225], 0, s[16:17]
	s_mov_b32 m0, s56
	s_nop 0
	global_load_lds_dwordx4 v[202:203], off
	s_waitcnt vmcnt(8)
	s_waitcnt lgkmcnt(0)
	s_barrier
	s_waitcnt lgkmcnt(0)
	v_mfma_f32_16x16x32_f16 v[60:63], v[80:83], v[178:181], v[60:63]
	v_mfma_f32_16x16x32_f16 v[56:59], v[92:95], v[178:181], v[56:59]
	v_mfma_f32_16x16x32_f16 v[44:47], v[80:83], v[186:189], v[44:47]
	v_mfma_f32_16x16x32_f16 v[40:43], v[92:95], v[186:189], v[40:43]
	v_mfma_f32_16x16x32_f16 v[28:31], v[80:83], v[194:197], v[28:31]
	v_mfma_f32_16x16x32_f16 v[24:27], v[92:95], v[194:197], v[24:27]
	v_mfma_f32_16x16x32_f16 v[12:15], v[80:83], v[212:215], v[12:15]
	v_mfma_f32_16x16x32_f16 v[8:11], v[92:95], v[212:215], v[8:11]
	v_mfma_f32_16x16x32_f16 v[60:63], v[84:87], v[182:185], v[60:63]
	v_mfma_f32_16x16x32_f16 v[56:59], v[96:99], v[182:185], v[56:59]
	v_mfma_f32_16x16x32_f16 v[44:47], v[84:87], v[190:193], v[44:47]
	v_mfma_f32_16x16x32_f16 v[40:43], v[96:99], v[190:193], v[40:43]
	v_mfma_f32_16x16x32_f16 v[28:31], v[84:87], v[198:201], v[28:31]
	v_mfma_f32_16x16x32_f16 v[24:27], v[96:99], v[198:201], v[24:27]
	v_mfma_f32_16x16x32_f16 v[12:15], v[84:87], v[216:219], v[12:15]
	v_mfma_f32_16x16x32_f16 v[8:11], v[96:99], v[216:219], v[8:11]
	v_mfma_f32_16x16x32_f16 v[52:55], v[144:147], v[178:181], v[52:55]
	v_mfma_f32_16x16x32_f16 v[48:51], v[152:155], v[178:181], v[48:51]
	v_mfma_f32_16x16x32_f16 v[36:39], v[144:147], v[186:189], v[36:39]
	v_mfma_f32_16x16x32_f16 v[32:35], v[152:155], v[186:189], v[32:35]
	v_mfma_f32_16x16x32_f16 v[20:23], v[144:147], v[194:197], v[20:23]
	v_mfma_f32_16x16x32_f16 v[16:19], v[152:155], v[194:197], v[16:19]
	v_mfma_f32_16x16x32_f16 v[4:7], v[144:147], v[212:215], v[4:7]
	v_mfma_f32_16x16x32_f16 v[0:3], v[152:155], v[212:215], v[0:3]
	v_mfma_f32_16x16x32_f16 v[52:55], v[148:151], v[182:185], v[52:55]
	v_mfma_f32_16x16x32_f16 v[48:51], v[156:159], v[182:185], v[48:51]
	v_mfma_f32_16x16x32_f16 v[36:39], v[148:151], v[190:193], v[36:39]
	v_mfma_f32_16x16x32_f16 v[32:35], v[156:159], v[190:193], v[32:35]
	v_mfma_f32_16x16x32_f16 v[20:23], v[148:151], v[198:201], v[20:23]
	v_mfma_f32_16x16x32_f16 v[16:19], v[156:159], v[198:201], v[16:19]
	v_mfma_f32_16x16x32_f16 v[4:7], v[148:151], v[216:219], v[4:7]
	v_mfma_f32_16x16x32_f16 v[0:3], v[156:159], v[216:219], v[0:3]
	s_barrier
	s_add_i32 s67, s67, 2
	s_add_u32 s65, s65, 0x100
	s_addc_u32 s66, s66, 0
	s_cmp_gt_u32 s67, 41
	s_mov_b64 s[22:23], s[24:25]

.LBB0_463:
	s_ashr_i32 s23, s22, 31
	s_lshl_b64 s[24:25], s[22:23], 19
	s_add_u32 s24, s42, s24
	s_addc_u32 s25, s43, s25
	s_and_b64 s[26:27], s[2:3], exec
	s_cselect_b32 s23, s25, s41
	s_cselect_b32 s69, s24, s40
	s_ashr_i32 s21, s20, 31
	s_lshl_b64 s[26:27], s[20:21], 19
	s_add_u32 s26, s12, s26
	s_addc_u32 s27, s13, s27
	s_and_b64 s[46:47], s[2:3], exec
	s_cselect_b32 s21, s27, s45
	s_cselect_b32 s70, s26, s44
	s_add_u32 s40, s40, 0x40080
	s_addc_u32 s41, s41, 0
	s_add_u32 s71, s44, 0x100
	s_addc_u32 s72, s45, 0
	s_mov_b32 s73, -2
	s_waitcnt lgkmcnt(0)
	ds_read_b128 v[128:131], v167
	ds_read_b128 v[132:135], v167 offset:1024
	ds_read_b128 v[136:139], v167 offset:2048
	ds_read_b128 v[140:143], v167 offset:3072
	ds_read_b128 v[160:163], v168
	ds_read_b128 v[172:175], v168 offset:1024
	ds_read_b128 v[178:181], v168 offset:2048
	ds_read_b128 v[182:185], v168 offset:3072
	s_add_u32 s44, s40, 0xfffc0080
	s_addc_u32 s45, s41, -1
	s_cmp_eq_u32 s73, 12
	s_cselect_b32 s47, s23, s45
	s_cselect_b32 s46, s69, s44
	s_cselect_b32 s45, s21, s72
	s_cselect_b32 s44, s70, s71
	v_lshl_add_u64 v[202:203], s[40:41], 0, v[152:153]
	s_add_i32 m0, s35, 0xc000
	ds_read_b128 v[186:189], v169
	ds_read_b128 v[190:193], v169 offset:1024
	ds_read_b128 v[194:197], v169 offset:2048
	ds_read_b128 v[198:201], v169 offset:3072
	ds_read_b128 v[206:209], v169 offset:4096
	ds_read_b128 v[210:213], v169 offset:5120
	ds_read_b128 v[214:217], v169 offset:6144
	ds_read_b128 v[218:221], v169 offset:7168
	global_load_lds_dwordx4 v[202:203], off
	v_lshl_add_u64 v[202:203], s[40:41], 0, v[154:155]
	s_add_i32 m0, s35, 0xe000
	s_nop 0
	global_load_lds_dwordx4 v[202:203], off
	s_waitcnt vmcnt(8)
	s_waitcnt lgkmcnt(0)
	s_barrier
	s_waitcnt lgkmcnt(0)
	v_mfma_f32_16x16x32_f16 v[124:127], v[128:131], v[186:189], 0
	v_mfma_f32_16x16x32_f16 v[120:123], v[136:139], v[186:189], 0
	v_mfma_f32_16x16x32_f16 v[108:111], v[128:131], v[194:197], 0
	v_mfma_f32_16x16x32_f16 v[104:107], v[136:139], v[194:197], 0
	v_mfma_f32_16x16x32_f16 v[92:95], v[128:131], v[206:209], 0
	v_mfma_f32_16x16x32_f16 v[88:91], v[136:139], v[206:209], 0
	v_mfma_f32_16x16x32_f16 v[84:87], v[128:131], v[214:217], 0
	v_mfma_f32_16x16x32_f16 v[76:79], v[136:139], v[214:217], 0
	v_mfma_f32_16x16x32_f16 v[124:127], v[132:135], v[190:193], v[124:127]
	v_mfma_f32_16x16x32_f16 v[120:123], v[140:143], v[190:193], v[120:123]
	v_mfma_f32_16x16x32_f16 v[108:111], v[132:135], v[198:201], v[108:111]
	v_mfma_f32_16x16x32_f16 v[104:107], v[140:143], v[198:201], v[104:107]
	v_mfma_f32_16x16x32_f16 v[92:95], v[132:135], v[210:213], v[92:95]
	v_mfma_f32_16x16x32_f16 v[88:91], v[140:143], v[210:213], v[88:91]
	v_mfma_f32_16x16x32_f16 v[84:87], v[132:135], v[218:221], v[84:87]
	v_mfma_f32_16x16x32_f16 v[76:79], v[140:143], v[218:221], v[76:79]
	v_mfma_f32_16x16x32_f16 v[116:119], v[160:163], v[186:189], 0
	v_mfma_f32_16x16x32_f16 v[112:115], v[178:181], v[186:189], 0
	v_mfma_f32_16x16x32_f16 v[100:103], v[160:163], v[194:197], 0
	v_mfma_f32_16x16x32_f16 v[96:99], v[178:181], v[194:197], 0
	v_mfma_f32_16x16x32_f16 v[80:83], v[160:163], v[206:209], 0
	v_mfma_f32_16x16x32_f16 v[72:75], v[178:181], v[206:209], 0
	v_mfma_f32_16x16x32_f16 v[68:71], v[160:163], v[214:217], 0
	v_mfma_f32_16x16x32_f16 v[64:67], v[178:181], v[214:217], 0
	v_mfma_f32_16x16x32_f16 v[116:119], v[172:175], v[190:193], v[116:119]
	v_mfma_f32_16x16x32_f16 v[112:115], v[182:185], v[190:193], v[112:115]
	v_mfma_f32_16x16x32_f16 v[100:103], v[172:175], v[198:201], v[100:103]
	v_mfma_f32_16x16x32_f16 v[96:99], v[182:185], v[198:201], v[96:99]
	v_mfma_f32_16x16x32_f16 v[80:83], v[172:175], v[210:213], v[80:83]
	v_mfma_f32_16x16x32_f16 v[72:75], v[182:185], v[210:213], v[72:75]
	v_mfma_f32_16x16x32_f16 v[68:71], v[172:175], v[218:221], v[68:71]
	v_mfma_f32_16x16x32_f16 v[64:67], v[182:185], v[218:221], v[64:67]
	s_barrier
	s_add_i32 s74, s62, s48
	v_lshl_add_u64 v[202:203], s[44:45], 0, v[146:147]
	s_mov_b32 m0, s74
	ds_read_b128 v[186:189], v169 offset:16384
	ds_read_b128 v[190:193], v169 offset:17408
	ds_read_b128 v[194:197], v169 offset:18432
	ds_read_b128 v[198:201], v169 offset:19456
	ds_read_b128 v[206:209], v169 offset:20480
	ds_read_b128 v[210:213], v169 offset:21504
	ds_read_b128 v[214:217], v169 offset:22528
	ds_read_b128 v[218:221], v169 offset:23552
	global_load_lds_dwordx4 v[202:203], off
	s_add_i32 m0, s74, 0x2000
	s_add_u32 s74, s44, 0x40000
	v_lshl_add_u64 v[222:223], s[44:45], 0, v[150:151]
	s_addc_u32 s75, s45, 0
	s_add_i32 s76, s63, s48
	global_load_lds_dwordx4 v[222:223], off
	v_lshl_add_u64 v[224:225], s[74:75], 0, v[146:147]
	s_mov_b32 m0, s76
	v_lshl_add_u64 v[226:227], s[46:47], 0, v[148:149]
	global_load_lds_dwordx4 v[224:225], off
	v_lshl_add_u64 v[224:225], s[74:75], 0, v[150:151]
	s_add_i32 m0, s76, 0x2000
	s_nop 0
	global_load_lds_dwordx4 v[224:225], off
	v_lshl_add_u64 v[224:225], s[46:47], 0, v[144:145]
	s_mov_b32 m0, s35
	s_nop 0
	global_load_lds_dwordx4 v[224:225], off
	s_mov_b32 m0, s49
	s_nop 0
	global_load_lds_dwordx4 v[226:227], off
	s_waitcnt vmcnt(8)
	s_waitcnt lgkmcnt(0)
	s_barrier
	s_waitcnt lgkmcnt(0)
	v_mfma_f32_16x16x32_f16 v[60:63], v[128:131], v[186:189], 0
	v_mfma_f32_16x16x32_f16 v[56:59], v[136:139], v[186:189], 0
	v_mfma_f32_16x16x32_f16 v[44:47], v[128:131], v[194:197], 0
	v_mfma_f32_16x16x32_f16 v[40:43], v[136:139], v[194:197], 0
	v_mfma_f32_16x16x32_f16 v[28:31], v[128:131], v[206:209], 0
	v_mfma_f32_16x16x32_f16 v[24:27], v[136:139], v[206:209], 0
	v_mfma_f32_16x16x32_f16 v[12:15], v[128:131], v[214:217], 0
	v_mfma_f32_16x16x32_f16 v[8:11], v[136:139], v[214:217], 0
	v_mfma_f32_16x16x32_f16 v[60:63], v[132:135], v[190:193], v[60:63]
	v_mfma_f32_16x16x32_f16 v[56:59], v[140:143], v[190:193], v[56:59]
	v_mfma_f32_16x16x32_f16 v[44:47], v[132:135], v[198:201], v[44:47]
	v_mfma_f32_16x16x32_f16 v[40:43], v[140:143], v[198:201], v[40:43]
	v_mfma_f32_16x16x32_f16 v[28:31], v[132:135], v[210:213], v[28:31]
	v_mfma_f32_16x16x32_f16 v[24:27], v[140:143], v[210:213], v[24:27]
	v_mfma_f32_16x16x32_f16 v[12:15], v[132:135], v[218:221], v[12:15]
	v_mfma_f32_16x16x32_f16 v[8:11], v[140:143], v[218:221], v[8:11]
	v_mfma_f32_16x16x32_f16 v[52:55], v[160:163], v[186:189], 0
	v_mfma_f32_16x16x32_f16 v[48:51], v[178:181], v[186:189], 0
	v_mfma_f32_16x16x32_f16 v[36:39], v[160:163], v[194:197], 0
	v_mfma_f32_16x16x32_f16 v[32:35], v[178:181], v[194:197], 0
	v_mfma_f32_16x16x32_f16 v[20:23], v[160:163], v[206:209], 0
	v_mfma_f32_16x16x32_f16 v[16:19], v[178:181], v[206:209], 0
	v_mfma_f32_16x16x32_f16 v[4:7], v[160:163], v[214:217], 0
	v_mfma_f32_16x16x32_f16 v[0:3], v[178:181], v[214:217], 0
	v_mfma_f32_16x16x32_f16 v[52:55], v[172:175], v[190:193], v[52:55]
	v_mfma_f32_16x16x32_f16 v[48:51], v[182:185], v[190:193], v[48:51]
	v_mfma_f32_16x16x32_f16 v[36:39], v[172:175], v[198:201], v[36:39]
	v_mfma_f32_16x16x32_f16 v[32:35], v[182:185], v[198:201], v[32:35]
	v_mfma_f32_16x16x32_f16 v[20:23], v[172:175], v[210:213], v[20:23]
	v_mfma_f32_16x16x32_f16 v[16:19], v[182:185], v[210:213], v[16:19]
	v_mfma_f32_16x16x32_f16 v[4:7], v[172:175], v[218:221], v[4:7]
	v_mfma_f32_16x16x32_f16 v[0:3], v[182:185], v[218:221], v[0:3]
	s_barrier
	s_add_i32 s74, 0, 0x18000
	s_add_i32 s75, 0, 0x1c000
	v_add_u32_e32 v140, s74, v165
	v_add_u32_e32 v177, s75, v165
	ds_read_b128 v[128:131], v140
	ds_read_b128 v[132:135], v140 offset:1024
	ds_read_b128 v[136:139], v140 offset:2048
	ds_read_b128 v[140:143], v140 offset:3072
	ds_read_b128 v[160:163], v177
	ds_read_b128 v[172:175], v177 offset:1024
	ds_read_b128 v[178:181], v177 offset:2048
	ds_read_b128 v[182:185], v177 offset:3072
	s_add_u32 s46, s46, 0x40000
	s_addc_u32 s47, s47, 0
	s_mov_b32 m0, s54
	v_lshl_add_u64 v[228:229], s[46:47], 0, v[144:145]
	ds_read_b128 v[186:189], v169 offset:32768
	ds_read_b128 v[190:193], v169 offset:33792
	ds_read_b128 v[194:197], v169 offset:34816
	ds_read_b128 v[198:201], v169 offset:35840
	ds_read_b128 v[206:209], v169 offset:36864
	ds_read_b128 v[210:213], v169 offset:37888
	ds_read_b128 v[214:217], v169 offset:38912
	ds_read_b128 v[218:221], v169 offset:39936
	global_load_lds_dwordx4 v[228:229], off
	v_lshl_add_u64 v[228:229], s[46:47], 0, v[148:149]
	s_mov_b32 m0, s55
	s_nop 0
	global_load_lds_dwordx4 v[228:229], off
	s_waitcnt vmcnt(8)
	s_waitcnt lgkmcnt(0)
	s_barrier
	s_waitcnt lgkmcnt(0)
	v_mfma_f32_16x16x32_f16 v[124:127], v[128:131], v[186:189], v[124:127]
	v_mfma_f32_16x16x32_f16 v[120:123], v[136:139], v[186:189], v[120:123]
	v_mfma_f32_16x16x32_f16 v[108:111], v[128:131], v[194:197], v[108:111]
	v_mfma_f32_16x16x32_f16 v[104:107], v[136:139], v[194:197], v[104:107]
	v_mfma_f32_16x16x32_f16 v[92:95], v[128:131], v[206:209], v[92:95]
	v_mfma_f32_16x16x32_f16 v[88:91], v[136:139], v[206:209], v[88:91]
	v_mfma_f32_16x16x32_f16 v[84:87], v[128:131], v[214:217], v[84:87]
	v_mfma_f32_16x16x32_f16 v[76:79], v[136:139], v[214:217], v[76:79]
	v_mfma_f32_16x16x32_f16 v[124:127], v[132:135], v[190:193], v[124:127]
	v_mfma_f32_16x16x32_f16 v[120:123], v[140:143], v[190:193], v[120:123]
	v_mfma_f32_16x16x32_f16 v[108:111], v[132:135], v[198:201], v[108:111]
	v_mfma_f32_16x16x32_f16 v[104:107], v[140:143], v[198:201], v[104:107]
	v_mfma_f32_16x16x32_f16 v[92:95], v[132:135], v[210:213], v[92:95]
	v_mfma_f32_16x16x32_f16 v[88:91], v[140:143], v[210:213], v[88:91]
	v_mfma_f32_16x16x32_f16 v[84:87], v[132:135], v[218:221], v[84:87]
	v_mfma_f32_16x16x32_f16 v[76:79], v[140:143], v[218:221], v[76:79]
	v_mfma_f32_16x16x32_f16 v[116:119], v[160:163], v[186:189], v[116:119]
	v_mfma_f32_16x16x32_f16 v[112:115], v[178:181], v[186:189], v[112:115]
	v_mfma_f32_16x16x32_f16 v[100:103], v[160:163], v[194:197], v[100:103]
	v_mfma_f32_16x16x32_f16 v[96:99], v[178:181], v[194:197], v[96:99]
	v_mfma_f32_16x16x32_f16 v[80:83], v[160:163], v[206:209], v[80:83]
	v_mfma_f32_16x16x32_f16 v[72:75], v[178:181], v[206:209], v[72:75]
	v_mfma_f32_16x16x32_f16 v[68:71], v[160:163], v[214:217], v[68:71]
	v_mfma_f32_16x16x32_f16 v[64:67], v[178:181], v[214:217], v[64:67]
	v_mfma_f32_16x16x32_f16 v[116:119], v[172:175], v[190:193], v[116:119]
	v_mfma_f32_16x16x32_f16 v[112:115], v[182:185], v[190:193], v[112:115]
	v_mfma_f32_16x16x32_f16 v[100:103], v[172:175], v[198:201], v[100:103]
	v_mfma_f32_16x16x32_f16 v[96:99], v[182:185], v[198:201], v[96:99]
	v_mfma_f32_16x16x32_f16 v[80:83], v[172:175], v[210:213], v[80:83]
	v_mfma_f32_16x16x32_f16 v[72:75], v[182:185], v[210:213], v[72:75]
	v_mfma_f32_16x16x32_f16 v[68:71], v[172:175], v[218:221], v[68:71]
	v_mfma_f32_16x16x32_f16 v[64:67], v[182:185], v[218:221], v[64:67]
	s_barrier
	s_add_i32 s46, s74, s48
	v_lshl_add_u64 v[202:203], v[202:203], 0, s[4:5]
	s_mov_b32 m0, s46
	ds_read_b128 v[186:189], v169 offset:49152
	ds_read_b128 v[190:193], v169 offset:50176
	ds_read_b128 v[194:197], v169 offset:51200
	ds_read_b128 v[198:201], v169 offset:52224
	ds_read_b128 v[206:209], v169 offset:53248
	ds_read_b128 v[210:213], v169 offset:54272
	ds_read_b128 v[214:217], v169 offset:55296
	ds_read_b128 v[218:221], v169 offset:56320
	global_load_lds_dwordx4 v[202:203], off
	s_add_i32 m0, s46, 0x2000
	s_add_u32 s44, s44, 0x40080
	v_lshl_add_u64 v[202:203], v[222:223], 0, s[4:5]
	s_addc_u32 s45, s45, 0
	s_add_i32 s46, s75, s48
	global_load_lds_dwordx4 v[202:203], off
	v_lshl_add_u64 v[202:203], s[44:45], 0, v[146:147]
	s_mov_b32 m0, s46
	s_nop 0
	global_load_lds_dwordx4 v[202:203], off
	v_lshl_add_u64 v[202:203], s[44:45], 0, v[150:151]
	s_add_i32 m0, s46, 0x2000
	s_nop 0
	global_load_lds_dwordx4 v[202:203], off
	v_lshl_add_u64 v[202:203], v[224:225], 0, s[4:5]
	s_mov_b32 m0, s59
	s_nop 0
	global_load_lds_dwordx4 v[202:203], off
	v_lshl_add_u64 v[202:203], v[226:227], 0, s[4:5]
	s_mov_b32 m0, s60
	s_nop 0
	global_load_lds_dwordx4 v[202:203], off
	s_waitcnt vmcnt(8)
	s_waitcnt lgkmcnt(0)
	s_barrier
	s_waitcnt lgkmcnt(0)
	v_mfma_f32_16x16x32_f16 v[60:63], v[128:131], v[186:189], v[60:63]
	v_mfma_f32_16x16x32_f16 v[56:59], v[136:139], v[186:189], v[56:59]
	v_mfma_f32_16x16x32_f16 v[44:47], v[128:131], v[194:197], v[44:47]
	v_mfma_f32_16x16x32_f16 v[40:43], v[136:139], v[194:197], v[40:43]
	v_mfma_f32_16x16x32_f16 v[28:31], v[128:131], v[206:209], v[28:31]
	v_mfma_f32_16x16x32_f16 v[24:27], v[136:139], v[206:209], v[24:27]
	v_mfma_f32_16x16x32_f16 v[12:15], v[128:131], v[214:217], v[12:15]
	v_mfma_f32_16x16x32_f16 v[8:11], v[136:139], v[214:217], v[8:11]
	v_mfma_f32_16x16x32_f16 v[60:63], v[132:135], v[190:193], v[60:63]
	v_mfma_f32_16x16x32_f16 v[56:59], v[140:143], v[190:193], v[56:59]
	v_mfma_f32_16x16x32_f16 v[44:47], v[132:135], v[198:201], v[44:47]
	v_mfma_f32_16x16x32_f16 v[40:43], v[140:143], v[198:201], v[40:43]
	v_mfma_f32_16x16x32_f16 v[28:31], v[132:135], v[210:213], v[28:31]
	v_mfma_f32_16x16x32_f16 v[24:27], v[140:143], v[210:213], v[24:27]
	v_mfma_f32_16x16x32_f16 v[12:15], v[132:135], v[218:221], v[12:15]
	v_mfma_f32_16x16x32_f16 v[8:11], v[140:143], v[218:221], v[8:11]
	v_mfma_f32_16x16x32_f16 v[52:55], v[160:163], v[186:189], v[52:55]
	v_mfma_f32_16x16x32_f16 v[48:51], v[178:181], v[186:189], v[48:51]
	v_mfma_f32_16x16x32_f16 v[36:39], v[160:163], v[194:197], v[36:39]
	v_mfma_f32_16x16x32_f16 v[32:35], v[178:181], v[194:197], v[32:35]
	v_mfma_f32_16x16x32_f16 v[20:23], v[160:163], v[206:209], v[20:23]
	v_mfma_f32_16x16x32_f16 v[16:19], v[178:181], v[206:209], v[16:19]
	v_mfma_f32_16x16x32_f16 v[4:7], v[160:163], v[214:217], v[4:7]
	v_mfma_f32_16x16x32_f16 v[0:3], v[178:181], v[214:217], v[0:3]
	v_mfma_f32_16x16x32_f16 v[52:55], v[172:175], v[190:193], v[52:55]
	v_mfma_f32_16x16x32_f16 v[48:51], v[182:185], v[190:193], v[48:51]
	v_mfma_f32_16x16x32_f16 v[36:39], v[172:175], v[198:201], v[36:39]
	v_mfma_f32_16x16x32_f16 v[32:35], v[182:185], v[198:201], v[32:35]
	v_mfma_f32_16x16x32_f16 v[20:23], v[172:175], v[210:213], v[20:23]
	v_mfma_f32_16x16x32_f16 v[16:19], v[182:185], v[210:213], v[16:19]
	v_mfma_f32_16x16x32_f16 v[4:7], v[172:175], v[218:221], v[4:7]
	v_mfma_f32_16x16x32_f16 v[0:3], v[182:185], v[218:221], v[0:3]
	s_barrier
	s_add_i32 s73, s73, 2
	s_add_u32 s40, s40, 0x100
	s_addc_u32 s41, s41, 0
	s_add_u32 s71, s71, 0x100
	s_addc_u32 s72, s72, 0
	s_cmp_gt_u32 s73, 13

.LBB0_733:
	s_ashr_i32 s19, s18, 31
	s_lshl_b64 s[20:21], s[18:19], 19
	s_add_u32 s20, s33, s20
	s_addc_u32 s21, s46, s21
	s_and_b64 s[22:23], s[4:5], exec
	s_cselect_b32 s19, s21, s35
	s_cselect_b32 s25, s20, s34
	s_ashr_i32 s17, s16, 31
	s_lshl_b64 s[22:23], s[16:17], 19
	s_add_u32 s22, s47, s22
	s_addc_u32 s23, s48, s23
	s_and_b64 s[44:45], s[4:5], exec
	s_cselect_b32 s17, s23, s41
	s_cselect_b32 s68, s22, s40
	s_add_u32 s34, s34, 0x40080
	s_addc_u32 s35, s35, 0
	s_add_u32 s69, s40, 0x100
	s_addc_u32 s70, s41, 0
	s_mov_b32 s71, -2
	s_waitcnt lgkmcnt(0)
	s_waitcnt lgkmcnt(0)
	ds_read_b128 v[84:87], v208
	ds_read_b128 v[88:91], v208 offset:1024
	ds_read_b128 v[92:95], v208 offset:2048
	ds_read_b128 v[100:103], v208 offset:3072
	ds_read_b128 v[144:147], v209
	ds_read_b128 v[148:151], v209 offset:1024
	ds_read_b128 v[152:155], v209 offset:2048
	ds_read_b128 v[156:159], v209 offset:3072
	s_add_u32 s40, s34, 0xfffc0080
	s_addc_u32 s41, s35, -1
	s_cmp_eq_u32 s71, 12
	s_cselect_b32 s45, s19, s41
	s_cselect_b32 s44, s25, s40
	s_cselect_b32 s41, s17, s70
	s_cselect_b32 s40, s68, s69
	v_lshl_add_u64 v[202:203], s[34:35], 0, v[178:179]
	s_add_i32 m0, s27, 0xc000
	ds_read_b128 v[160:163], v210
	ds_read_b128 v[164:167], v210 offset:1024
	ds_read_b128 v[186:189], v210 offset:2048
	ds_read_b128 v[190:193], v210 offset:3072
	ds_read_b128 v[194:197], v210 offset:4096
	ds_read_b128 v[198:201], v210 offset:5120
	ds_read_b128 v[212:215], v210 offset:6144
	ds_read_b128 v[216:219], v210 offset:7168
	global_load_lds_dwordx4 v[202:203], off
	v_lshl_add_u64 v[202:203], s[34:35], 0, v[180:181]
	s_add_i32 m0, s27, 0xe000
	s_nop 0
	global_load_lds_dwordx4 v[202:203], off
	s_waitcnt vmcnt(8)
	s_waitcnt lgkmcnt(0)
	s_barrier
	s_waitcnt lgkmcnt(0)
	v_mfma_f32_16x16x32_f16 v[136:139], v[84:87], v[160:163], 0
	v_mfma_f32_16x16x32_f16 v[128:131], v[92:95], v[160:163], 0
	v_mfma_f32_16x16x32_f16 v[124:127], v[84:87], v[186:189], 0
	v_mfma_f32_16x16x32_f16 v[116:119], v[92:95], v[186:189], 0
	v_mfma_f32_16x16x32_f16 v[108:111], v[84:87], v[194:197], 0
	v_mfma_f32_16x16x32_f16 v[96:99], v[92:95], v[194:197], 0
	v_mfma_f32_16x16x32_f16 v[76:79], v[84:87], v[212:215], 0
	v_mfma_f32_16x16x32_f16 v[68:71], v[92:95], v[212:215], 0
	v_mfma_f32_16x16x32_f16 v[136:139], v[88:91], v[164:167], v[136:139]
	v_mfma_f32_16x16x32_f16 v[128:131], v[100:103], v[164:167], v[128:131]
	v_mfma_f32_16x16x32_f16 v[124:127], v[88:91], v[190:193], v[124:127]
	v_mfma_f32_16x16x32_f16 v[116:119], v[100:103], v[190:193], v[116:119]
	v_mfma_f32_16x16x32_f16 v[108:111], v[88:91], v[198:201], v[108:111]
	v_mfma_f32_16x16x32_f16 v[96:99], v[100:103], v[198:201], v[96:99]
	v_mfma_f32_16x16x32_f16 v[76:79], v[88:91], v[216:219], v[76:79]
	v_mfma_f32_16x16x32_f16 v[68:71], v[100:103], v[216:219], v[68:71]
	v_mfma_f32_16x16x32_f16 v[140:143], v[144:147], v[160:163], 0
	v_mfma_f32_16x16x32_f16 v[132:135], v[152:155], v[160:163], 0
	v_mfma_f32_16x16x32_f16 v[120:123], v[144:147], v[186:189], 0
	v_mfma_f32_16x16x32_f16 v[112:115], v[152:155], v[186:189], 0
	v_mfma_f32_16x16x32_f16 v[104:107], v[144:147], v[194:197], 0
	v_mfma_f32_16x16x32_f16 v[80:83], v[152:155], v[194:197], 0
	v_mfma_f32_16x16x32_f16 v[72:75], v[144:147], v[212:215], 0
	v_mfma_f32_16x16x32_f16 v[64:67], v[152:155], v[212:215], 0
	v_mfma_f32_16x16x32_f16 v[140:143], v[148:151], v[164:167], v[140:143]
	v_mfma_f32_16x16x32_f16 v[132:135], v[156:159], v[164:167], v[132:135]
	v_mfma_f32_16x16x32_f16 v[120:123], v[148:151], v[190:193], v[120:123]
	v_mfma_f32_16x16x32_f16 v[112:115], v[156:159], v[190:193], v[112:115]
	v_mfma_f32_16x16x32_f16 v[104:107], v[148:151], v[198:201], v[104:107]
	v_mfma_f32_16x16x32_f16 v[80:83], v[156:159], v[198:201], v[80:83]
	v_mfma_f32_16x16x32_f16 v[72:75], v[148:151], v[216:219], v[72:75]
	v_mfma_f32_16x16x32_f16 v[64:67], v[156:159], v[216:219], v[64:67]
	s_barrier
	s_add_i32 s72, s66, s49
	v_lshl_add_u64 v[202:203], s[40:41], 0, v[170:171]
	s_mov_b32 m0, s72
	ds_read_b128 v[160:163], v210 offset:16384
	ds_read_b128 v[164:167], v210 offset:17408
	ds_read_b128 v[186:189], v210 offset:18432
	ds_read_b128 v[190:193], v210 offset:19456
	ds_read_b128 v[194:197], v210 offset:20480
	ds_read_b128 v[198:201], v210 offset:21504
	ds_read_b128 v[212:215], v210 offset:22528
	ds_read_b128 v[216:219], v210 offset:23552
	global_load_lds_dwordx4 v[202:203], off
	s_add_i32 m0, s72, 0x2000
	s_add_u32 s72, s40, 0x40000
	v_lshl_add_u64 v[220:221], s[40:41], 0, v[174:175]
	s_addc_u32 s73, s41, 0
	s_add_i32 s74, s67, s49
	global_load_lds_dwordx4 v[220:221], off
	v_lshl_add_u64 v[222:223], s[72:73], 0, v[170:171]
	s_mov_b32 m0, s74
	v_lshl_add_u64 v[224:225], s[44:45], 0, v[172:173]
	global_load_lds_dwordx4 v[222:223], off
	v_lshl_add_u64 v[222:223], s[72:73], 0, v[174:175]
	s_add_i32 m0, s74, 0x2000
	s_nop 0
	global_load_lds_dwordx4 v[222:223], off
	v_lshl_add_u64 v[222:223], s[44:45], 0, v[168:169]
	s_mov_b32 m0, s27
	s_nop 0
	global_load_lds_dwordx4 v[222:223], off
	s_mov_b32 m0, s54
	s_nop 0
	global_load_lds_dwordx4 v[224:225], off
	s_waitcnt vmcnt(8)
	s_waitcnt lgkmcnt(0)
	s_barrier
	s_waitcnt lgkmcnt(0)
	v_mfma_f32_16x16x32_f16 v[60:63], v[84:87], v[160:163], 0
	v_mfma_f32_16x16x32_f16 v[52:55], v[92:95], v[160:163], 0
	v_mfma_f32_16x16x32_f16 v[44:47], v[84:87], v[186:189], 0
	v_mfma_f32_16x16x32_f16 v[36:39], v[92:95], v[186:189], 0
	v_mfma_f32_16x16x32_f16 v[28:31], v[84:87], v[194:197], 0
	v_mfma_f32_16x16x32_f16 v[20:23], v[92:95], v[194:197], 0
	v_mfma_f32_16x16x32_f16 v[12:15], v[84:87], v[212:215], 0
	v_mfma_f32_16x16x32_f16 v[4:7], v[92:95], v[212:215], 0
	v_mfma_f32_16x16x32_f16 v[60:63], v[88:91], v[164:167], v[60:63]
	v_mfma_f32_16x16x32_f16 v[52:55], v[100:103], v[164:167], v[52:55]
	v_mfma_f32_16x16x32_f16 v[44:47], v[88:91], v[190:193], v[44:47]
	v_mfma_f32_16x16x32_f16 v[36:39], v[100:103], v[190:193], v[36:39]
	v_mfma_f32_16x16x32_f16 v[28:31], v[88:91], v[198:201], v[28:31]
	v_mfma_f32_16x16x32_f16 v[20:23], v[100:103], v[198:201], v[20:23]
	v_mfma_f32_16x16x32_f16 v[12:15], v[88:91], v[216:219], v[12:15]
	v_mfma_f32_16x16x32_f16 v[4:7], v[100:103], v[216:219], v[4:7]
	v_mfma_f32_16x16x32_f16 v[56:59], v[144:147], v[160:163], 0
	v_mfma_f32_16x16x32_f16 v[48:51], v[152:155], v[160:163], 0
	v_mfma_f32_16x16x32_f16 v[40:43], v[144:147], v[186:189], 0
	v_mfma_f32_16x16x32_f16 v[32:35], v[152:155], v[186:189], 0
	v_mfma_f32_16x16x32_f16 v[24:27], v[144:147], v[194:197], 0
	v_mfma_f32_16x16x32_f16 v[16:19], v[152:155], v[194:197], 0
	v_mfma_f32_16x16x32_f16 v[8:11], v[144:147], v[212:215], 0
	v_mfma_f32_16x16x32_f16 v[0:3], v[152:155], v[212:215], 0
	v_mfma_f32_16x16x32_f16 v[56:59], v[148:151], v[164:167], v[56:59]
	v_mfma_f32_16x16x32_f16 v[48:51], v[156:159], v[164:167], v[48:51]
	v_mfma_f32_16x16x32_f16 v[40:43], v[148:151], v[190:193], v[40:43]
	v_mfma_f32_16x16x32_f16 v[32:35], v[156:159], v[190:193], v[32:35]
	v_mfma_f32_16x16x32_f16 v[24:27], v[148:151], v[198:201], v[24:27]
	v_mfma_f32_16x16x32_f16 v[16:19], v[156:159], v[198:201], v[16:19]
	v_mfma_f32_16x16x32_f16 v[8:11], v[148:151], v[216:219], v[8:11]
	v_mfma_f32_16x16x32_f16 v[0:3], v[156:159], v[216:219], v[0:3]
	s_barrier
	s_add_i32 s72, 0, 0x18000
	s_add_i32 s73, 0, 0x1c000
	v_add_u32_e32 v100, s72, v206
	v_add_u32_e32 v156, s73, v206
	ds_read_b128 v[84:87], v100
	ds_read_b128 v[88:91], v100 offset:1024
	ds_read_b128 v[92:95], v100 offset:2048
	ds_read_b128 v[100:103], v100 offset:3072
	ds_read_b128 v[144:147], v156
	ds_read_b128 v[148:151], v156 offset:1024
	ds_read_b128 v[152:155], v156 offset:2048
	ds_read_b128 v[156:159], v156 offset:3072
	s_add_u32 s44, s44, 0x40000
	s_addc_u32 s45, s45, 0
	s_mov_b32 m0, s55
	v_lshl_add_u64 v[226:227], s[44:45], 0, v[168:169]
	ds_read_b128 v[160:163], v210 offset:32768
	ds_read_b128 v[164:167], v210 offset:33792
	ds_read_b128 v[186:189], v210 offset:34816
	ds_read_b128 v[190:193], v210 offset:35840
	ds_read_b128 v[194:197], v210 offset:36864
	ds_read_b128 v[198:201], v210 offset:37888
	ds_read_b128 v[212:215], v210 offset:38912
	ds_read_b128 v[216:219], v210 offset:39936
	global_load_lds_dwordx4 v[226:227], off
	v_lshl_add_u64 v[226:227], s[44:45], 0, v[172:173]
	s_mov_b32 m0, s56
	s_nop 0
	global_load_lds_dwordx4 v[226:227], off
	s_waitcnt vmcnt(8)
	s_waitcnt lgkmcnt(0)
	s_barrier
	s_waitcnt lgkmcnt(0)
	v_mfma_f32_16x16x32_f16 v[136:139], v[84:87], v[160:163], v[136:139]
	v_mfma_f32_16x16x32_f16 v[128:131], v[92:95], v[160:163], v[128:131]
	v_mfma_f32_16x16x32_f16 v[124:127], v[84:87], v[186:189], v[124:127]
	v_mfma_f32_16x16x32_f16 v[116:119], v[92:95], v[186:189], v[116:119]
	v_mfma_f32_16x16x32_f16 v[108:111], v[84:87], v[194:197], v[108:111]
	v_mfma_f32_16x16x32_f16 v[96:99], v[92:95], v[194:197], v[96:99]
	v_mfma_f32_16x16x32_f16 v[76:79], v[84:87], v[212:215], v[76:79]
	v_mfma_f32_16x16x32_f16 v[68:71], v[92:95], v[212:215], v[68:71]
	v_mfma_f32_16x16x32_f16 v[136:139], v[88:91], v[164:167], v[136:139]
	v_mfma_f32_16x16x32_f16 v[128:131], v[100:103], v[164:167], v[128:131]
	v_mfma_f32_16x16x32_f16 v[124:127], v[88:91], v[190:193], v[124:127]
	v_mfma_f32_16x16x32_f16 v[116:119], v[100:103], v[190:193], v[116:119]
	v_mfma_f32_16x16x32_f16 v[108:111], v[88:91], v[198:201], v[108:111]
	v_mfma_f32_16x16x32_f16 v[96:99], v[100:103], v[198:201], v[96:99]
	v_mfma_f32_16x16x32_f16 v[76:79], v[88:91], v[216:219], v[76:79]
	v_mfma_f32_16x16x32_f16 v[68:71], v[100:103], v[216:219], v[68:71]
	v_mfma_f32_16x16x32_f16 v[140:143], v[144:147], v[160:163], v[140:143]
	v_mfma_f32_16x16x32_f16 v[132:135], v[152:155], v[160:163], v[132:135]
	v_mfma_f32_16x16x32_f16 v[120:123], v[144:147], v[186:189], v[120:123]
	v_mfma_f32_16x16x32_f16 v[112:115], v[152:155], v[186:189], v[112:115]
	v_mfma_f32_16x16x32_f16 v[104:107], v[144:147], v[194:197], v[104:107]
	v_mfma_f32_16x16x32_f16 v[80:83], v[152:155], v[194:197], v[80:83]
	v_mfma_f32_16x16x32_f16 v[72:75], v[144:147], v[212:215], v[72:75]
	v_mfma_f32_16x16x32_f16 v[64:67], v[152:155], v[212:215], v[64:67]
	v_mfma_f32_16x16x32_f16 v[140:143], v[148:151], v[164:167], v[140:143]
	v_mfma_f32_16x16x32_f16 v[132:135], v[156:159], v[164:167], v[132:135]
	v_mfma_f32_16x16x32_f16 v[120:123], v[148:151], v[190:193], v[120:123]
	v_mfma_f32_16x16x32_f16 v[112:115], v[156:159], v[190:193], v[112:115]
	v_mfma_f32_16x16x32_f16 v[104:107], v[148:151], v[198:201], v[104:107]
	v_mfma_f32_16x16x32_f16 v[80:83], v[156:159], v[198:201], v[80:83]
	v_mfma_f32_16x16x32_f16 v[72:75], v[148:151], v[216:219], v[72:75]
	v_mfma_f32_16x16x32_f16 v[64:67], v[156:159], v[216:219], v[64:67]
	s_barrier
	s_add_i32 s44, s72, s49
	v_lshl_add_u64 v[202:203], v[202:203], 0, s[12:13]
	s_mov_b32 m0, s44
	ds_read_b128 v[160:163], v210 offset:49152
	ds_read_b128 v[164:167], v210 offset:50176
	ds_read_b128 v[186:189], v210 offset:51200
	ds_read_b128 v[190:193], v210 offset:52224
	ds_read_b128 v[194:197], v210 offset:53248
	ds_read_b128 v[198:201], v210 offset:54272
	ds_read_b128 v[212:215], v210 offset:55296
	ds_read_b128 v[216:219], v210 offset:56320
	global_load_lds_dwordx4 v[202:203], off
	s_add_i32 m0, s44, 0x2000
	s_add_u32 s40, s40, 0x40080
	v_lshl_add_u64 v[202:203], v[220:221], 0, s[12:13]
	s_addc_u32 s41, s41, 0
	s_add_i32 s44, s73, s49
	global_load_lds_dwordx4 v[202:203], off
	v_lshl_add_u64 v[202:203], s[40:41], 0, v[170:171]
	s_mov_b32 m0, s44
	s_nop 0
	global_load_lds_dwordx4 v[202:203], off
	v_lshl_add_u64 v[202:203], s[40:41], 0, v[174:175]
	s_add_i32 m0, s44, 0x2000
	s_nop 0
	global_load_lds_dwordx4 v[202:203], off
	v_lshl_add_u64 v[202:203], v[222:223], 0, s[12:13]
	s_mov_b32 m0, s62
	s_nop 0
	global_load_lds_dwordx4 v[202:203], off
	v_lshl_add_u64 v[202:203], v[224:225], 0, s[12:13]
	s_mov_b32 m0, s63
	s_nop 0
	global_load_lds_dwordx4 v[202:203], off
	s_waitcnt vmcnt(8)
	s_waitcnt lgkmcnt(0)
	s_barrier
	s_waitcnt lgkmcnt(0)
	v_mfma_f32_16x16x32_f16 v[60:63], v[84:87], v[160:163], v[60:63]
	v_mfma_f32_16x16x32_f16 v[52:55], v[92:95], v[160:163], v[52:55]
	v_mfma_f32_16x16x32_f16 v[44:47], v[84:87], v[186:189], v[44:47]
	v_mfma_f32_16x16x32_f16 v[36:39], v[92:95], v[186:189], v[36:39]
	v_mfma_f32_16x16x32_f16 v[28:31], v[84:87], v[194:197], v[28:31]
	v_mfma_f32_16x16x32_f16 v[20:23], v[92:95], v[194:197], v[20:23]
	v_mfma_f32_16x16x32_f16 v[12:15], v[84:87], v[212:215], v[12:15]
	v_mfma_f32_16x16x32_f16 v[4:7], v[92:95], v[212:215], v[4:7]
	v_mfma_f32_16x16x32_f16 v[60:63], v[88:91], v[164:167], v[60:63]
	v_mfma_f32_16x16x32_f16 v[52:55], v[100:103], v[164:167], v[52:55]
	v_mfma_f32_16x16x32_f16 v[44:47], v[88:91], v[190:193], v[44:47]
	v_mfma_f32_16x16x32_f16 v[36:39], v[100:103], v[190:193], v[36:39]
	v_mfma_f32_16x16x32_f16 v[28:31], v[88:91], v[198:201], v[28:31]
	v_mfma_f32_16x16x32_f16 v[20:23], v[100:103], v[198:201], v[20:23]
	v_mfma_f32_16x16x32_f16 v[12:15], v[88:91], v[216:219], v[12:15]
	v_mfma_f32_16x16x32_f16 v[4:7], v[100:103], v[216:219], v[4:7]
	v_mfma_f32_16x16x32_f16 v[56:59], v[144:147], v[160:163], v[56:59]
	v_mfma_f32_16x16x32_f16 v[48:51], v[152:155], v[160:163], v[48:51]
	v_mfma_f32_16x16x32_f16 v[40:43], v[144:147], v[186:189], v[40:43]
	v_mfma_f32_16x16x32_f16 v[32:35], v[152:155], v[186:189], v[32:35]
	v_mfma_f32_16x16x32_f16 v[24:27], v[144:147], v[194:197], v[24:27]
	v_mfma_f32_16x16x32_f16 v[16:19], v[152:155], v[194:197], v[16:19]
	v_mfma_f32_16x16x32_f16 v[8:11], v[144:147], v[212:215], v[8:11]
	v_mfma_f32_16x16x32_f16 v[0:3], v[152:155], v[212:215], v[0:3]
	v_mfma_f32_16x16x32_f16 v[56:59], v[148:151], v[164:167], v[56:59]
	v_mfma_f32_16x16x32_f16 v[48:51], v[156:159], v[164:167], v[48:51]
	v_mfma_f32_16x16x32_f16 v[40:43], v[148:151], v[190:193], v[40:43]
	v_mfma_f32_16x16x32_f16 v[32:35], v[156:159], v[190:193], v[32:35]
	v_mfma_f32_16x16x32_f16 v[24:27], v[148:151], v[198:201], v[24:27]
	v_mfma_f32_16x16x32_f16 v[16:19], v[156:159], v[198:201], v[16:19]
	v_mfma_f32_16x16x32_f16 v[8:11], v[148:151], v[216:219], v[8:11]
	v_mfma_f32_16x16x32_f16 v[0:3], v[156:159], v[216:219], v[0:3]
	s_barrier
	s_add_i32 s71, s71, 2
	s_add_u32 s34, s34, 0x100
	s_addc_u32 s35, s35, 0
	s_add_u32 s69, s69, 0x100
	s_addc_u32 s70, s70, 0
	s_cmp_gt_u32 s71, 13

.LBB0_872:
	s_ashr_i32 s17, s16, 31
	s_lshl_b64 s[18:19], s[16:17], 19
	s_add_u32 s18, s42, s18
	s_addc_u32 s19, s43, s19
	s_and_b64 s[20:21], s[2:3], exec
	s_cselect_b32 s17, s19, s25
	s_cselect_b32 s63, s18, s24
	s_ashr_i32 s15, s14, 31
	s_lshl_b64 s[20:21], s[14:15], 19
	s_add_u32 s20, s40, s20
	s_addc_u32 s21, s41, s21
	s_and_b64 s[34:35], s[2:3], exec
	s_cselect_b32 s15, s21, s27
	s_cselect_b32 s64, s20, s26
	s_add_u32 s24, s24, 0x40080
	s_addc_u32 s25, s25, 0
	s_add_u32 s65, s26, 0x100
	s_addc_u32 s66, s27, 0
	s_mov_b32 s67, -2
	ds_read_b128 v[104:107], v171
	ds_read_b128 v[108:111], v171 offset:1024
	ds_read_b128 v[112:115], v171 offset:2048
	ds_read_b128 v[116:119], v171 offset:3072
	ds_read_b128 v[160:163], v172
	ds_read_b128 v[164:167], v172 offset:1024
	ds_read_b128 v[178:181], v172 offset:2048
	ds_read_b128 v[182:185], v172 offset:3072
	s_add_u32 s26, s24, 0xfffc0080
	s_addc_u32 s27, s25, -1
	s_cmp_eq_u32 s67, 12
	s_cselect_b32 s35, s17, s27
	s_cselect_b32 s34, s63, s26
	s_cselect_b32 s27, s15, s66
	s_cselect_b32 s26, s64, s65
	v_lshl_add_u64 v[202:203], s[24:25], 0, v[152:153]
	s_add_i32 m0, s23, 0xc000
	ds_read_b128 v[186:189], v173
	ds_read_b128 v[190:193], v173 offset:1024
	ds_read_b128 v[194:197], v173 offset:2048
	ds_read_b128 v[198:201], v173 offset:3072
	ds_read_b128 v[206:209], v173 offset:4096
	ds_read_b128 v[210:213], v173 offset:5120
	ds_read_b128 v[214:217], v173 offset:6144
	ds_read_b128 v[218:221], v173 offset:7168
	global_load_lds_dwordx4 v[202:203], off
	v_lshl_add_u64 v[202:203], s[24:25], 0, v[154:155]
	s_add_i32 m0, s23, 0xe000
	s_nop 0
	global_load_lds_dwordx4 v[202:203], off
	s_waitcnt vmcnt(8)
	s_waitcnt lgkmcnt(0)
	s_barrier
	s_waitcnt lgkmcnt(0)
	v_mfma_f32_16x16x32_f16 v[140:143], v[104:107], v[186:189], 0
	v_mfma_f32_16x16x32_f16 v[136:139], v[112:115], v[186:189], 0
	v_mfma_f32_16x16x32_f16 v[124:127], v[104:107], v[194:197], 0
	v_mfma_f32_16x16x32_f16 v[120:123], v[112:115], v[194:197], 0
	v_mfma_f32_16x16x32_f16 v[92:95], v[104:107], v[206:209], 0
	v_mfma_f32_16x16x32_f16 v[88:91], v[112:115], v[206:209], 0
	v_mfma_f32_16x16x32_f16 v[76:79], v[104:107], v[214:217], 0
	v_mfma_f32_16x16x32_f16 v[72:75], v[112:115], v[214:217], 0
	v_mfma_f32_16x16x32_f16 v[140:143], v[108:111], v[190:193], v[140:143]
	v_mfma_f32_16x16x32_f16 v[136:139], v[116:119], v[190:193], v[136:139]
	v_mfma_f32_16x16x32_f16 v[124:127], v[108:111], v[198:201], v[124:127]
	v_mfma_f32_16x16x32_f16 v[120:123], v[116:119], v[198:201], v[120:123]
	v_mfma_f32_16x16x32_f16 v[92:95], v[108:111], v[210:213], v[92:95]
	v_mfma_f32_16x16x32_f16 v[88:91], v[116:119], v[210:213], v[88:91]
	v_mfma_f32_16x16x32_f16 v[76:79], v[108:111], v[218:221], v[76:79]
	v_mfma_f32_16x16x32_f16 v[72:75], v[116:119], v[218:221], v[72:75]
	v_mfma_f32_16x16x32_f16 v[132:135], v[160:163], v[186:189], 0
	v_mfma_f32_16x16x32_f16 v[128:131], v[178:181], v[186:189], 0
	v_mfma_f32_16x16x32_f16 v[100:103], v[160:163], v[194:197], 0
	v_mfma_f32_16x16x32_f16 v[96:99], v[178:181], v[194:197], 0
	v_mfma_f32_16x16x32_f16 v[84:87], v[160:163], v[206:209], 0
	v_mfma_f32_16x16x32_f16 v[80:83], v[178:181], v[206:209], 0
	v_mfma_f32_16x16x32_f16 v[68:71], v[160:163], v[214:217], 0
	v_mfma_f32_16x16x32_f16 v[64:67], v[178:181], v[214:217], 0
	v_mfma_f32_16x16x32_f16 v[132:135], v[164:167], v[190:193], v[132:135]
	v_mfma_f32_16x16x32_f16 v[128:131], v[182:185], v[190:193], v[128:131]
	v_mfma_f32_16x16x32_f16 v[100:103], v[164:167], v[198:201], v[100:103]
	v_mfma_f32_16x16x32_f16 v[96:99], v[182:185], v[198:201], v[96:99]
	v_mfma_f32_16x16x32_f16 v[84:87], v[164:167], v[210:213], v[84:87]
	v_mfma_f32_16x16x32_f16 v[80:83], v[182:185], v[210:213], v[80:83]
	v_mfma_f32_16x16x32_f16 v[68:71], v[164:167], v[218:221], v[68:71]
	v_mfma_f32_16x16x32_f16 v[64:67], v[182:185], v[218:221], v[64:67]
	s_barrier
	s_add_i32 s68, s58, s44
	v_lshl_add_u64 v[202:203], s[26:27], 0, v[146:147]
	s_mov_b32 m0, s68
	ds_read_b128 v[186:189], v173 offset:16384
	ds_read_b128 v[190:193], v173 offset:17408
	ds_read_b128 v[194:197], v173 offset:18432
	ds_read_b128 v[198:201], v173 offset:19456
	ds_read_b128 v[206:209], v173 offset:20480
	ds_read_b128 v[210:213], v173 offset:21504
	ds_read_b128 v[214:217], v173 offset:22528
	ds_read_b128 v[218:221], v173 offset:23552
	global_load_lds_dwordx4 v[202:203], off
	s_add_i32 m0, s68, 0x2000
	s_add_u32 s68, s26, 0x40000
	v_lshl_add_u64 v[222:223], s[26:27], 0, v[150:151]
	s_addc_u32 s69, s27, 0
	s_add_i32 s70, s59, s44
	global_load_lds_dwordx4 v[222:223], off
	v_lshl_add_u64 v[224:225], s[68:69], 0, v[146:147]
	s_mov_b32 m0, s70
	v_lshl_add_u64 v[226:227], s[34:35], 0, v[148:149]
	global_load_lds_dwordx4 v[224:225], off
	v_lshl_add_u64 v[224:225], s[68:69], 0, v[150:151]
	s_add_i32 m0, s70, 0x2000
	s_nop 0
	global_load_lds_dwordx4 v[224:225], off
	v_lshl_add_u64 v[224:225], s[34:35], 0, v[144:145]
	s_mov_b32 m0, s23
	s_nop 0
	global_load_lds_dwordx4 v[224:225], off
	s_mov_b32 m0, s45
	s_nop 0
	global_load_lds_dwordx4 v[226:227], off
	s_waitcnt vmcnt(8)
	s_waitcnt lgkmcnt(0)
	s_barrier
	s_waitcnt lgkmcnt(0)
	v_mfma_f32_16x16x32_f16 v[60:63], v[104:107], v[186:189], 0
	v_mfma_f32_16x16x32_f16 v[56:59], v[112:115], v[186:189], 0
	v_mfma_f32_16x16x32_f16 v[44:47], v[104:107], v[194:197], 0
	v_mfma_f32_16x16x32_f16 v[40:43], v[112:115], v[194:197], 0
	v_mfma_f32_16x16x32_f16 v[28:31], v[104:107], v[206:209], 0
	v_mfma_f32_16x16x32_f16 v[24:27], v[112:115], v[206:209], 0
	v_mfma_f32_16x16x32_f16 v[12:15], v[104:107], v[214:217], 0
	v_mfma_f32_16x16x32_f16 v[8:11], v[112:115], v[214:217], 0
	v_mfma_f32_16x16x32_f16 v[60:63], v[108:111], v[190:193], v[60:63]
	v_mfma_f32_16x16x32_f16 v[56:59], v[116:119], v[190:193], v[56:59]
	v_mfma_f32_16x16x32_f16 v[44:47], v[108:111], v[198:201], v[44:47]
	v_mfma_f32_16x16x32_f16 v[40:43], v[116:119], v[198:201], v[40:43]
	v_mfma_f32_16x16x32_f16 v[28:31], v[108:111], v[210:213], v[28:31]
	v_mfma_f32_16x16x32_f16 v[24:27], v[116:119], v[210:213], v[24:27]
	v_mfma_f32_16x16x32_f16 v[12:15], v[108:111], v[218:221], v[12:15]
	v_mfma_f32_16x16x32_f16 v[8:11], v[116:119], v[218:221], v[8:11]
	v_mfma_f32_16x16x32_f16 v[52:55], v[160:163], v[186:189], 0
	v_mfma_f32_16x16x32_f16 v[48:51], v[178:181], v[186:189], 0
	v_mfma_f32_16x16x32_f16 v[36:39], v[160:163], v[194:197], 0
	v_mfma_f32_16x16x32_f16 v[32:35], v[178:181], v[194:197], 0
	v_mfma_f32_16x16x32_f16 v[20:23], v[160:163], v[206:209], 0
	v_mfma_f32_16x16x32_f16 v[16:19], v[178:181], v[206:209], 0
	v_mfma_f32_16x16x32_f16 v[4:7], v[160:163], v[214:217], 0
	v_mfma_f32_16x16x32_f16 v[0:3], v[178:181], v[214:217], 0
	v_mfma_f32_16x16x32_f16 v[52:55], v[164:167], v[190:193], v[52:55]
	v_mfma_f32_16x16x32_f16 v[48:51], v[182:185], v[190:193], v[48:51]
	v_mfma_f32_16x16x32_f16 v[36:39], v[164:167], v[198:201], v[36:39]
	v_mfma_f32_16x16x32_f16 v[32:35], v[182:185], v[198:201], v[32:35]
	v_mfma_f32_16x16x32_f16 v[20:23], v[164:167], v[210:213], v[20:23]
	v_mfma_f32_16x16x32_f16 v[16:19], v[182:185], v[210:213], v[16:19]
	v_mfma_f32_16x16x32_f16 v[4:7], v[164:167], v[218:221], v[4:7]
	v_mfma_f32_16x16x32_f16 v[0:3], v[182:185], v[218:221], v[0:3]
	s_barrier
	s_add_i32 s68, 0, 0x18000
	s_add_i32 s69, 0, 0x1c000
	v_add_u32_e32 v116, s68, v169
	v_add_u32_e32 v177, s69, v169
	ds_read_b128 v[104:107], v116
	ds_read_b128 v[108:111], v116 offset:1024
	ds_read_b128 v[112:115], v116 offset:2048
	ds_read_b128 v[116:119], v116 offset:3072
	ds_read_b128 v[160:163], v177
	ds_read_b128 v[164:167], v177 offset:1024
	ds_read_b128 v[178:181], v177 offset:2048
	ds_read_b128 v[182:185], v177 offset:3072
	s_add_u32 s34, s34, 0x40000
	s_addc_u32 s35, s35, 0
	s_mov_b32 m0, s46
	v_lshl_add_u64 v[228:229], s[34:35], 0, v[144:145]
	ds_read_b128 v[186:189], v173 offset:32768
	ds_read_b128 v[190:193], v173 offset:33792
	ds_read_b128 v[194:197], v173 offset:34816
	ds_read_b128 v[198:201], v173 offset:35840
	ds_read_b128 v[206:209], v173 offset:36864
	ds_read_b128 v[210:213], v173 offset:37888
	ds_read_b128 v[214:217], v173 offset:38912
	ds_read_b128 v[218:221], v173 offset:39936
	global_load_lds_dwordx4 v[228:229], off
	v_lshl_add_u64 v[228:229], s[34:35], 0, v[148:149]
	s_mov_b32 m0, s47
	s_nop 0
	global_load_lds_dwordx4 v[228:229], off
	s_waitcnt vmcnt(8)
	s_waitcnt lgkmcnt(0)
	s_barrier
	s_waitcnt lgkmcnt(0)
	v_mfma_f32_16x16x32_f16 v[140:143], v[104:107], v[186:189], v[140:143]
	v_mfma_f32_16x16x32_f16 v[136:139], v[112:115], v[186:189], v[136:139]
	v_mfma_f32_16x16x32_f16 v[124:127], v[104:107], v[194:197], v[124:127]
	v_mfma_f32_16x16x32_f16 v[120:123], v[112:115], v[194:197], v[120:123]
	v_mfma_f32_16x16x32_f16 v[92:95], v[104:107], v[206:209], v[92:95]
	v_mfma_f32_16x16x32_f16 v[88:91], v[112:115], v[206:209], v[88:91]
	v_mfma_f32_16x16x32_f16 v[76:79], v[104:107], v[214:217], v[76:79]
	v_mfma_f32_16x16x32_f16 v[72:75], v[112:115], v[214:217], v[72:75]
	v_mfma_f32_16x16x32_f16 v[140:143], v[108:111], v[190:193], v[140:143]
	v_mfma_f32_16x16x32_f16 v[136:139], v[116:119], v[190:193], v[136:139]
	v_mfma_f32_16x16x32_f16 v[124:127], v[108:111], v[198:201], v[124:127]
	v_mfma_f32_16x16x32_f16 v[120:123], v[116:119], v[198:201], v[120:123]
	v_mfma_f32_16x16x32_f16 v[92:95], v[108:111], v[210:213], v[92:95]
	v_mfma_f32_16x16x32_f16 v[88:91], v[116:119], v[210:213], v[88:91]
	v_mfma_f32_16x16x32_f16 v[76:79], v[108:111], v[218:221], v[76:79]
	v_mfma_f32_16x16x32_f16 v[72:75], v[116:119], v[218:221], v[72:75]
	v_mfma_f32_16x16x32_f16 v[132:135], v[160:163], v[186:189], v[132:135]
	v_mfma_f32_16x16x32_f16 v[128:131], v[178:181], v[186:189], v[128:131]
	v_mfma_f32_16x16x32_f16 v[100:103], v[160:163], v[194:197], v[100:103]
	v_mfma_f32_16x16x32_f16 v[96:99], v[178:181], v[194:197], v[96:99]
	v_mfma_f32_16x16x32_f16 v[84:87], v[160:163], v[206:209], v[84:87]
	v_mfma_f32_16x16x32_f16 v[80:83], v[178:181], v[206:209], v[80:83]
	v_mfma_f32_16x16x32_f16 v[68:71], v[160:163], v[214:217], v[68:71]
	v_mfma_f32_16x16x32_f16 v[64:67], v[178:181], v[214:217], v[64:67]
	v_mfma_f32_16x16x32_f16 v[132:135], v[164:167], v[190:193], v[132:135]
	v_mfma_f32_16x16x32_f16 v[128:131], v[182:185], v[190:193], v[128:131]
	v_mfma_f32_16x16x32_f16 v[100:103], v[164:167], v[198:201], v[100:103]
	v_mfma_f32_16x16x32_f16 v[96:99], v[182:185], v[198:201], v[96:99]
	v_mfma_f32_16x16x32_f16 v[84:87], v[164:167], v[210:213], v[84:87]
	v_mfma_f32_16x16x32_f16 v[80:83], v[182:185], v[210:213], v[80:83]
	v_mfma_f32_16x16x32_f16 v[68:71], v[164:167], v[218:221], v[68:71]
	v_mfma_f32_16x16x32_f16 v[64:67], v[182:185], v[218:221], v[64:67]
	s_barrier
	s_add_i32 s34, s68, s44
	v_lshl_add_u64 v[202:203], v[202:203], 0, s[10:11]
	s_mov_b32 m0, s34
	ds_read_b128 v[186:189], v173 offset:49152
	ds_read_b128 v[190:193], v173 offset:50176
	ds_read_b128 v[194:197], v173 offset:51200
	ds_read_b128 v[198:201], v173 offset:52224
	ds_read_b128 v[206:209], v173 offset:53248
	ds_read_b128 v[210:213], v173 offset:54272
	ds_read_b128 v[214:217], v173 offset:55296
	ds_read_b128 v[218:221], v173 offset:56320
	global_load_lds_dwordx4 v[202:203], off
	s_add_i32 m0, s34, 0x2000
	s_add_u32 s26, s26, 0x40080
	v_lshl_add_u64 v[202:203], v[222:223], 0, s[10:11]
	s_addc_u32 s27, s27, 0
	s_add_i32 s34, s69, s44
	global_load_lds_dwordx4 v[202:203], off
	v_lshl_add_u64 v[202:203], s[26:27], 0, v[146:147]
	s_mov_b32 m0, s34
	s_nop 0
	global_load_lds_dwordx4 v[202:203], off
	v_lshl_add_u64 v[202:203], s[26:27], 0, v[150:151]
	s_add_i32 m0, s34, 0x2000
	s_nop 0
	global_load_lds_dwordx4 v[202:203], off
	v_lshl_add_u64 v[202:203], v[224:225], 0, s[10:11]
	s_mov_b32 m0, s55
	s_nop 0
	global_load_lds_dwordx4 v[202:203], off
	v_lshl_add_u64 v[202:203], v[226:227], 0, s[10:11]
	s_mov_b32 m0, s56
	s_nop 0
	global_load_lds_dwordx4 v[202:203], off
	s_waitcnt vmcnt(8)
	s_waitcnt lgkmcnt(0)
	s_barrier
	s_waitcnt lgkmcnt(0)
	v_mfma_f32_16x16x32_f16 v[60:63], v[104:107], v[186:189], v[60:63]
	v_mfma_f32_16x16x32_f16 v[56:59], v[112:115], v[186:189], v[56:59]
	v_mfma_f32_16x16x32_f16 v[44:47], v[104:107], v[194:197], v[44:47]
	v_mfma_f32_16x16x32_f16 v[40:43], v[112:115], v[194:197], v[40:43]
	v_mfma_f32_16x16x32_f16 v[28:31], v[104:107], v[206:209], v[28:31]
	v_mfma_f32_16x16x32_f16 v[24:27], v[112:115], v[206:209], v[24:27]
	v_mfma_f32_16x16x32_f16 v[12:15], v[104:107], v[214:217], v[12:15]
	v_mfma_f32_16x16x32_f16 v[8:11], v[112:115], v[214:217], v[8:11]
	v_mfma_f32_16x16x32_f16 v[60:63], v[108:111], v[190:193], v[60:63]
	v_mfma_f32_16x16x32_f16 v[56:59], v[116:119], v[190:193], v[56:59]
	v_mfma_f32_16x16x32_f16 v[44:47], v[108:111], v[198:201], v[44:47]
	v_mfma_f32_16x16x32_f16 v[40:43], v[116:119], v[198:201], v[40:43]
	v_mfma_f32_16x16x32_f16 v[28:31], v[108:111], v[210:213], v[28:31]
	v_mfma_f32_16x16x32_f16 v[24:27], v[116:119], v[210:213], v[24:27]
	v_mfma_f32_16x16x32_f16 v[12:15], v[108:111], v[218:221], v[12:15]
	v_mfma_f32_16x16x32_f16 v[8:11], v[116:119], v[218:221], v[8:11]
	v_mfma_f32_16x16x32_f16 v[52:55], v[160:163], v[186:189], v[52:55]
	v_mfma_f32_16x16x32_f16 v[48:51], v[178:181], v[186:189], v[48:51]
	v_mfma_f32_16x16x32_f16 v[36:39], v[160:163], v[194:197], v[36:39]
	v_mfma_f32_16x16x32_f16 v[32:35], v[178:181], v[194:197], v[32:35]
	v_mfma_f32_16x16x32_f16 v[20:23], v[160:163], v[206:209], v[20:23]
	v_mfma_f32_16x16x32_f16 v[16:19], v[178:181], v[206:209], v[16:19]
	v_mfma_f32_16x16x32_f16 v[4:7], v[160:163], v[214:217], v[4:7]
	v_mfma_f32_16x16x32_f16 v[0:3], v[178:181], v[214:217], v[0:3]
	v_mfma_f32_16x16x32_f16 v[52:55], v[164:167], v[190:193], v[52:55]
	v_mfma_f32_16x16x32_f16 v[48:51], v[182:185], v[190:193], v[48:51]
	v_mfma_f32_16x16x32_f16 v[36:39], v[164:167], v[198:201], v[36:39]
	v_mfma_f32_16x16x32_f16 v[32:35], v[182:185], v[198:201], v[32:35]
	v_mfma_f32_16x16x32_f16 v[20:23], v[164:167], v[210:213], v[20:23]
	v_mfma_f32_16x16x32_f16 v[16:19], v[182:185], v[210:213], v[16:19]
	v_mfma_f32_16x16x32_f16 v[4:7], v[164:167], v[218:221], v[4:7]
	v_mfma_f32_16x16x32_f16 v[0:3], v[182:185], v[218:221], v[0:3]
	s_barrier
	s_add_i32 s67, s67, 2
	s_add_u32 s24, s24, 0x100
	s_addc_u32 s25, s25, 0
	s_add_u32 s65, s65, 0x100
	s_addc_u32 s66, s66, 0
	s_cmp_gt_u32 s67, 13

.LBB0_993:
	s_add_u32 s65, s24, 0x100
	s_addc_u32 s66, s25, 0
	s_mov_b32 s67, -2
	s_waitcnt lgkmcnt(0)
	ds_read_b128 v[80:83], v208
	ds_read_b128 v[84:87], v208 offset:1024
	ds_read_b128 v[92:95], v208 offset:2048
	ds_read_b128 v[96:99], v208 offset:3072
	ds_read_b128 v[144:147], v209
	ds_read_b128 v[148:151], v209 offset:1024
	ds_read_b128 v[152:155], v209 offset:2048
	ds_read_b128 v[156:159], v209 offset:3072
	s_add_u32 s24, s22, 0x100
	s_addc_u32 s25, s23, 0
	s_cmp_eq_u32 s67, 40
	s_cselect_b32 s35, s1, s25
	s_cselect_b32 s34, s0, s24
	s_cselect_b32 s27, s21, s66
	s_cselect_b32 s26, s20, s65
	v_lshl_add_u64 v[202:203], s[22:23], 0, v[168:169]
	s_add_i32 m0, s40, 0xc000
	ds_read_b128 v[178:181], v210
	ds_read_b128 v[182:185], v210 offset:1024
	ds_read_b128 v[186:189], v210 offset:2048
	ds_read_b128 v[190:193], v210 offset:3072
	ds_read_b128 v[194:197], v210 offset:4096
	ds_read_b128 v[198:201], v210 offset:5120
	ds_read_b128 v[212:215], v210 offset:6144
	ds_read_b128 v[216:219], v210 offset:7168
	global_load_lds_dwordx4 v[202:203], off
	v_lshl_add_u64 v[202:203], s[22:23], 0, v[170:171]
	s_add_i32 m0, s40, 0xe000
	s_nop 0
	global_load_lds_dwordx4 v[202:203], off
	s_waitcnt vmcnt(8)
	s_waitcnt lgkmcnt(0)
	s_barrier
	s_waitcnt lgkmcnt(0)
	v_mfma_f32_16x16x32_f16 v[140:143], v[80:83], v[178:181], 0
	v_mfma_f32_16x16x32_f16 v[136:139], v[92:95], v[178:181], 0
	v_mfma_f32_16x16x32_f16 v[124:127], v[80:83], v[186:189], 0
	v_mfma_f32_16x16x32_f16 v[120:123], v[92:95], v[186:189], 0
	v_mfma_f32_16x16x32_f16 v[108:111], v[80:83], v[194:197], 0
	v_mfma_f32_16x16x32_f16 v[104:107], v[92:95], v[194:197], 0
	v_mfma_f32_16x16x32_f16 v[76:79], v[80:83], v[212:215], 0
	v_mfma_f32_16x16x32_f16 v[72:75], v[92:95], v[212:215], 0
	v_mfma_f32_16x16x32_f16 v[140:143], v[84:87], v[182:185], v[140:143]
	v_mfma_f32_16x16x32_f16 v[136:139], v[96:99], v[182:185], v[136:139]
	v_mfma_f32_16x16x32_f16 v[124:127], v[84:87], v[190:193], v[124:127]
	v_mfma_f32_16x16x32_f16 v[120:123], v[96:99], v[190:193], v[120:123]
	v_mfma_f32_16x16x32_f16 v[108:111], v[84:87], v[198:201], v[108:111]
	v_mfma_f32_16x16x32_f16 v[104:107], v[96:99], v[198:201], v[104:107]
	v_mfma_f32_16x16x32_f16 v[76:79], v[84:87], v[216:219], v[76:79]
	v_mfma_f32_16x16x32_f16 v[72:75], v[96:99], v[216:219], v[72:75]
	v_mfma_f32_16x16x32_f16 v[132:135], v[144:147], v[178:181], 0
	v_mfma_f32_16x16x32_f16 v[128:131], v[152:155], v[178:181], 0
	v_mfma_f32_16x16x32_f16 v[116:119], v[144:147], v[186:189], 0
	v_mfma_f32_16x16x32_f16 v[112:115], v[152:155], v[186:189], 0
	v_mfma_f32_16x16x32_f16 v[100:103], v[144:147], v[194:197], 0
	v_mfma_f32_16x16x32_f16 v[88:91], v[152:155], v[194:197], 0
	v_mfma_f32_16x16x32_f16 v[68:71], v[144:147], v[212:215], 0
	v_mfma_f32_16x16x32_f16 v[64:67], v[152:155], v[212:215], 0
	v_mfma_f32_16x16x32_f16 v[132:135], v[148:151], v[182:185], v[132:135]
	v_mfma_f32_16x16x32_f16 v[128:131], v[156:159], v[182:185], v[128:131]
	v_mfma_f32_16x16x32_f16 v[116:119], v[148:151], v[190:193], v[116:119]
	v_mfma_f32_16x16x32_f16 v[112:115], v[156:159], v[190:193], v[112:115]
	v_mfma_f32_16x16x32_f16 v[100:103], v[148:151], v[198:201], v[100:103]
	v_mfma_f32_16x16x32_f16 v[88:91], v[156:159], v[198:201], v[88:91]
	v_mfma_f32_16x16x32_f16 v[68:71], v[148:151], v[216:219], v[68:71]
	v_mfma_f32_16x16x32_f16 v[64:67], v[156:159], v[216:219], v[64:67]
	s_barrier
	s_add_i32 s22, s59, s33
	v_lshl_add_u64 v[202:203], s[26:27], 0, v[162:163]
	s_mov_b32 m0, s22
	ds_read_b128 v[178:181], v210 offset:16384
	ds_read_b128 v[182:185], v210 offset:17408
	ds_read_b128 v[186:189], v210 offset:18432
	ds_read_b128 v[190:193], v210 offset:19456
	ds_read_b128 v[194:197], v210 offset:20480
	ds_read_b128 v[198:201], v210 offset:21504
	ds_read_b128 v[212:215], v210 offset:22528
	ds_read_b128 v[216:219], v210 offset:23552
	global_load_lds_dwordx4 v[202:203], off
	s_add_i32 m0, s22, 0x2000
	s_add_u32 s22, s26, 0xb0000
	v_lshl_add_u64 v[220:221], s[26:27], 0, v[166:167]
	s_addc_u32 s23, s27, 0
	s_add_i32 s68, s60, s33
	global_load_lds_dwordx4 v[220:221], off
	v_lshl_add_u64 v[222:223], s[22:23], 0, v[162:163]
	s_mov_b32 m0, s68
	v_lshl_add_u64 v[224:225], s[34:35], 0, v[164:165]
	global_load_lds_dwordx4 v[222:223], off
	v_lshl_add_u64 v[222:223], s[22:23], 0, v[166:167]
	s_add_i32 m0, s68, 0x2000
	s_nop 0
	global_load_lds_dwordx4 v[222:223], off
	v_lshl_add_u64 v[222:223], s[34:35], 0, v[160:161]
	s_mov_b32 m0, s40
	s_nop 0
	global_load_lds_dwordx4 v[222:223], off
	s_mov_b32 m0, s41
	s_nop 0
	global_load_lds_dwordx4 v[224:225], off
	s_waitcnt vmcnt(8)
	s_waitcnt lgkmcnt(0)
	s_barrier
	s_waitcnt lgkmcnt(0)
	v_mfma_f32_16x16x32_f16 v[60:63], v[80:83], v[178:181], 0
	v_mfma_f32_16x16x32_f16 v[56:59], v[92:95], v[178:181], 0
	v_mfma_f32_16x16x32_f16 v[44:47], v[80:83], v[186:189], 0
	v_mfma_f32_16x16x32_f16 v[40:43], v[92:95], v[186:189], 0
	v_mfma_f32_16x16x32_f16 v[28:31], v[80:83], v[194:197], 0
	v_mfma_f32_16x16x32_f16 v[24:27], v[92:95], v[194:197], 0
	v_mfma_f32_16x16x32_f16 v[12:15], v[80:83], v[212:215], 0
	v_mfma_f32_16x16x32_f16 v[8:11], v[92:95], v[212:215], 0
	v_mfma_f32_16x16x32_f16 v[60:63], v[84:87], v[182:185], v[60:63]
	v_mfma_f32_16x16x32_f16 v[56:59], v[96:99], v[182:185], v[56:59]
	v_mfma_f32_16x16x32_f16 v[44:47], v[84:87], v[190:193], v[44:47]
	v_mfma_f32_16x16x32_f16 v[40:43], v[96:99], v[190:193], v[40:43]
	v_mfma_f32_16x16x32_f16 v[28:31], v[84:87], v[198:201], v[28:31]
	v_mfma_f32_16x16x32_f16 v[24:27], v[96:99], v[198:201], v[24:27]
	v_mfma_f32_16x16x32_f16 v[12:15], v[84:87], v[216:219], v[12:15]
	v_mfma_f32_16x16x32_f16 v[8:11], v[96:99], v[216:219], v[8:11]
	v_mfma_f32_16x16x32_f16 v[52:55], v[144:147], v[178:181], 0
	v_mfma_f32_16x16x32_f16 v[48:51], v[152:155], v[178:181], 0
	v_mfma_f32_16x16x32_f16 v[36:39], v[144:147], v[186:189], 0
	v_mfma_f32_16x16x32_f16 v[32:35], v[152:155], v[186:189], 0
	v_mfma_f32_16x16x32_f16 v[20:23], v[144:147], v[194:197], 0
	v_mfma_f32_16x16x32_f16 v[16:19], v[152:155], v[194:197], 0
	v_mfma_f32_16x16x32_f16 v[4:7], v[144:147], v[212:215], 0
	v_mfma_f32_16x16x32_f16 v[0:3], v[152:155], v[212:215], 0
	v_mfma_f32_16x16x32_f16 v[52:55], v[148:151], v[182:185], v[52:55]
	v_mfma_f32_16x16x32_f16 v[48:51], v[156:159], v[182:185], v[48:51]
	v_mfma_f32_16x16x32_f16 v[36:39], v[148:151], v[190:193], v[36:39]
	v_mfma_f32_16x16x32_f16 v[32:35], v[156:159], v[190:193], v[32:35]
	v_mfma_f32_16x16x32_f16 v[20:23], v[148:151], v[198:201], v[20:23]
	v_mfma_f32_16x16x32_f16 v[16:19], v[156:159], v[198:201], v[16:19]
	v_mfma_f32_16x16x32_f16 v[4:7], v[148:151], v[216:219], v[4:7]
	v_mfma_f32_16x16x32_f16 v[0:3], v[156:159], v[216:219], v[0:3]
	s_barrier
	s_add_i32 s68, 0, 0x18000
	s_add_i32 s69, 0, 0x1c000
	v_add_u32_e32 v96, s68, v206
	v_add_u32_e32 v156, s69, v206
	ds_read_b128 v[80:83], v96
	ds_read_b128 v[84:87], v96 offset:1024
	ds_read_b128 v[92:95], v96 offset:2048
	ds_read_b128 v[96:99], v96 offset:3072
	ds_read_b128 v[144:147], v156
	ds_read_b128 v[148:151], v156 offset:1024
	ds_read_b128 v[152:155], v156 offset:2048
	ds_read_b128 v[156:159], v156 offset:3072
	s_add_u32 s22, s34, 0xb0000
	s_addc_u32 s23, s35, 0
	s_mov_b32 m0, s44
	v_lshl_add_u64 v[226:227], s[22:23], 0, v[160:161]
	ds_read_b128 v[178:181], v210 offset:32768
	ds_read_b128 v[182:185], v210 offset:33792
	ds_read_b128 v[186:189], v210 offset:34816
	ds_read_b128 v[190:193], v210 offset:35840
	ds_read_b128 v[194:197], v210 offset:36864
	ds_read_b128 v[198:201], v210 offset:37888
	ds_read_b128 v[212:215], v210 offset:38912
	ds_read_b128 v[216:219], v210 offset:39936
	global_load_lds_dwordx4 v[226:227], off
	v_lshl_add_u64 v[226:227], s[22:23], 0, v[164:165]
	s_mov_b32 m0, s45
	s_nop 0
	global_load_lds_dwordx4 v[226:227], off
	s_waitcnt vmcnt(8)
	s_waitcnt lgkmcnt(0)
	s_barrier
	s_waitcnt lgkmcnt(0)
	v_mfma_f32_16x16x32_f16 v[140:143], v[80:83], v[178:181], v[140:143]
	v_mfma_f32_16x16x32_f16 v[136:139], v[92:95], v[178:181], v[136:139]
	v_mfma_f32_16x16x32_f16 v[124:127], v[80:83], v[186:189], v[124:127]
	v_mfma_f32_16x16x32_f16 v[120:123], v[92:95], v[186:189], v[120:123]
	v_mfma_f32_16x16x32_f16 v[108:111], v[80:83], v[194:197], v[108:111]
	v_mfma_f32_16x16x32_f16 v[104:107], v[92:95], v[194:197], v[104:107]
	v_mfma_f32_16x16x32_f16 v[76:79], v[80:83], v[212:215], v[76:79]
	v_mfma_f32_16x16x32_f16 v[72:75], v[92:95], v[212:215], v[72:75]
	v_mfma_f32_16x16x32_f16 v[140:143], v[84:87], v[182:185], v[140:143]
	v_mfma_f32_16x16x32_f16 v[136:139], v[96:99], v[182:185], v[136:139]
	v_mfma_f32_16x16x32_f16 v[124:127], v[84:87], v[190:193], v[124:127]
	v_mfma_f32_16x16x32_f16 v[120:123], v[96:99], v[190:193], v[120:123]
	v_mfma_f32_16x16x32_f16 v[108:111], v[84:87], v[198:201], v[108:111]
	v_mfma_f32_16x16x32_f16 v[104:107], v[96:99], v[198:201], v[104:107]
	v_mfma_f32_16x16x32_f16 v[76:79], v[84:87], v[216:219], v[76:79]
	v_mfma_f32_16x16x32_f16 v[72:75], v[96:99], v[216:219], v[72:75]
	v_mfma_f32_16x16x32_f16 v[132:135], v[144:147], v[178:181], v[132:135]
	v_mfma_f32_16x16x32_f16 v[128:131], v[152:155], v[178:181], v[128:131]
	v_mfma_f32_16x16x32_f16 v[116:119], v[144:147], v[186:189], v[116:119]
	v_mfma_f32_16x16x32_f16 v[112:115], v[152:155], v[186:189], v[112:115]
	v_mfma_f32_16x16x32_f16 v[100:103], v[144:147], v[194:197], v[100:103]
	v_mfma_f32_16x16x32_f16 v[88:91], v[152:155], v[194:197], v[88:91]
	v_mfma_f32_16x16x32_f16 v[68:71], v[144:147], v[212:215], v[68:71]
	v_mfma_f32_16x16x32_f16 v[64:67], v[152:155], v[212:215], v[64:67]
	v_mfma_f32_16x16x32_f16 v[132:135], v[148:151], v[182:185], v[132:135]
	v_mfma_f32_16x16x32_f16 v[128:131], v[156:159], v[182:185], v[128:131]
	v_mfma_f32_16x16x32_f16 v[116:119], v[148:151], v[190:193], v[116:119]
	v_mfma_f32_16x16x32_f16 v[112:115], v[156:159], v[190:193], v[112:115]
	v_mfma_f32_16x16x32_f16 v[100:103], v[148:151], v[198:201], v[100:103]
	v_mfma_f32_16x16x32_f16 v[88:91], v[156:159], v[198:201], v[88:91]
	v_mfma_f32_16x16x32_f16 v[68:71], v[148:151], v[216:219], v[68:71]
	v_mfma_f32_16x16x32_f16 v[64:67], v[156:159], v[216:219], v[64:67]
	s_barrier
	s_add_i32 s22, s68, s33
	v_lshl_add_u64 v[202:203], v[202:203], 0, s[16:17]
	s_mov_b32 m0, s22
	ds_read_b128 v[178:181], v210 offset:49152
	ds_read_b128 v[182:185], v210 offset:50176
	ds_read_b128 v[186:189], v210 offset:51200
	ds_read_b128 v[190:193], v210 offset:52224
	ds_read_b128 v[194:197], v210 offset:53248
	ds_read_b128 v[198:201], v210 offset:54272
	ds_read_b128 v[212:215], v210 offset:55296
	ds_read_b128 v[216:219], v210 offset:56320
	global_load_lds_dwordx4 v[202:203], off
	s_add_i32 m0, s22, 0x2000
	s_add_u32 s22, s26, 0xb0080
	v_lshl_add_u64 v[202:203], v[220:221], 0, s[16:17]
	s_addc_u32 s23, s27, 0
	s_add_i32 s26, s69, s33
	global_load_lds_dwordx4 v[202:203], off
	v_lshl_add_u64 v[202:203], s[22:23], 0, v[162:163]
	s_mov_b32 m0, s26
	s_nop 0
	global_load_lds_dwordx4 v[202:203], off
	v_lshl_add_u64 v[202:203], s[22:23], 0, v[166:167]
	s_add_i32 m0, s26, 0x2000
	s_nop 0
	global_load_lds_dwordx4 v[202:203], off
	v_lshl_add_u64 v[202:203], v[222:223], 0, s[16:17]
	s_mov_b32 m0, s55
	s_nop 0
	global_load_lds_dwordx4 v[202:203], off
	v_lshl_add_u64 v[202:203], v[224:225], 0, s[16:17]
	s_mov_b32 m0, s56
	s_nop 0
	global_load_lds_dwordx4 v[202:203], off
	s_waitcnt vmcnt(8)
	s_waitcnt lgkmcnt(0)
	s_barrier
	s_waitcnt lgkmcnt(0)
	v_mfma_f32_16x16x32_f16 v[60:63], v[80:83], v[178:181], v[60:63]
	v_mfma_f32_16x16x32_f16 v[56:59], v[92:95], v[178:181], v[56:59]
	v_mfma_f32_16x16x32_f16 v[44:47], v[80:83], v[186:189], v[44:47]
	v_mfma_f32_16x16x32_f16 v[40:43], v[92:95], v[186:189], v[40:43]
	v_mfma_f32_16x16x32_f16 v[28:31], v[80:83], v[194:197], v[28:31]
	v_mfma_f32_16x16x32_f16 v[24:27], v[92:95], v[194:197], v[24:27]
	v_mfma_f32_16x16x32_f16 v[12:15], v[80:83], v[212:215], v[12:15]
	v_mfma_f32_16x16x32_f16 v[8:11], v[92:95], v[212:215], v[8:11]
	v_mfma_f32_16x16x32_f16 v[60:63], v[84:87], v[182:185], v[60:63]
	v_mfma_f32_16x16x32_f16 v[56:59], v[96:99], v[182:185], v[56:59]
	v_mfma_f32_16x16x32_f16 v[44:47], v[84:87], v[190:193], v[44:47]
	v_mfma_f32_16x16x32_f16 v[40:43], v[96:99], v[190:193], v[40:43]
	v_mfma_f32_16x16x32_f16 v[28:31], v[84:87], v[198:201], v[28:31]
	v_mfma_f32_16x16x32_f16 v[24:27], v[96:99], v[198:201], v[24:27]
	v_mfma_f32_16x16x32_f16 v[12:15], v[84:87], v[216:219], v[12:15]
	v_mfma_f32_16x16x32_f16 v[8:11], v[96:99], v[216:219], v[8:11]
	v_mfma_f32_16x16x32_f16 v[52:55], v[144:147], v[178:181], v[52:55]
	v_mfma_f32_16x16x32_f16 v[48:51], v[152:155], v[178:181], v[48:51]
	v_mfma_f32_16x16x32_f16 v[36:39], v[144:147], v[186:189], v[36:39]
	v_mfma_f32_16x16x32_f16 v[32:35], v[152:155], v[186:189], v[32:35]
	v_mfma_f32_16x16x32_f16 v[20:23], v[144:147], v[194:197], v[20:23]
	v_mfma_f32_16x16x32_f16 v[16:19], v[152:155], v[194:197], v[16:19]
	v_mfma_f32_16x16x32_f16 v[4:7], v[144:147], v[212:215], v[4:7]
	v_mfma_f32_16x16x32_f16 v[0:3], v[152:155], v[212:215], v[0:3]
	v_mfma_f32_16x16x32_f16 v[52:55], v[148:151], v[182:185], v[52:55]
	v_mfma_f32_16x16x32_f16 v[48:51], v[156:159], v[182:185], v[48:51]
	v_mfma_f32_16x16x32_f16 v[36:39], v[148:151], v[190:193], v[36:39]
	v_mfma_f32_16x16x32_f16 v[32:35], v[156:159], v[190:193], v[32:35]
	v_mfma_f32_16x16x32_f16 v[20:23], v[148:151], v[198:201], v[20:23]
	v_mfma_f32_16x16x32_f16 v[16:19], v[156:159], v[198:201], v[16:19]
	v_mfma_f32_16x16x32_f16 v[4:7], v[148:151], v[216:219], v[4:7]
	v_mfma_f32_16x16x32_f16 v[0:3], v[156:159], v[216:219], v[0:3]
	s_barrier
	s_add_i32 s67, s67, 2
	s_add_u32 s65, s65, 0x100
	s_addc_u32 s66, s66, 0
	s_cmp_gt_u32 s67, 41
	s_mov_b64 s[22:23], s[24:25]

.LBB0_1219:
	s_add_u32 s61, s24, 0x100
	s_addc_u32 s62, s25, 0
	s_mov_b32 s63, -2
	s_waitcnt lgkmcnt(0)
	ds_read_b128 v[80:83], v208
	ds_read_b128 v[84:87], v208 offset:1024
	ds_read_b128 v[92:95], v208 offset:2048
	ds_read_b128 v[96:99], v208 offset:3072
	ds_read_b128 v[144:147], v209
	ds_read_b128 v[148:151], v209 offset:1024
	ds_read_b128 v[152:155], v209 offset:2048
	ds_read_b128 v[156:159], v209 offset:3072
	s_add_u32 s24, s22, 0x100
	s_addc_u32 s25, s23, 0
	s_cmp_eq_u32 s63, 40
	s_cselect_b32 s35, s1, s25
	s_cselect_b32 s34, s0, s24
	s_cselect_b32 s27, s21, s62
	s_cselect_b32 s26, s20, s61
	v_lshl_add_u64 v[202:203], s[22:23], 0, v[168:169]
	s_add_i32 m0, s40, 0xc000
	ds_read_b128 v[178:181], v210
	ds_read_b128 v[182:185], v210 offset:1024
	ds_read_b128 v[186:189], v210 offset:2048
	ds_read_b128 v[190:193], v210 offset:3072
	ds_read_b128 v[194:197], v210 offset:4096
	ds_read_b128 v[198:201], v210 offset:5120
	ds_read_b128 v[212:215], v210 offset:6144
	ds_read_b128 v[216:219], v210 offset:7168
	global_load_lds_dwordx4 v[202:203], off
	v_lshl_add_u64 v[202:203], s[22:23], 0, v[170:171]
	s_add_i32 m0, s40, 0xe000
	s_nop 0
	global_load_lds_dwordx4 v[202:203], off
	s_waitcnt vmcnt(8)
	s_waitcnt lgkmcnt(0)
	s_barrier
	s_waitcnt lgkmcnt(0)
	v_mfma_f32_16x16x32_f16 v[140:143], v[80:83], v[178:181], 0
	v_mfma_f32_16x16x32_f16 v[136:139], v[92:95], v[178:181], 0
	v_mfma_f32_16x16x32_f16 v[124:127], v[80:83], v[186:189], 0
	v_mfma_f32_16x16x32_f16 v[120:123], v[92:95], v[186:189], 0
	v_mfma_f32_16x16x32_f16 v[108:111], v[80:83], v[194:197], 0
	v_mfma_f32_16x16x32_f16 v[104:107], v[92:95], v[194:197], 0
	v_mfma_f32_16x16x32_f16 v[76:79], v[80:83], v[212:215], 0
	v_mfma_f32_16x16x32_f16 v[72:75], v[92:95], v[212:215], 0
	v_mfma_f32_16x16x32_f16 v[140:143], v[84:87], v[182:185], v[140:143]
	v_mfma_f32_16x16x32_f16 v[136:139], v[96:99], v[182:185], v[136:139]
	v_mfma_f32_16x16x32_f16 v[124:127], v[84:87], v[190:193], v[124:127]
	v_mfma_f32_16x16x32_f16 v[120:123], v[96:99], v[190:193], v[120:123]
	v_mfma_f32_16x16x32_f16 v[108:111], v[84:87], v[198:201], v[108:111]
	v_mfma_f32_16x16x32_f16 v[104:107], v[96:99], v[198:201], v[104:107]
	v_mfma_f32_16x16x32_f16 v[76:79], v[84:87], v[216:219], v[76:79]
	v_mfma_f32_16x16x32_f16 v[72:75], v[96:99], v[216:219], v[72:75]
	v_mfma_f32_16x16x32_f16 v[132:135], v[144:147], v[178:181], 0
	v_mfma_f32_16x16x32_f16 v[128:131], v[152:155], v[178:181], 0
	v_mfma_f32_16x16x32_f16 v[116:119], v[144:147], v[186:189], 0
	v_mfma_f32_16x16x32_f16 v[112:115], v[152:155], v[186:189], 0
	v_mfma_f32_16x16x32_f16 v[100:103], v[144:147], v[194:197], 0
	v_mfma_f32_16x16x32_f16 v[88:91], v[152:155], v[194:197], 0
	v_mfma_f32_16x16x32_f16 v[68:71], v[144:147], v[212:215], 0
	v_mfma_f32_16x16x32_f16 v[64:67], v[152:155], v[212:215], 0
	v_mfma_f32_16x16x32_f16 v[132:135], v[148:151], v[182:185], v[132:135]
	v_mfma_f32_16x16x32_f16 v[128:131], v[156:159], v[182:185], v[128:131]
	v_mfma_f32_16x16x32_f16 v[116:119], v[148:151], v[190:193], v[116:119]
	v_mfma_f32_16x16x32_f16 v[112:115], v[156:159], v[190:193], v[112:115]
	v_mfma_f32_16x16x32_f16 v[100:103], v[148:151], v[198:201], v[100:103]
	v_mfma_f32_16x16x32_f16 v[88:91], v[156:159], v[198:201], v[88:91]
	v_mfma_f32_16x16x32_f16 v[68:71], v[148:151], v[216:219], v[68:71]
	v_mfma_f32_16x16x32_f16 v[64:67], v[156:159], v[216:219], v[64:67]
	s_barrier
	s_add_i32 s22, s55, s33
	v_lshl_add_u64 v[202:203], s[26:27], 0, v[162:163]
	s_mov_b32 m0, s22
	ds_read_b128 v[178:181], v210 offset:16384
	ds_read_b128 v[182:185], v210 offset:17408
	ds_read_b128 v[186:189], v210 offset:18432
	ds_read_b128 v[190:193], v210 offset:19456
	ds_read_b128 v[194:197], v210 offset:20480
	ds_read_b128 v[198:201], v210 offset:21504
	ds_read_b128 v[212:215], v210 offset:22528
	ds_read_b128 v[216:219], v210 offset:23552
	global_load_lds_dwordx4 v[202:203], off
	s_add_i32 m0, s22, 0x2000
	s_add_u32 s22, s26, 0xb0000
	v_lshl_add_u64 v[220:221], s[26:27], 0, v[166:167]
	s_addc_u32 s23, s27, 0
	s_add_i32 s64, s56, s33
	global_load_lds_dwordx4 v[220:221], off
	v_lshl_add_u64 v[222:223], s[22:23], 0, v[162:163]
	s_mov_b32 m0, s64
	v_lshl_add_u64 v[224:225], s[34:35], 0, v[164:165]
	global_load_lds_dwordx4 v[222:223], off
	v_lshl_add_u64 v[222:223], s[22:23], 0, v[166:167]
	s_add_i32 m0, s64, 0x2000
	s_nop 0
	global_load_lds_dwordx4 v[222:223], off
	v_lshl_add_u64 v[222:223], s[34:35], 0, v[160:161]
	s_mov_b32 m0, s40
	s_nop 0
	global_load_lds_dwordx4 v[222:223], off
	s_mov_b32 m0, s41
	s_nop 0
	global_load_lds_dwordx4 v[224:225], off
	s_waitcnt vmcnt(8)
	s_waitcnt lgkmcnt(0)
	s_barrier
	s_waitcnt lgkmcnt(0)
	v_mfma_f32_16x16x32_f16 v[60:63], v[80:83], v[178:181], 0
	v_mfma_f32_16x16x32_f16 v[56:59], v[92:95], v[178:181], 0
	v_mfma_f32_16x16x32_f16 v[44:47], v[80:83], v[186:189], 0
	v_mfma_f32_16x16x32_f16 v[40:43], v[92:95], v[186:189], 0
	v_mfma_f32_16x16x32_f16 v[28:31], v[80:83], v[194:197], 0
	v_mfma_f32_16x16x32_f16 v[24:27], v[92:95], v[194:197], 0
	v_mfma_f32_16x16x32_f16 v[12:15], v[80:83], v[212:215], 0
	v_mfma_f32_16x16x32_f16 v[8:11], v[92:95], v[212:215], 0
	v_mfma_f32_16x16x32_f16 v[60:63], v[84:87], v[182:185], v[60:63]
	v_mfma_f32_16x16x32_f16 v[56:59], v[96:99], v[182:185], v[56:59]
	v_mfma_f32_16x16x32_f16 v[44:47], v[84:87], v[190:193], v[44:47]
	v_mfma_f32_16x16x32_f16 v[40:43], v[96:99], v[190:193], v[40:43]
	v_mfma_f32_16x16x32_f16 v[28:31], v[84:87], v[198:201], v[28:31]
	v_mfma_f32_16x16x32_f16 v[24:27], v[96:99], v[198:201], v[24:27]
	v_mfma_f32_16x16x32_f16 v[12:15], v[84:87], v[216:219], v[12:15]
	v_mfma_f32_16x16x32_f16 v[8:11], v[96:99], v[216:219], v[8:11]
	v_mfma_f32_16x16x32_f16 v[52:55], v[144:147], v[178:181], 0
	v_mfma_f32_16x16x32_f16 v[48:51], v[152:155], v[178:181], 0
	v_mfma_f32_16x16x32_f16 v[36:39], v[144:147], v[186:189], 0
	v_mfma_f32_16x16x32_f16 v[32:35], v[152:155], v[186:189], 0
	v_mfma_f32_16x16x32_f16 v[20:23], v[144:147], v[194:197], 0
	v_mfma_f32_16x16x32_f16 v[16:19], v[152:155], v[194:197], 0
	v_mfma_f32_16x16x32_f16 v[4:7], v[144:147], v[212:215], 0
	v_mfma_f32_16x16x32_f16 v[0:3], v[152:155], v[212:215], 0
	v_mfma_f32_16x16x32_f16 v[52:55], v[148:151], v[182:185], v[52:55]
	v_mfma_f32_16x16x32_f16 v[48:51], v[156:159], v[182:185], v[48:51]
	v_mfma_f32_16x16x32_f16 v[36:39], v[148:151], v[190:193], v[36:39]
	v_mfma_f32_16x16x32_f16 v[32:35], v[156:159], v[190:193], v[32:35]
	v_mfma_f32_16x16x32_f16 v[20:23], v[148:151], v[198:201], v[20:23]
	v_mfma_f32_16x16x32_f16 v[16:19], v[156:159], v[198:201], v[16:19]
	v_mfma_f32_16x16x32_f16 v[4:7], v[148:151], v[216:219], v[4:7]
	v_mfma_f32_16x16x32_f16 v[0:3], v[156:159], v[216:219], v[0:3]
	s_barrier
	s_add_i32 s64, 0, 0x18000
	s_add_i32 s65, 0, 0x1c000
	v_add_u32_e32 v96, s64, v206
	v_add_u32_e32 v156, s65, v206
	ds_read_b128 v[80:83], v96
	ds_read_b128 v[84:87], v96 offset:1024
	ds_read_b128 v[92:95], v96 offset:2048
	ds_read_b128 v[96:99], v96 offset:3072
	ds_read_b128 v[144:147], v156
	ds_read_b128 v[148:151], v156 offset:1024
	ds_read_b128 v[152:155], v156 offset:2048
	ds_read_b128 v[156:159], v156 offset:3072
	s_add_u32 s22, s34, 0xb0000
	s_addc_u32 s23, s35, 0
	s_mov_b32 m0, s44
	v_lshl_add_u64 v[226:227], s[22:23], 0, v[160:161]
	ds_read_b128 v[178:181], v210 offset:32768
	ds_read_b128 v[182:185], v210 offset:33792
	ds_read_b128 v[186:189], v210 offset:34816
	ds_read_b128 v[190:193], v210 offset:35840
	ds_read_b128 v[194:197], v210 offset:36864
	ds_read_b128 v[198:201], v210 offset:37888
	ds_read_b128 v[212:215], v210 offset:38912
	ds_read_b128 v[216:219], v210 offset:39936
	global_load_lds_dwordx4 v[226:227], off
	v_lshl_add_u64 v[226:227], s[22:23], 0, v[164:165]
	s_mov_b32 m0, s45
	s_nop 0
	global_load_lds_dwordx4 v[226:227], off
	s_waitcnt vmcnt(8)
	s_waitcnt lgkmcnt(0)
	s_barrier
	s_waitcnt lgkmcnt(0)
	v_mfma_f32_16x16x32_f16 v[140:143], v[80:83], v[178:181], v[140:143]
	v_mfma_f32_16x16x32_f16 v[136:139], v[92:95], v[178:181], v[136:139]
	v_mfma_f32_16x16x32_f16 v[124:127], v[80:83], v[186:189], v[124:127]
	v_mfma_f32_16x16x32_f16 v[120:123], v[92:95], v[186:189], v[120:123]
	v_mfma_f32_16x16x32_f16 v[108:111], v[80:83], v[194:197], v[108:111]
	v_mfma_f32_16x16x32_f16 v[104:107], v[92:95], v[194:197], v[104:107]
	v_mfma_f32_16x16x32_f16 v[76:79], v[80:83], v[212:215], v[76:79]
	v_mfma_f32_16x16x32_f16 v[72:75], v[92:95], v[212:215], v[72:75]
	v_mfma_f32_16x16x32_f16 v[140:143], v[84:87], v[182:185], v[140:143]
	v_mfma_f32_16x16x32_f16 v[136:139], v[96:99], v[182:185], v[136:139]
	v_mfma_f32_16x16x32_f16 v[124:127], v[84:87], v[190:193], v[124:127]
	v_mfma_f32_16x16x32_f16 v[120:123], v[96:99], v[190:193], v[120:123]
	v_mfma_f32_16x16x32_f16 v[108:111], v[84:87], v[198:201], v[108:111]
	v_mfma_f32_16x16x32_f16 v[104:107], v[96:99], v[198:201], v[104:107]
	v_mfma_f32_16x16x32_f16 v[76:79], v[84:87], v[216:219], v[76:79]
	v_mfma_f32_16x16x32_f16 v[72:75], v[96:99], v[216:219], v[72:75]
	v_mfma_f32_16x16x32_f16 v[132:135], v[144:147], v[178:181], v[132:135]
	v_mfma_f32_16x16x32_f16 v[128:131], v[152:155], v[178:181], v[128:131]
	v_mfma_f32_16x16x32_f16 v[116:119], v[144:147], v[186:189], v[116:119]
	v_mfma_f32_16x16x32_f16 v[112:115], v[152:155], v[186:189], v[112:115]
	v_mfma_f32_16x16x32_f16 v[100:103], v[144:147], v[194:197], v[100:103]
	v_mfma_f32_16x16x32_f16 v[88:91], v[152:155], v[194:197], v[88:91]
	v_mfma_f32_16x16x32_f16 v[68:71], v[144:147], v[212:215], v[68:71]
	v_mfma_f32_16x16x32_f16 v[64:67], v[152:155], v[212:215], v[64:67]
	v_mfma_f32_16x16x32_f16 v[132:135], v[148:151], v[182:185], v[132:135]
	v_mfma_f32_16x16x32_f16 v[128:131], v[156:159], v[182:185], v[128:131]
	v_mfma_f32_16x16x32_f16 v[116:119], v[148:151], v[190:193], v[116:119]
	v_mfma_f32_16x16x32_f16 v[112:115], v[156:159], v[190:193], v[112:115]
	v_mfma_f32_16x16x32_f16 v[100:103], v[148:151], v[198:201], v[100:103]
	v_mfma_f32_16x16x32_f16 v[88:91], v[156:159], v[198:201], v[88:91]
	v_mfma_f32_16x16x32_f16 v[68:71], v[148:151], v[216:219], v[68:71]
	v_mfma_f32_16x16x32_f16 v[64:67], v[156:159], v[216:219], v[64:67]
	s_barrier
	s_add_i32 s22, s64, s33
	v_lshl_add_u64 v[202:203], v[202:203], 0, s[16:17]
	s_mov_b32 m0, s22
	ds_read_b128 v[178:181], v210 offset:49152
	ds_read_b128 v[182:185], v210 offset:50176
	ds_read_b128 v[186:189], v210 offset:51200
	ds_read_b128 v[190:193], v210 offset:52224
	ds_read_b128 v[194:197], v210 offset:53248
	ds_read_b128 v[198:201], v210 offset:54272
	ds_read_b128 v[212:215], v210 offset:55296
	ds_read_b128 v[216:219], v210 offset:56320
	global_load_lds_dwordx4 v[202:203], off
	s_add_i32 m0, s22, 0x2000
	s_add_u32 s22, s26, 0xb0080
	v_lshl_add_u64 v[202:203], v[220:221], 0, s[16:17]
	s_addc_u32 s23, s27, 0
	s_add_i32 s26, s65, s33
	global_load_lds_dwordx4 v[202:203], off
	v_lshl_add_u64 v[202:203], s[22:23], 0, v[162:163]
	s_mov_b32 m0, s26
	s_nop 0
	global_load_lds_dwordx4 v[202:203], off
	v_lshl_add_u64 v[202:203], s[22:23], 0, v[166:167]
	s_add_i32 m0, s26, 0x2000
	s_nop 0
	global_load_lds_dwordx4 v[202:203], off
	v_lshl_add_u64 v[202:203], v[222:223], 0, s[16:17]
	s_mov_b32 m0, s51
	s_nop 0
	global_load_lds_dwordx4 v[202:203], off
	v_lshl_add_u64 v[202:203], v[224:225], 0, s[16:17]
	s_mov_b32 m0, s52
	s_nop 0
	global_load_lds_dwordx4 v[202:203], off
	s_waitcnt vmcnt(8)
	s_waitcnt lgkmcnt(0)
	s_barrier
	s_waitcnt lgkmcnt(0)
	v_mfma_f32_16x16x32_f16 v[60:63], v[80:83], v[178:181], v[60:63]
	v_mfma_f32_16x16x32_f16 v[56:59], v[92:95], v[178:181], v[56:59]
	v_mfma_f32_16x16x32_f16 v[44:47], v[80:83], v[186:189], v[44:47]
	v_mfma_f32_16x16x32_f16 v[40:43], v[92:95], v[186:189], v[40:43]
	v_mfma_f32_16x16x32_f16 v[28:31], v[80:83], v[194:197], v[28:31]
	v_mfma_f32_16x16x32_f16 v[24:27], v[92:95], v[194:197], v[24:27]
	v_mfma_f32_16x16x32_f16 v[12:15], v[80:83], v[212:215], v[12:15]
	v_mfma_f32_16x16x32_f16 v[8:11], v[92:95], v[212:215], v[8:11]
	v_mfma_f32_16x16x32_f16 v[60:63], v[84:87], v[182:185], v[60:63]
	v_mfma_f32_16x16x32_f16 v[56:59], v[96:99], v[182:185], v[56:59]
	v_mfma_f32_16x16x32_f16 v[44:47], v[84:87], v[190:193], v[44:47]
	v_mfma_f32_16x16x32_f16 v[40:43], v[96:99], v[190:193], v[40:43]
	v_mfma_f32_16x16x32_f16 v[28:31], v[84:87], v[198:201], v[28:31]
	v_mfma_f32_16x16x32_f16 v[24:27], v[96:99], v[198:201], v[24:27]
	v_mfma_f32_16x16x32_f16 v[12:15], v[84:87], v[216:219], v[12:15]
	v_mfma_f32_16x16x32_f16 v[8:11], v[96:99], v[216:219], v[8:11]
	v_mfma_f32_16x16x32_f16 v[52:55], v[144:147], v[178:181], v[52:55]
	v_mfma_f32_16x16x32_f16 v[48:51], v[152:155], v[178:181], v[48:51]
	v_mfma_f32_16x16x32_f16 v[36:39], v[144:147], v[186:189], v[36:39]
	v_mfma_f32_16x16x32_f16 v[32:35], v[152:155], v[186:189], v[32:35]
	v_mfma_f32_16x16x32_f16 v[20:23], v[144:147], v[194:197], v[20:23]
	v_mfma_f32_16x16x32_f16 v[16:19], v[152:155], v[194:197], v[16:19]
	v_mfma_f32_16x16x32_f16 v[4:7], v[144:147], v[212:215], v[4:7]
	v_mfma_f32_16x16x32_f16 v[0:3], v[152:155], v[212:215], v[0:3]
	v_mfma_f32_16x16x32_f16 v[52:55], v[148:151], v[182:185], v[52:55]
	v_mfma_f32_16x16x32_f16 v[48:51], v[156:159], v[182:185], v[48:51]
	v_mfma_f32_16x16x32_f16 v[36:39], v[148:151], v[190:193], v[36:39]
	v_mfma_f32_16x16x32_f16 v[32:35], v[156:159], v[190:193], v[32:35]
	v_mfma_f32_16x16x32_f16 v[20:23], v[148:151], v[198:201], v[20:23]
	v_mfma_f32_16x16x32_f16 v[16:19], v[156:159], v[198:201], v[16:19]
	v_mfma_f32_16x16x32_f16 v[4:7], v[148:151], v[216:219], v[4:7]
	v_mfma_f32_16x16x32_f16 v[0:3], v[156:159], v[216:219], v[0:3]
	s_barrier
	s_add_i32 s63, s63, 2
	s_add_u32 s61, s61, 0x100
	s_addc_u32 s62, s62, 0
	s_cmp_gt_u32 s63, 41
	s_mov_b64 s[22:23], s[24:25]

.LBB0_1332:
	s_ashr_i32 s35, s34, 31
	s_lshl_b64 s[40:41], s[34:35], 19
	s_add_u32 s40, s42, s40
	s_addc_u32 s41, s43, s41
	s_and_b64 s[44:45], s[2:3], exec
	s_cselect_b32 s35, s41, s47
	s_cselect_b32 s72, s40, s46
	s_ashr_i32 s27, s26, 31
	s_lshl_b64 s[44:45], s[26:27], 19
	s_add_u32 s44, s22, s44
	s_addc_u32 s45, s23, s45
	s_and_b64 s[50:51], s[2:3], exec
	s_cselect_b32 s27, s45, s49
	s_cselect_b32 s73, s44, s48
	s_add_u32 s46, s46, 0x40080
	s_addc_u32 s47, s47, 0
	s_add_u32 s74, s48, 0x100
	s_addc_u32 s75, s49, 0
	s_mov_b32 s76, -2
	ds_read_b128 v[128:131], v167
	ds_read_b128 v[132:135], v167 offset:1024
	ds_read_b128 v[136:139], v167 offset:2048
	ds_read_b128 v[140:143], v167 offset:3072
	ds_read_b128 v[160:163], v168
	ds_read_b128 v[172:175], v168 offset:1024
	ds_read_b128 v[178:181], v168 offset:2048
	ds_read_b128 v[182:185], v168 offset:3072
	s_add_u32 s48, s46, 0xfffc0080
	s_addc_u32 s49, s47, -1
	s_cmp_eq_u32 s76, 12
	s_cselect_b32 s51, s35, s49
	s_cselect_b32 s50, s72, s48
	s_cselect_b32 s49, s27, s75
	s_cselect_b32 s48, s73, s74
	v_lshl_add_u64 v[202:203], s[46:47], 0, v[152:153]
	s_add_i32 m0, s54, 0xc000
	ds_read_b128 v[186:189], v169
	ds_read_b128 v[190:193], v169 offset:1024
	ds_read_b128 v[194:197], v169 offset:2048
	ds_read_b128 v[198:201], v169 offset:3072
	ds_read_b128 v[206:209], v169 offset:4096
	ds_read_b128 v[210:213], v169 offset:5120
	ds_read_b128 v[214:217], v169 offset:6144
	ds_read_b128 v[218:221], v169 offset:7168
	global_load_lds_dwordx4 v[202:203], off
	v_lshl_add_u64 v[202:203], s[46:47], 0, v[154:155]
	s_add_i32 m0, s54, 0xe000
	s_nop 0
	global_load_lds_dwordx4 v[202:203], off
	s_waitcnt vmcnt(8)
	s_waitcnt lgkmcnt(0)
	s_barrier
	s_waitcnt lgkmcnt(0)
	v_mfma_f32_16x16x32_f16 v[124:127], v[128:131], v[186:189], 0
	v_mfma_f32_16x16x32_f16 v[120:123], v[136:139], v[186:189], 0
	v_mfma_f32_16x16x32_f16 v[108:111], v[128:131], v[194:197], 0
	v_mfma_f32_16x16x32_f16 v[104:107], v[136:139], v[194:197], 0
	v_mfma_f32_16x16x32_f16 v[92:95], v[128:131], v[206:209], 0
	v_mfma_f32_16x16x32_f16 v[88:91], v[136:139], v[206:209], 0
	v_mfma_f32_16x16x32_f16 v[84:87], v[128:131], v[214:217], 0
	v_mfma_f32_16x16x32_f16 v[76:79], v[136:139], v[214:217], 0
	v_mfma_f32_16x16x32_f16 v[124:127], v[132:135], v[190:193], v[124:127]
	v_mfma_f32_16x16x32_f16 v[120:123], v[140:143], v[190:193], v[120:123]
	v_mfma_f32_16x16x32_f16 v[108:111], v[132:135], v[198:201], v[108:111]
	v_mfma_f32_16x16x32_f16 v[104:107], v[140:143], v[198:201], v[104:107]
	v_mfma_f32_16x16x32_f16 v[92:95], v[132:135], v[210:213], v[92:95]
	v_mfma_f32_16x16x32_f16 v[88:91], v[140:143], v[210:213], v[88:91]
	v_mfma_f32_16x16x32_f16 v[84:87], v[132:135], v[218:221], v[84:87]
	v_mfma_f32_16x16x32_f16 v[76:79], v[140:143], v[218:221], v[76:79]
	v_mfma_f32_16x16x32_f16 v[116:119], v[160:163], v[186:189], 0
	v_mfma_f32_16x16x32_f16 v[112:115], v[178:181], v[186:189], 0
	v_mfma_f32_16x16x32_f16 v[100:103], v[160:163], v[194:197], 0
	v_mfma_f32_16x16x32_f16 v[96:99], v[178:181], v[194:197], 0
	v_mfma_f32_16x16x32_f16 v[80:83], v[160:163], v[206:209], 0
	v_mfma_f32_16x16x32_f16 v[72:75], v[178:181], v[206:209], 0
	v_mfma_f32_16x16x32_f16 v[68:71], v[160:163], v[214:217], 0
	v_mfma_f32_16x16x32_f16 v[64:67], v[178:181], v[214:217], 0
	v_mfma_f32_16x16x32_f16 v[116:119], v[172:175], v[190:193], v[116:119]
	v_mfma_f32_16x16x32_f16 v[112:115], v[182:185], v[190:193], v[112:115]
	v_mfma_f32_16x16x32_f16 v[100:103], v[172:175], v[198:201], v[100:103]
	v_mfma_f32_16x16x32_f16 v[96:99], v[182:185], v[198:201], v[96:99]
	v_mfma_f32_16x16x32_f16 v[80:83], v[172:175], v[210:213], v[80:83]
	v_mfma_f32_16x16x32_f16 v[72:75], v[182:185], v[210:213], v[72:75]
	v_mfma_f32_16x16x32_f16 v[68:71], v[172:175], v[218:221], v[68:71]
	v_mfma_f32_16x16x32_f16 v[64:67], v[182:185], v[218:221], v[64:67]
	s_barrier
	s_add_i32 s77, s64, s33
	v_lshl_add_u64 v[202:203], s[48:49], 0, v[148:149]
	s_mov_b32 m0, s77
	ds_read_b128 v[186:189], v169 offset:16384
	ds_read_b128 v[190:193], v169 offset:17408
	ds_read_b128 v[194:197], v169 offset:18432
	ds_read_b128 v[198:201], v169 offset:19456
	ds_read_b128 v[206:209], v169 offset:20480
	ds_read_b128 v[210:213], v169 offset:21504
	ds_read_b128 v[214:217], v169 offset:22528
	ds_read_b128 v[218:221], v169 offset:23552
	global_load_lds_dwordx4 v[202:203], off
	s_add_i32 m0, s77, 0x2000
	s_add_u32 s78, s48, 0x40000
	v_lshl_add_u64 v[222:223], s[48:49], 0, v[144:145]
	s_addc_u32 s79, s49, 0
	s_add_i32 s77, s65, s33
	global_load_lds_dwordx4 v[222:223], off
	v_lshl_add_u64 v[224:225], s[78:79], 0, v[148:149]
	s_mov_b32 m0, s77
	v_lshl_add_u64 v[226:227], s[50:51], 0, v[146:147]
	global_load_lds_dwordx4 v[224:225], off
	v_lshl_add_u64 v[224:225], s[78:79], 0, v[144:145]
	s_add_i32 m0, s77, 0x2000
	s_nop 0
	global_load_lds_dwordx4 v[224:225], off
	v_lshl_add_u64 v[224:225], s[50:51], 0, v[150:151]
	s_mov_b32 m0, s54
	s_nop 0
	global_load_lds_dwordx4 v[224:225], off
	s_mov_b32 m0, s55
	s_nop 0
	global_load_lds_dwordx4 v[226:227], off
	s_waitcnt vmcnt(8)
	s_waitcnt lgkmcnt(0)
	s_barrier
	s_waitcnt lgkmcnt(0)
	v_mfma_f32_16x16x32_f16 v[60:63], v[128:131], v[186:189], 0
	v_mfma_f32_16x16x32_f16 v[56:59], v[136:139], v[186:189], 0
	v_mfma_f32_16x16x32_f16 v[44:47], v[128:131], v[194:197], 0
	v_mfma_f32_16x16x32_f16 v[40:43], v[136:139], v[194:197], 0
	v_mfma_f32_16x16x32_f16 v[28:31], v[128:131], v[206:209], 0
	v_mfma_f32_16x16x32_f16 v[24:27], v[136:139], v[206:209], 0
	v_mfma_f32_16x16x32_f16 v[12:15], v[128:131], v[214:217], 0
	v_mfma_f32_16x16x32_f16 v[8:11], v[136:139], v[214:217], 0
	v_mfma_f32_16x16x32_f16 v[60:63], v[132:135], v[190:193], v[60:63]
	v_mfma_f32_16x16x32_f16 v[56:59], v[140:143], v[190:193], v[56:59]
	v_mfma_f32_16x16x32_f16 v[44:47], v[132:135], v[198:201], v[44:47]
	v_mfma_f32_16x16x32_f16 v[40:43], v[140:143], v[198:201], v[40:43]
	v_mfma_f32_16x16x32_f16 v[28:31], v[132:135], v[210:213], v[28:31]
	v_mfma_f32_16x16x32_f16 v[24:27], v[140:143], v[210:213], v[24:27]
	v_mfma_f32_16x16x32_f16 v[12:15], v[132:135], v[218:221], v[12:15]
	v_mfma_f32_16x16x32_f16 v[8:11], v[140:143], v[218:221], v[8:11]
	v_mfma_f32_16x16x32_f16 v[52:55], v[160:163], v[186:189], 0
	v_mfma_f32_16x16x32_f16 v[48:51], v[178:181], v[186:189], 0
	v_mfma_f32_16x16x32_f16 v[36:39], v[160:163], v[194:197], 0
	v_mfma_f32_16x16x32_f16 v[32:35], v[178:181], v[194:197], 0
	v_mfma_f32_16x16x32_f16 v[20:23], v[160:163], v[206:209], 0
	v_mfma_f32_16x16x32_f16 v[16:19], v[178:181], v[206:209], 0
	v_mfma_f32_16x16x32_f16 v[4:7], v[160:163], v[214:217], 0
	v_mfma_f32_16x16x32_f16 v[0:3], v[178:181], v[214:217], 0
	v_mfma_f32_16x16x32_f16 v[52:55], v[172:175], v[190:193], v[52:55]
	v_mfma_f32_16x16x32_f16 v[48:51], v[182:185], v[190:193], v[48:51]
	v_mfma_f32_16x16x32_f16 v[36:39], v[172:175], v[198:201], v[36:39]
	v_mfma_f32_16x16x32_f16 v[32:35], v[182:185], v[198:201], v[32:35]
	v_mfma_f32_16x16x32_f16 v[20:23], v[172:175], v[210:213], v[20:23]
	v_mfma_f32_16x16x32_f16 v[16:19], v[182:185], v[210:213], v[16:19]
	v_mfma_f32_16x16x32_f16 v[4:7], v[172:175], v[218:221], v[4:7]
	v_mfma_f32_16x16x32_f16 v[0:3], v[182:185], v[218:221], v[0:3]
	s_barrier
	s_add_i32 s77, 0, 0x18000
	s_add_i32 s78, 0, 0x1c000
	v_add_u32_e32 v140, s77, v165
	v_add_u32_e32 v177, s78, v165
	ds_read_b128 v[128:131], v140
	ds_read_b128 v[132:135], v140 offset:1024
	ds_read_b128 v[136:139], v140 offset:2048
	ds_read_b128 v[140:143], v140 offset:3072
	ds_read_b128 v[160:163], v177
	ds_read_b128 v[172:175], v177 offset:1024
	ds_read_b128 v[178:181], v177 offset:2048
	ds_read_b128 v[182:185], v177 offset:3072
	s_add_u32 s50, s50, 0x40000
	s_addc_u32 s51, s51, 0
	s_mov_b32 m0, s56
	v_lshl_add_u64 v[228:229], s[50:51], 0, v[150:151]
	ds_read_b128 v[186:189], v169 offset:32768
	ds_read_b128 v[190:193], v169 offset:33792
	ds_read_b128 v[194:197], v169 offset:34816
	ds_read_b128 v[198:201], v169 offset:35840
	ds_read_b128 v[206:209], v169 offset:36864
	ds_read_b128 v[210:213], v169 offset:37888
	ds_read_b128 v[214:217], v169 offset:38912
	ds_read_b128 v[218:221], v169 offset:39936
	global_load_lds_dwordx4 v[228:229], off
	v_lshl_add_u64 v[228:229], s[50:51], 0, v[146:147]
	s_mov_b32 m0, s57
	s_nop 0
	global_load_lds_dwordx4 v[228:229], off
	s_waitcnt vmcnt(8)
	s_waitcnt lgkmcnt(0)
	s_barrier
	s_waitcnt lgkmcnt(0)
	v_mfma_f32_16x16x32_f16 v[124:127], v[128:131], v[186:189], v[124:127]
	v_mfma_f32_16x16x32_f16 v[120:123], v[136:139], v[186:189], v[120:123]
	v_mfma_f32_16x16x32_f16 v[108:111], v[128:131], v[194:197], v[108:111]
	v_mfma_f32_16x16x32_f16 v[104:107], v[136:139], v[194:197], v[104:107]
	v_mfma_f32_16x16x32_f16 v[92:95], v[128:131], v[206:209], v[92:95]
	v_mfma_f32_16x16x32_f16 v[88:91], v[136:139], v[206:209], v[88:91]
	v_mfma_f32_16x16x32_f16 v[84:87], v[128:131], v[214:217], v[84:87]
	v_mfma_f32_16x16x32_f16 v[76:79], v[136:139], v[214:217], v[76:79]
	v_mfma_f32_16x16x32_f16 v[124:127], v[132:135], v[190:193], v[124:127]
	v_mfma_f32_16x16x32_f16 v[120:123], v[140:143], v[190:193], v[120:123]
	v_mfma_f32_16x16x32_f16 v[108:111], v[132:135], v[198:201], v[108:111]
	v_mfma_f32_16x16x32_f16 v[104:107], v[140:143], v[198:201], v[104:107]
	v_mfma_f32_16x16x32_f16 v[92:95], v[132:135], v[210:213], v[92:95]
	v_mfma_f32_16x16x32_f16 v[88:91], v[140:143], v[210:213], v[88:91]
	v_mfma_f32_16x16x32_f16 v[84:87], v[132:135], v[218:221], v[84:87]
	v_mfma_f32_16x16x32_f16 v[76:79], v[140:143], v[218:221], v[76:79]
	v_mfma_f32_16x16x32_f16 v[116:119], v[160:163], v[186:189], v[116:119]
	v_mfma_f32_16x16x32_f16 v[112:115], v[178:181], v[186:189], v[112:115]
	v_mfma_f32_16x16x32_f16 v[100:103], v[160:163], v[194:197], v[100:103]
	v_mfma_f32_16x16x32_f16 v[96:99], v[178:181], v[194:197], v[96:99]
	v_mfma_f32_16x16x32_f16 v[80:83], v[160:163], v[206:209], v[80:83]
	v_mfma_f32_16x16x32_f16 v[72:75], v[178:181], v[206:209], v[72:75]
	v_mfma_f32_16x16x32_f16 v[68:71], v[160:163], v[214:217], v[68:71]
	v_mfma_f32_16x16x32_f16 v[64:67], v[178:181], v[214:217], v[64:67]
	v_mfma_f32_16x16x32_f16 v[116:119], v[172:175], v[190:193], v[116:119]
	v_mfma_f32_16x16x32_f16 v[112:115], v[182:185], v[190:193], v[112:115]
	v_mfma_f32_16x16x32_f16 v[100:103], v[172:175], v[198:201], v[100:103]
	v_mfma_f32_16x16x32_f16 v[96:99], v[182:185], v[198:201], v[96:99]
	v_mfma_f32_16x16x32_f16 v[80:83], v[172:175], v[210:213], v[80:83]
	v_mfma_f32_16x16x32_f16 v[72:75], v[182:185], v[210:213], v[72:75]
	v_mfma_f32_16x16x32_f16 v[68:71], v[172:175], v[218:221], v[68:71]
	v_mfma_f32_16x16x32_f16 v[64:67], v[182:185], v[218:221], v[64:67]
	s_barrier
	s_add_i32 s50, s77, s33
	v_lshl_add_u64 v[202:203], v[202:203], 0, s[12:13]
	s_mov_b32 m0, s50
	ds_read_b128 v[186:189], v169 offset:49152
	ds_read_b128 v[190:193], v169 offset:50176
	ds_read_b128 v[194:197], v169 offset:51200
	ds_read_b128 v[198:201], v169 offset:52224
	ds_read_b128 v[206:209], v169 offset:53248
	ds_read_b128 v[210:213], v169 offset:54272
	ds_read_b128 v[214:217], v169 offset:55296
	ds_read_b128 v[218:221], v169 offset:56320
	global_load_lds_dwordx4 v[202:203], off
	s_add_i32 m0, s50, 0x2000
	s_add_u32 s48, s48, 0x40080
	v_lshl_add_u64 v[202:203], v[222:223], 0, s[12:13]
	s_addc_u32 s49, s49, 0
	s_add_i32 s50, s78, s33
	global_load_lds_dwordx4 v[202:203], off
	v_lshl_add_u64 v[202:203], s[48:49], 0, v[148:149]
	s_mov_b32 m0, s50
	s_nop 0
	global_load_lds_dwordx4 v[202:203], off
	v_lshl_add_u64 v[202:203], s[48:49], 0, v[144:145]
	s_add_i32 m0, s50, 0x2000
	s_nop 0
	global_load_lds_dwordx4 v[202:203], off
	v_lshl_add_u64 v[202:203], v[224:225], 0, s[12:13]
	s_mov_b32 m0, s61
	s_nop 0
	global_load_lds_dwordx4 v[202:203], off
	v_lshl_add_u64 v[202:203], v[226:227], 0, s[12:13]
	s_mov_b32 m0, s62
	s_nop 0
	global_load_lds_dwordx4 v[202:203], off
	s_waitcnt vmcnt(8)
	s_waitcnt lgkmcnt(0)
	s_barrier
	s_waitcnt lgkmcnt(0)
	v_mfma_f32_16x16x32_f16 v[60:63], v[128:131], v[186:189], v[60:63]
	v_mfma_f32_16x16x32_f16 v[56:59], v[136:139], v[186:189], v[56:59]
	v_mfma_f32_16x16x32_f16 v[44:47], v[128:131], v[194:197], v[44:47]
	v_mfma_f32_16x16x32_f16 v[40:43], v[136:139], v[194:197], v[40:43]
	v_mfma_f32_16x16x32_f16 v[28:31], v[128:131], v[206:209], v[28:31]
	v_mfma_f32_16x16x32_f16 v[24:27], v[136:139], v[206:209], v[24:27]
	v_mfma_f32_16x16x32_f16 v[12:15], v[128:131], v[214:217], v[12:15]
	v_mfma_f32_16x16x32_f16 v[8:11], v[136:139], v[214:217], v[8:11]
	v_mfma_f32_16x16x32_f16 v[60:63], v[132:135], v[190:193], v[60:63]
	v_mfma_f32_16x16x32_f16 v[56:59], v[140:143], v[190:193], v[56:59]
	v_mfma_f32_16x16x32_f16 v[44:47], v[132:135], v[198:201], v[44:47]
	v_mfma_f32_16x16x32_f16 v[40:43], v[140:143], v[198:201], v[40:43]
	v_mfma_f32_16x16x32_f16 v[28:31], v[132:135], v[210:213], v[28:31]
	v_mfma_f32_16x16x32_f16 v[24:27], v[140:143], v[210:213], v[24:27]
	v_mfma_f32_16x16x32_f16 v[12:15], v[132:135], v[218:221], v[12:15]
	v_mfma_f32_16x16x32_f16 v[8:11], v[140:143], v[218:221], v[8:11]
	v_mfma_f32_16x16x32_f16 v[52:55], v[160:163], v[186:189], v[52:55]
	v_mfma_f32_16x16x32_f16 v[48:51], v[178:181], v[186:189], v[48:51]
	v_mfma_f32_16x16x32_f16 v[36:39], v[160:163], v[194:197], v[36:39]
	v_mfma_f32_16x16x32_f16 v[32:35], v[178:181], v[194:197], v[32:35]
	v_mfma_f32_16x16x32_f16 v[20:23], v[160:163], v[206:209], v[20:23]
	v_mfma_f32_16x16x32_f16 v[16:19], v[178:181], v[206:209], v[16:19]
	v_mfma_f32_16x16x32_f16 v[4:7], v[160:163], v[214:217], v[4:7]
	v_mfma_f32_16x16x32_f16 v[0:3], v[178:181], v[214:217], v[0:3]
	v_mfma_f32_16x16x32_f16 v[52:55], v[172:175], v[190:193], v[52:55]
	v_mfma_f32_16x16x32_f16 v[48:51], v[182:185], v[190:193], v[48:51]
	v_mfma_f32_16x16x32_f16 v[36:39], v[172:175], v[198:201], v[36:39]
	v_mfma_f32_16x16x32_f16 v[32:35], v[182:185], v[198:201], v[32:35]
	v_mfma_f32_16x16x32_f16 v[20:23], v[172:175], v[210:213], v[20:23]
	v_mfma_f32_16x16x32_f16 v[16:19], v[182:185], v[210:213], v[16:19]
	v_mfma_f32_16x16x32_f16 v[4:7], v[172:175], v[218:221], v[4:7]
	v_mfma_f32_16x16x32_f16 v[0:3], v[182:185], v[218:221], v[0:3]
	s_barrier
	s_add_i32 s76, s76, 2
	s_add_u32 s46, s46, 0x100
	s_addc_u32 s47, s47, 0
	s_add_u32 s74, s74, 0x100
	s_addc_u32 s75, s75, 0
	s_cmp_gt_u32 s76, 13

.LBB0_1497:
	s_ashr_i32 s19, s18, 31
	s_lshl_b64 s[20:21], s[18:19], 19
	s_add_u32 s20, s36, s20
	s_addc_u32 s21, s37, s21
	s_and_b64 s[22:23], s[4:5], exec
	s_cselect_b32 s19, s21, s35
	s_cselect_b32 s25, s20, s34
	s_ashr_i32 s17, s16, 31
	s_lshl_b64 s[22:23], s[16:17], 19
	s_add_u32 s22, s33, s22
	s_addc_u32 s23, s46, s23
	s_and_b64 s[44:45], s[4:5], exec
	s_cselect_b32 s17, s23, s41
	s_cselect_b32 s62, s22, s40
	s_add_u32 s34, s34, 0x40080
	s_addc_u32 s35, s35, 0
	s_add_u32 s63, s40, 0x100
	s_addc_u32 s64, s41, 0
	s_mov_b32 s65, -2
	s_waitcnt lgkmcnt(0)
	ds_read_b128 v[80:83], v208
	ds_read_b128 v[84:87], v208 offset:1024
	ds_read_b128 v[88:91], v208 offset:2048
	ds_read_b128 v[92:95], v208 offset:3072
	ds_read_b128 v[96:99], v209
	ds_read_b128 v[104:107], v209 offset:1024
	ds_read_b128 v[108:111], v209 offset:2048
	ds_read_b128 v[112:115], v209 offset:3072
	s_add_u32 s40, s34, 0xfffc0080
	s_addc_u32 s41, s35, -1
	s_cmp_eq_u32 s65, 12
	s_cselect_b32 s45, s19, s41
	s_cselect_b32 s44, s25, s40
	s_cselect_b32 s41, s17, s64
	s_cselect_b32 s40, s62, s63
	v_lshl_add_u64 v[202:203], s[34:35], 0, v[186:187]
	s_add_i32 m0, s27, 0xc000
	ds_read_b128 v[160:163], v210
	ds_read_b128 v[164:167], v210 offset:1024
	ds_read_b128 v[168:171], v210 offset:2048
	ds_read_b128 v[172:175], v210 offset:3072
	ds_read_b128 v[194:197], v210 offset:4096
	ds_read_b128 v[198:201], v210 offset:5120
	ds_read_b128 v[212:215], v210 offset:6144
	ds_read_b128 v[216:219], v210 offset:7168
	global_load_lds_dwordx4 v[202:203], off
	v_lshl_add_u64 v[202:203], s[34:35], 0, v[188:189]
	s_add_i32 m0, s27, 0xe000
	s_nop 0
	global_load_lds_dwordx4 v[202:203], off
	s_waitcnt vmcnt(8)
	s_waitcnt lgkmcnt(0)
	s_barrier
	s_waitcnt lgkmcnt(0)
	v_mfma_f32_16x16x32_f16 v[156:159], v[80:83], v[160:163], 0
	v_mfma_f32_16x16x32_f16 v[152:155], v[88:91], v[160:163], 0
	v_mfma_f32_16x16x32_f16 v[140:143], v[80:83], v[168:171], 0
	v_mfma_f32_16x16x32_f16 v[136:139], v[88:91], v[168:171], 0
	v_mfma_f32_16x16x32_f16 v[124:127], v[80:83], v[194:197], 0
	v_mfma_f32_16x16x32_f16 v[120:123], v[88:91], v[194:197], 0
	v_mfma_f32_16x16x32_f16 v[76:79], v[80:83], v[212:215], 0
	v_mfma_f32_16x16x32_f16 v[72:75], v[88:91], v[212:215], 0
	v_mfma_f32_16x16x32_f16 v[156:159], v[84:87], v[164:167], v[156:159]
	v_mfma_f32_16x16x32_f16 v[152:155], v[92:95], v[164:167], v[152:155]
	v_mfma_f32_16x16x32_f16 v[140:143], v[84:87], v[172:175], v[140:143]
	v_mfma_f32_16x16x32_f16 v[136:139], v[92:95], v[172:175], v[136:139]
	v_mfma_f32_16x16x32_f16 v[124:127], v[84:87], v[198:201], v[124:127]
	v_mfma_f32_16x16x32_f16 v[120:123], v[92:95], v[198:201], v[120:123]
	v_mfma_f32_16x16x32_f16 v[76:79], v[84:87], v[216:219], v[76:79]
	v_mfma_f32_16x16x32_f16 v[72:75], v[92:95], v[216:219], v[72:75]
	v_mfma_f32_16x16x32_f16 v[148:151], v[96:99], v[160:163], 0
	v_mfma_f32_16x16x32_f16 v[144:147], v[108:111], v[160:163], 0
	v_mfma_f32_16x16x32_f16 v[132:135], v[96:99], v[168:171], 0
	v_mfma_f32_16x16x32_f16 v[128:131], v[108:111], v[168:171], 0
	v_mfma_f32_16x16x32_f16 v[116:119], v[96:99], v[194:197], 0
	v_mfma_f32_16x16x32_f16 v[100:103], v[108:111], v[194:197], 0
	v_mfma_f32_16x16x32_f16 v[68:71], v[96:99], v[212:215], 0
	v_mfma_f32_16x16x32_f16 v[64:67], v[108:111], v[212:215], 0
	v_mfma_f32_16x16x32_f16 v[148:151], v[104:107], v[164:167], v[148:151]
	v_mfma_f32_16x16x32_f16 v[144:147], v[112:115], v[164:167], v[144:147]
	v_mfma_f32_16x16x32_f16 v[132:135], v[104:107], v[172:175], v[132:135]
	v_mfma_f32_16x16x32_f16 v[128:131], v[112:115], v[172:175], v[128:131]
	v_mfma_f32_16x16x32_f16 v[116:119], v[104:107], v[198:201], v[116:119]
	v_mfma_f32_16x16x32_f16 v[100:103], v[112:115], v[198:201], v[100:103]
	v_mfma_f32_16x16x32_f16 v[68:71], v[104:107], v[216:219], v[68:71]
	v_mfma_f32_16x16x32_f16 v[64:67], v[112:115], v[216:219], v[64:67]
	s_barrier
	s_add_i32 s66, s60, s47
	v_lshl_add_u64 v[202:203], s[40:41], 0, v[180:181]
	s_mov_b32 m0, s66
	ds_read_b128 v[160:163], v210 offset:16384
	ds_read_b128 v[164:167], v210 offset:17408
	ds_read_b128 v[168:171], v210 offset:18432
	ds_read_b128 v[172:175], v210 offset:19456
	ds_read_b128 v[194:197], v210 offset:20480
	ds_read_b128 v[198:201], v210 offset:21504
	ds_read_b128 v[212:215], v210 offset:22528
	ds_read_b128 v[216:219], v210 offset:23552
	global_load_lds_dwordx4 v[202:203], off
	s_add_i32 m0, s66, 0x2000
	s_add_u32 s66, s40, 0x40000
	v_lshl_add_u64 v[220:221], s[40:41], 0, v[184:185]
	s_addc_u32 s67, s41, 0
	s_add_i32 s68, s61, s47
	global_load_lds_dwordx4 v[220:221], off
	v_lshl_add_u64 v[222:223], s[66:67], 0, v[180:181]
	s_mov_b32 m0, s68
	v_lshl_add_u64 v[224:225], s[44:45], 0, v[182:183]
	global_load_lds_dwordx4 v[222:223], off
	v_lshl_add_u64 v[222:223], s[66:67], 0, v[184:185]
	s_add_i32 m0, s68, 0x2000
	s_nop 0
	global_load_lds_dwordx4 v[222:223], off
	v_lshl_add_u64 v[222:223], s[44:45], 0, v[178:179]
	s_mov_b32 m0, s27
	s_nop 0
	global_load_lds_dwordx4 v[222:223], off
	s_mov_b32 m0, s48
	s_nop 0
	global_load_lds_dwordx4 v[224:225], off
	s_waitcnt vmcnt(8)
	s_waitcnt lgkmcnt(0)
	s_barrier
	s_waitcnt lgkmcnt(0)
	v_mfma_f32_16x16x32_f16 v[60:63], v[80:83], v[160:163], 0
	v_mfma_f32_16x16x32_f16 v[56:59], v[88:91], v[160:163], 0
	v_mfma_f32_16x16x32_f16 v[44:47], v[80:83], v[168:171], 0
	v_mfma_f32_16x16x32_f16 v[40:43], v[88:91], v[168:171], 0
	v_mfma_f32_16x16x32_f16 v[28:31], v[80:83], v[194:197], 0
	v_mfma_f32_16x16x32_f16 v[24:27], v[88:91], v[194:197], 0
	v_mfma_f32_16x16x32_f16 v[12:15], v[80:83], v[212:215], 0
	v_mfma_f32_16x16x32_f16 v[8:11], v[88:91], v[212:215], 0
	v_mfma_f32_16x16x32_f16 v[60:63], v[84:87], v[164:167], v[60:63]
	v_mfma_f32_16x16x32_f16 v[56:59], v[92:95], v[164:167], v[56:59]
	v_mfma_f32_16x16x32_f16 v[44:47], v[84:87], v[172:175], v[44:47]
	v_mfma_f32_16x16x32_f16 v[40:43], v[92:95], v[172:175], v[40:43]
	v_mfma_f32_16x16x32_f16 v[28:31], v[84:87], v[198:201], v[28:31]
	v_mfma_f32_16x16x32_f16 v[24:27], v[92:95], v[198:201], v[24:27]
	v_mfma_f32_16x16x32_f16 v[12:15], v[84:87], v[216:219], v[12:15]
	v_mfma_f32_16x16x32_f16 v[8:11], v[92:95], v[216:219], v[8:11]
	v_mfma_f32_16x16x32_f16 v[52:55], v[96:99], v[160:163], 0
	v_mfma_f32_16x16x32_f16 v[48:51], v[108:111], v[160:163], 0
	v_mfma_f32_16x16x32_f16 v[36:39], v[96:99], v[168:171], 0
	v_mfma_f32_16x16x32_f16 v[32:35], v[108:111], v[168:171], 0
	v_mfma_f32_16x16x32_f16 v[20:23], v[96:99], v[194:197], 0
	v_mfma_f32_16x16x32_f16 v[16:19], v[108:111], v[194:197], 0
	v_mfma_f32_16x16x32_f16 v[4:7], v[96:99], v[212:215], 0
	v_mfma_f32_16x16x32_f16 v[0:3], v[108:111], v[212:215], 0
	v_mfma_f32_16x16x32_f16 v[52:55], v[104:107], v[164:167], v[52:55]
	v_mfma_f32_16x16x32_f16 v[48:51], v[112:115], v[164:167], v[48:51]
	v_mfma_f32_16x16x32_f16 v[36:39], v[104:107], v[172:175], v[36:39]
	v_mfma_f32_16x16x32_f16 v[32:35], v[112:115], v[172:175], v[32:35]
	v_mfma_f32_16x16x32_f16 v[20:23], v[104:107], v[198:201], v[20:23]
	v_mfma_f32_16x16x32_f16 v[16:19], v[112:115], v[198:201], v[16:19]
	v_mfma_f32_16x16x32_f16 v[4:7], v[104:107], v[216:219], v[4:7]
	v_mfma_f32_16x16x32_f16 v[0:3], v[112:115], v[216:219], v[0:3]
	s_barrier
	s_add_i32 s66, 0, 0x18000
	s_add_i32 s67, 0, 0x1c000
	v_add_u32_e32 v92, s66, v206
	v_add_u32_e32 v112, s67, v206
	ds_read_b128 v[80:83], v92
	ds_read_b128 v[84:87], v92 offset:1024
	ds_read_b128 v[88:91], v92 offset:2048
	ds_read_b128 v[92:95], v92 offset:3072
	ds_read_b128 v[96:99], v112
	ds_read_b128 v[104:107], v112 offset:1024
	ds_read_b128 v[108:111], v112 offset:2048
	ds_read_b128 v[112:115], v112 offset:3072
	s_add_u32 s44, s44, 0x40000
	s_addc_u32 s45, s45, 0
	s_mov_b32 m0, s49
	v_lshl_add_u64 v[226:227], s[44:45], 0, v[178:179]
	ds_read_b128 v[160:163], v210 offset:32768
	ds_read_b128 v[164:167], v210 offset:33792
	ds_read_b128 v[168:171], v210 offset:34816
	ds_read_b128 v[172:175], v210 offset:35840
	ds_read_b128 v[194:197], v210 offset:36864
	ds_read_b128 v[198:201], v210 offset:37888
	ds_read_b128 v[212:215], v210 offset:38912
	ds_read_b128 v[216:219], v210 offset:39936
	global_load_lds_dwordx4 v[226:227], off
	v_lshl_add_u64 v[226:227], s[44:45], 0, v[182:183]
	s_mov_b32 m0, s50
	s_nop 0
	global_load_lds_dwordx4 v[226:227], off
	s_waitcnt vmcnt(8)
	s_waitcnt lgkmcnt(0)
	s_barrier
	s_waitcnt lgkmcnt(0)
	v_mfma_f32_16x16x32_f16 v[156:159], v[80:83], v[160:163], v[156:159]
	v_mfma_f32_16x16x32_f16 v[152:155], v[88:91], v[160:163], v[152:155]
	v_mfma_f32_16x16x32_f16 v[140:143], v[80:83], v[168:171], v[140:143]
	v_mfma_f32_16x16x32_f16 v[136:139], v[88:91], v[168:171], v[136:139]
	v_mfma_f32_16x16x32_f16 v[124:127], v[80:83], v[194:197], v[124:127]
	v_mfma_f32_16x16x32_f16 v[120:123], v[88:91], v[194:197], v[120:123]
	v_mfma_f32_16x16x32_f16 v[76:79], v[80:83], v[212:215], v[76:79]
	v_mfma_f32_16x16x32_f16 v[72:75], v[88:91], v[212:215], v[72:75]
	v_mfma_f32_16x16x32_f16 v[156:159], v[84:87], v[164:167], v[156:159]
	v_mfma_f32_16x16x32_f16 v[152:155], v[92:95], v[164:167], v[152:155]
	v_mfma_f32_16x16x32_f16 v[140:143], v[84:87], v[172:175], v[140:143]
	v_mfma_f32_16x16x32_f16 v[136:139], v[92:95], v[172:175], v[136:139]
	v_mfma_f32_16x16x32_f16 v[124:127], v[84:87], v[198:201], v[124:127]
	v_mfma_f32_16x16x32_f16 v[120:123], v[92:95], v[198:201], v[120:123]
	v_mfma_f32_16x16x32_f16 v[76:79], v[84:87], v[216:219], v[76:79]
	v_mfma_f32_16x16x32_f16 v[72:75], v[92:95], v[216:219], v[72:75]
	v_mfma_f32_16x16x32_f16 v[148:151], v[96:99], v[160:163], v[148:151]
	v_mfma_f32_16x16x32_f16 v[144:147], v[108:111], v[160:163], v[144:147]
	v_mfma_f32_16x16x32_f16 v[132:135], v[96:99], v[168:171], v[132:135]
	v_mfma_f32_16x16x32_f16 v[128:131], v[108:111], v[168:171], v[128:131]
	v_mfma_f32_16x16x32_f16 v[116:119], v[96:99], v[194:197], v[116:119]
	v_mfma_f32_16x16x32_f16 v[100:103], v[108:111], v[194:197], v[100:103]
	v_mfma_f32_16x16x32_f16 v[68:71], v[96:99], v[212:215], v[68:71]
	v_mfma_f32_16x16x32_f16 v[64:67], v[108:111], v[212:215], v[64:67]
	v_mfma_f32_16x16x32_f16 v[148:151], v[104:107], v[164:167], v[148:151]
	v_mfma_f32_16x16x32_f16 v[144:147], v[112:115], v[164:167], v[144:147]
	v_mfma_f32_16x16x32_f16 v[132:135], v[104:107], v[172:175], v[132:135]
	v_mfma_f32_16x16x32_f16 v[128:131], v[112:115], v[172:175], v[128:131]
	v_mfma_f32_16x16x32_f16 v[116:119], v[104:107], v[198:201], v[116:119]
	v_mfma_f32_16x16x32_f16 v[100:103], v[112:115], v[198:201], v[100:103]
	v_mfma_f32_16x16x32_f16 v[68:71], v[104:107], v[216:219], v[68:71]
	v_mfma_f32_16x16x32_f16 v[64:67], v[112:115], v[216:219], v[64:67]
	s_barrier
	s_add_i32 s44, s66, s47
	v_lshl_add_u64 v[202:203], v[202:203], 0, s[12:13]
	s_mov_b32 m0, s44
	ds_read_b128 v[160:163], v210 offset:49152
	ds_read_b128 v[164:167], v210 offset:50176
	ds_read_b128 v[168:171], v210 offset:51200
	ds_read_b128 v[172:175], v210 offset:52224
	ds_read_b128 v[194:197], v210 offset:53248
	ds_read_b128 v[198:201], v210 offset:54272
	ds_read_b128 v[212:215], v210 offset:55296
	ds_read_b128 v[216:219], v210 offset:56320
	global_load_lds_dwordx4 v[202:203], off
	s_add_i32 m0, s44, 0x2000
	s_add_u32 s40, s40, 0x40080
	v_lshl_add_u64 v[202:203], v[220:221], 0, s[12:13]
	s_addc_u32 s41, s41, 0
	s_add_i32 s44, s67, s47
	global_load_lds_dwordx4 v[202:203], off
	v_lshl_add_u64 v[202:203], s[40:41], 0, v[180:181]
	s_mov_b32 m0, s44
	s_nop 0
	global_load_lds_dwordx4 v[202:203], off
	v_lshl_add_u64 v[202:203], s[40:41], 0, v[184:185]
	s_add_i32 m0, s44, 0x2000
	s_nop 0
	global_load_lds_dwordx4 v[202:203], off
	v_lshl_add_u64 v[202:203], v[222:223], 0, s[12:13]
	s_mov_b32 m0, s56
	s_nop 0
	global_load_lds_dwordx4 v[202:203], off
	v_lshl_add_u64 v[202:203], v[224:225], 0, s[12:13]
	s_mov_b32 m0, s57
	s_nop 0
	global_load_lds_dwordx4 v[202:203], off
	s_waitcnt vmcnt(8)
	s_waitcnt lgkmcnt(0)
	s_barrier
	s_waitcnt lgkmcnt(0)
	v_mfma_f32_16x16x32_f16 v[60:63], v[80:83], v[160:163], v[60:63]
	v_mfma_f32_16x16x32_f16 v[56:59], v[88:91], v[160:163], v[56:59]
	v_mfma_f32_16x16x32_f16 v[44:47], v[80:83], v[168:171], v[44:47]
	v_mfma_f32_16x16x32_f16 v[40:43], v[88:91], v[168:171], v[40:43]
	v_mfma_f32_16x16x32_f16 v[28:31], v[80:83], v[194:197], v[28:31]
	v_mfma_f32_16x16x32_f16 v[24:27], v[88:91], v[194:197], v[24:27]
	v_mfma_f32_16x16x32_f16 v[12:15], v[80:83], v[212:215], v[12:15]
	v_mfma_f32_16x16x32_f16 v[8:11], v[88:91], v[212:215], v[8:11]
	v_mfma_f32_16x16x32_f16 v[60:63], v[84:87], v[164:167], v[60:63]
	v_mfma_f32_16x16x32_f16 v[56:59], v[92:95], v[164:167], v[56:59]
	v_mfma_f32_16x16x32_f16 v[44:47], v[84:87], v[172:175], v[44:47]
	v_mfma_f32_16x16x32_f16 v[40:43], v[92:95], v[172:175], v[40:43]
	v_mfma_f32_16x16x32_f16 v[28:31], v[84:87], v[198:201], v[28:31]
	v_mfma_f32_16x16x32_f16 v[24:27], v[92:95], v[198:201], v[24:27]
	v_mfma_f32_16x16x32_f16 v[12:15], v[84:87], v[216:219], v[12:15]
	v_mfma_f32_16x16x32_f16 v[8:11], v[92:95], v[216:219], v[8:11]
	v_mfma_f32_16x16x32_f16 v[52:55], v[96:99], v[160:163], v[52:55]
	v_mfma_f32_16x16x32_f16 v[48:51], v[108:111], v[160:163], v[48:51]
	v_mfma_f32_16x16x32_f16 v[36:39], v[96:99], v[168:171], v[36:39]
	v_mfma_f32_16x16x32_f16 v[32:35], v[108:111], v[168:171], v[32:35]
	v_mfma_f32_16x16x32_f16 v[20:23], v[96:99], v[194:197], v[20:23]
	v_mfma_f32_16x16x32_f16 v[16:19], v[108:111], v[194:197], v[16:19]
	v_mfma_f32_16x16x32_f16 v[4:7], v[96:99], v[212:215], v[4:7]
	v_mfma_f32_16x16x32_f16 v[0:3], v[108:111], v[212:215], v[0:3]
	v_mfma_f32_16x16x32_f16 v[52:55], v[104:107], v[164:167], v[52:55]
	v_mfma_f32_16x16x32_f16 v[48:51], v[112:115], v[164:167], v[48:51]
	v_mfma_f32_16x16x32_f16 v[36:39], v[104:107], v[172:175], v[36:39]
	v_mfma_f32_16x16x32_f16 v[32:35], v[112:115], v[172:175], v[32:35]
	v_mfma_f32_16x16x32_f16 v[20:23], v[104:107], v[198:201], v[20:23]
	v_mfma_f32_16x16x32_f16 v[16:19], v[112:115], v[198:201], v[16:19]
	v_mfma_f32_16x16x32_f16 v[4:7], v[104:107], v[216:219], v[4:7]
	v_mfma_f32_16x16x32_f16 v[0:3], v[112:115], v[216:219], v[0:3]
	s_barrier
	s_add_i32 s65, s65, 2
	s_add_u32 s34, s34, 0x100
	s_addc_u32 s35, s35, 0
	s_add_u32 s63, s63, 0x100
	s_addc_u32 s64, s64, 0
	s_cmp_gt_u32 s65, 13

.LBB0_1584:
	s_ashr_i32 s17, s16, 31
	s_lshl_b64 s[18:19], s[16:17], 19
	s_add_u32 s18, s42, s18
	s_addc_u32 s19, s43, s19
	s_and_b64 s[20:21], s[2:3], exec
	s_cselect_b32 s17, s19, s25
	s_cselect_b32 s60, s18, s24
	s_ashr_i32 s15, s14, 31
	s_lshl_b64 s[20:21], s[14:15], 19
	s_add_u32 s20, s33, s20
	s_addc_u32 s21, s40, s21
	s_and_b64 s[34:35], s[2:3], exec
	s_cselect_b32 s15, s21, s27
	s_cselect_b32 s61, s20, s26
	s_add_u32 s24, s24, 0x40080
	s_addc_u32 s25, s25, 0
	s_add_u32 s62, s26, 0x100
	s_addc_u32 s63, s27, 0
	s_mov_b32 s64, -2
	ds_read_b128 v[104:107], v171
	ds_read_b128 v[108:111], v171 offset:1024
	ds_read_b128 v[112:115], v171 offset:2048
	ds_read_b128 v[116:119], v171 offset:3072
	ds_read_b128 v[160:163], v172
	ds_read_b128 v[164:167], v172 offset:1024
	ds_read_b128 v[178:181], v172 offset:2048
	ds_read_b128 v[182:185], v172 offset:3072
	s_add_u32 s26, s24, 0xfffc0080
	s_addc_u32 s27, s25, -1
	s_cmp_eq_u32 s64, 12
	s_cselect_b32 s35, s17, s27
	s_cselect_b32 s34, s60, s26
	s_cselect_b32 s27, s15, s63
	s_cselect_b32 s26, s61, s62
	v_lshl_add_u64 v[202:203], s[24:25], 0, v[152:153]
	s_add_i32 m0, s23, 0xc000
	ds_read_b128 v[186:189], v173
	ds_read_b128 v[190:193], v173 offset:1024
	ds_read_b128 v[194:197], v173 offset:2048
	ds_read_b128 v[198:201], v173 offset:3072
	ds_read_b128 v[206:209], v173 offset:4096
	ds_read_b128 v[210:213], v173 offset:5120
	ds_read_b128 v[214:217], v173 offset:6144
	ds_read_b128 v[218:221], v173 offset:7168
	global_load_lds_dwordx4 v[202:203], off
	v_lshl_add_u64 v[202:203], s[24:25], 0, v[154:155]
	s_add_i32 m0, s23, 0xe000
	s_nop 0
	global_load_lds_dwordx4 v[202:203], off
	s_waitcnt vmcnt(8)
	s_waitcnt lgkmcnt(0)
	s_barrier
	s_waitcnt lgkmcnt(0)
	v_mfma_f32_16x16x32_f16 v[140:143], v[104:107], v[186:189], 0
	v_mfma_f32_16x16x32_f16 v[136:139], v[112:115], v[186:189], 0
	v_mfma_f32_16x16x32_f16 v[124:127], v[104:107], v[194:197], 0
	v_mfma_f32_16x16x32_f16 v[120:123], v[112:115], v[194:197], 0
	v_mfma_f32_16x16x32_f16 v[92:95], v[104:107], v[206:209], 0
	v_mfma_f32_16x16x32_f16 v[88:91], v[112:115], v[206:209], 0
	v_mfma_f32_16x16x32_f16 v[76:79], v[104:107], v[214:217], 0
	v_mfma_f32_16x16x32_f16 v[72:75], v[112:115], v[214:217], 0
	v_mfma_f32_16x16x32_f16 v[140:143], v[108:111], v[190:193], v[140:143]
	v_mfma_f32_16x16x32_f16 v[136:139], v[116:119], v[190:193], v[136:139]
	v_mfma_f32_16x16x32_f16 v[124:127], v[108:111], v[198:201], v[124:127]
	v_mfma_f32_16x16x32_f16 v[120:123], v[116:119], v[198:201], v[120:123]
	v_mfma_f32_16x16x32_f16 v[92:95], v[108:111], v[210:213], v[92:95]
	v_mfma_f32_16x16x32_f16 v[88:91], v[116:119], v[210:213], v[88:91]
	v_mfma_f32_16x16x32_f16 v[76:79], v[108:111], v[218:221], v[76:79]
	v_mfma_f32_16x16x32_f16 v[72:75], v[116:119], v[218:221], v[72:75]
	v_mfma_f32_16x16x32_f16 v[132:135], v[160:163], v[186:189], 0
	v_mfma_f32_16x16x32_f16 v[128:131], v[178:181], v[186:189], 0
	v_mfma_f32_16x16x32_f16 v[100:103], v[160:163], v[194:197], 0
	v_mfma_f32_16x16x32_f16 v[96:99], v[178:181], v[194:197], 0
	v_mfma_f32_16x16x32_f16 v[84:87], v[160:163], v[206:209], 0
	v_mfma_f32_16x16x32_f16 v[80:83], v[178:181], v[206:209], 0
	v_mfma_f32_16x16x32_f16 v[68:71], v[160:163], v[214:217], 0
	v_mfma_f32_16x16x32_f16 v[64:67], v[178:181], v[214:217], 0
	v_mfma_f32_16x16x32_f16 v[132:135], v[164:167], v[190:193], v[132:135]
	v_mfma_f32_16x16x32_f16 v[128:131], v[182:185], v[190:193], v[128:131]
	v_mfma_f32_16x16x32_f16 v[100:103], v[164:167], v[198:201], v[100:103]
	v_mfma_f32_16x16x32_f16 v[96:99], v[182:185], v[198:201], v[96:99]
	v_mfma_f32_16x16x32_f16 v[84:87], v[164:167], v[210:213], v[84:87]
	v_mfma_f32_16x16x32_f16 v[80:83], v[182:185], v[210:213], v[80:83]
	v_mfma_f32_16x16x32_f16 v[68:71], v[164:167], v[218:221], v[68:71]
	v_mfma_f32_16x16x32_f16 v[64:67], v[182:185], v[218:221], v[64:67]
	s_barrier
	s_add_i32 s65, s55, s41
	v_lshl_add_u64 v[202:203], s[26:27], 0, v[148:149]
	s_mov_b32 m0, s65
	ds_read_b128 v[186:189], v173 offset:16384
	ds_read_b128 v[190:193], v173 offset:17408
	ds_read_b128 v[194:197], v173 offset:18432
	ds_read_b128 v[198:201], v173 offset:19456
	ds_read_b128 v[206:209], v173 offset:20480
	ds_read_b128 v[210:213], v173 offset:21504
	ds_read_b128 v[214:217], v173 offset:22528
	ds_read_b128 v[218:221], v173 offset:23552
	global_load_lds_dwordx4 v[202:203], off
	s_add_i32 m0, s65, 0x2000
	s_add_u32 s66, s26, 0x40000
	v_lshl_add_u64 v[222:223], s[26:27], 0, v[144:145]
	s_addc_u32 s67, s27, 0
	s_add_i32 s65, s56, s41
	global_load_lds_dwordx4 v[222:223], off
	v_lshl_add_u64 v[224:225], s[66:67], 0, v[148:149]
	s_mov_b32 m0, s65
	v_lshl_add_u64 v[226:227], s[34:35], 0, v[146:147]
	global_load_lds_dwordx4 v[224:225], off
	v_lshl_add_u64 v[224:225], s[66:67], 0, v[144:145]
	s_add_i32 m0, s65, 0x2000
	s_nop 0
	global_load_lds_dwordx4 v[224:225], off
	v_lshl_add_u64 v[224:225], s[34:35], 0, v[150:151]
	s_mov_b32 m0, s23
	s_nop 0
	global_load_lds_dwordx4 v[224:225], off
	s_mov_b32 m0, s46
	s_nop 0
	global_load_lds_dwordx4 v[226:227], off
	s_waitcnt vmcnt(8)
	s_waitcnt lgkmcnt(0)
	s_barrier
	s_waitcnt lgkmcnt(0)
	v_mfma_f32_16x16x32_f16 v[60:63], v[104:107], v[186:189], 0
	v_mfma_f32_16x16x32_f16 v[56:59], v[112:115], v[186:189], 0
	v_mfma_f32_16x16x32_f16 v[44:47], v[104:107], v[194:197], 0
	v_mfma_f32_16x16x32_f16 v[40:43], v[112:115], v[194:197], 0
	v_mfma_f32_16x16x32_f16 v[28:31], v[104:107], v[206:209], 0
	v_mfma_f32_16x16x32_f16 v[24:27], v[112:115], v[206:209], 0
	v_mfma_f32_16x16x32_f16 v[12:15], v[104:107], v[214:217], 0
	v_mfma_f32_16x16x32_f16 v[8:11], v[112:115], v[214:217], 0
	v_mfma_f32_16x16x32_f16 v[60:63], v[108:111], v[190:193], v[60:63]
	v_mfma_f32_16x16x32_f16 v[56:59], v[116:119], v[190:193], v[56:59]
	v_mfma_f32_16x16x32_f16 v[44:47], v[108:111], v[198:201], v[44:47]
	v_mfma_f32_16x16x32_f16 v[40:43], v[116:119], v[198:201], v[40:43]
	v_mfma_f32_16x16x32_f16 v[28:31], v[108:111], v[210:213], v[28:31]
	v_mfma_f32_16x16x32_f16 v[24:27], v[116:119], v[210:213], v[24:27]
	v_mfma_f32_16x16x32_f16 v[12:15], v[108:111], v[218:221], v[12:15]
	v_mfma_f32_16x16x32_f16 v[8:11], v[116:119], v[218:221], v[8:11]
	v_mfma_f32_16x16x32_f16 v[52:55], v[160:163], v[186:189], 0
	v_mfma_f32_16x16x32_f16 v[48:51], v[178:181], v[186:189], 0
	v_mfma_f32_16x16x32_f16 v[36:39], v[160:163], v[194:197], 0
	v_mfma_f32_16x16x32_f16 v[32:35], v[178:181], v[194:197], 0
	v_mfma_f32_16x16x32_f16 v[20:23], v[160:163], v[206:209], 0
	v_mfma_f32_16x16x32_f16 v[16:19], v[178:181], v[206:209], 0
	v_mfma_f32_16x16x32_f16 v[4:7], v[160:163], v[214:217], 0
	v_mfma_f32_16x16x32_f16 v[0:3], v[178:181], v[214:217], 0
	v_mfma_f32_16x16x32_f16 v[52:55], v[164:167], v[190:193], v[52:55]
	v_mfma_f32_16x16x32_f16 v[48:51], v[182:185], v[190:193], v[48:51]
	v_mfma_f32_16x16x32_f16 v[36:39], v[164:167], v[198:201], v[36:39]
	v_mfma_f32_16x16x32_f16 v[32:35], v[182:185], v[198:201], v[32:35]
	v_mfma_f32_16x16x32_f16 v[20:23], v[164:167], v[210:213], v[20:23]
	v_mfma_f32_16x16x32_f16 v[16:19], v[182:185], v[210:213], v[16:19]
	v_mfma_f32_16x16x32_f16 v[4:7], v[164:167], v[218:221], v[4:7]
	v_mfma_f32_16x16x32_f16 v[0:3], v[182:185], v[218:221], v[0:3]
	s_barrier
	s_add_i32 s65, 0, 0x18000
	s_add_i32 s66, 0, 0x1c000
	v_add_u32_e32 v116, s65, v169
	v_add_u32_e32 v177, s66, v169
	ds_read_b128 v[104:107], v116
	ds_read_b128 v[108:111], v116 offset:1024
	ds_read_b128 v[112:115], v116 offset:2048
	ds_read_b128 v[116:119], v116 offset:3072
	ds_read_b128 v[160:163], v177
	ds_read_b128 v[164:167], v177 offset:1024
	ds_read_b128 v[178:181], v177 offset:2048
	ds_read_b128 v[182:185], v177 offset:3072
	s_add_u32 s34, s34, 0x40000
	s_addc_u32 s35, s35, 0
	s_mov_b32 m0, s47
	v_lshl_add_u64 v[228:229], s[34:35], 0, v[150:151]
	ds_read_b128 v[186:189], v173 offset:32768
	ds_read_b128 v[190:193], v173 offset:33792
	ds_read_b128 v[194:197], v173 offset:34816
	ds_read_b128 v[198:201], v173 offset:35840
	ds_read_b128 v[206:209], v173 offset:36864
	ds_read_b128 v[210:213], v173 offset:37888
	ds_read_b128 v[214:217], v173 offset:38912
	ds_read_b128 v[218:221], v173 offset:39936
	global_load_lds_dwordx4 v[228:229], off
	v_lshl_add_u64 v[228:229], s[34:35], 0, v[146:147]
	s_mov_b32 m0, s48
	s_nop 0
	global_load_lds_dwordx4 v[228:229], off
	s_waitcnt vmcnt(8)
	s_waitcnt lgkmcnt(0)
	s_barrier
	s_waitcnt lgkmcnt(0)
	v_mfma_f32_16x16x32_f16 v[140:143], v[104:107], v[186:189], v[140:143]
	v_mfma_f32_16x16x32_f16 v[136:139], v[112:115], v[186:189], v[136:139]
	v_mfma_f32_16x16x32_f16 v[124:127], v[104:107], v[194:197], v[124:127]
	v_mfma_f32_16x16x32_f16 v[120:123], v[112:115], v[194:197], v[120:123]
	v_mfma_f32_16x16x32_f16 v[92:95], v[104:107], v[206:209], v[92:95]
	v_mfma_f32_16x16x32_f16 v[88:91], v[112:115], v[206:209], v[88:91]
	v_mfma_f32_16x16x32_f16 v[76:79], v[104:107], v[214:217], v[76:79]
	v_mfma_f32_16x16x32_f16 v[72:75], v[112:115], v[214:217], v[72:75]
	v_mfma_f32_16x16x32_f16 v[140:143], v[108:111], v[190:193], v[140:143]
	v_mfma_f32_16x16x32_f16 v[136:139], v[116:119], v[190:193], v[136:139]
	v_mfma_f32_16x16x32_f16 v[124:127], v[108:111], v[198:201], v[124:127]
	v_mfma_f32_16x16x32_f16 v[120:123], v[116:119], v[198:201], v[120:123]
	v_mfma_f32_16x16x32_f16 v[92:95], v[108:111], v[210:213], v[92:95]
	v_mfma_f32_16x16x32_f16 v[88:91], v[116:119], v[210:213], v[88:91]
	v_mfma_f32_16x16x32_f16 v[76:79], v[108:111], v[218:221], v[76:79]
	v_mfma_f32_16x16x32_f16 v[72:75], v[116:119], v[218:221], v[72:75]
	v_mfma_f32_16x16x32_f16 v[132:135], v[160:163], v[186:189], v[132:135]
	v_mfma_f32_16x16x32_f16 v[128:131], v[178:181], v[186:189], v[128:131]
	v_mfma_f32_16x16x32_f16 v[100:103], v[160:163], v[194:197], v[100:103]
	v_mfma_f32_16x16x32_f16 v[96:99], v[178:181], v[194:197], v[96:99]
	v_mfma_f32_16x16x32_f16 v[84:87], v[160:163], v[206:209], v[84:87]
	v_mfma_f32_16x16x32_f16 v[80:83], v[178:181], v[206:209], v[80:83]
	v_mfma_f32_16x16x32_f16 v[68:71], v[160:163], v[214:217], v[68:71]
	v_mfma_f32_16x16x32_f16 v[64:67], v[178:181], v[214:217], v[64:67]
	v_mfma_f32_16x16x32_f16 v[132:135], v[164:167], v[190:193], v[132:135]
	v_mfma_f32_16x16x32_f16 v[128:131], v[182:185], v[190:193], v[128:131]
	v_mfma_f32_16x16x32_f16 v[100:103], v[164:167], v[198:201], v[100:103]
	v_mfma_f32_16x16x32_f16 v[96:99], v[182:185], v[198:201], v[96:99]
	v_mfma_f32_16x16x32_f16 v[84:87], v[164:167], v[210:213], v[84:87]
	v_mfma_f32_16x16x32_f16 v[80:83], v[182:185], v[210:213], v[80:83]
	v_mfma_f32_16x16x32_f16 v[68:71], v[164:167], v[218:221], v[68:71]
	v_mfma_f32_16x16x32_f16 v[64:67], v[182:185], v[218:221], v[64:67]
	s_barrier
	s_add_i32 s34, s65, s41
	v_lshl_add_u64 v[202:203], v[202:203], 0, s[10:11]
	s_mov_b32 m0, s34
	ds_read_b128 v[186:189], v173 offset:49152
	ds_read_b128 v[190:193], v173 offset:50176
	ds_read_b128 v[194:197], v173 offset:51200
	ds_read_b128 v[198:201], v173 offset:52224
	ds_read_b128 v[206:209], v173 offset:53248
	ds_read_b128 v[210:213], v173 offset:54272
	ds_read_b128 v[214:217], v173 offset:55296
	ds_read_b128 v[218:221], v173 offset:56320
	global_load_lds_dwordx4 v[202:203], off
	s_add_i32 m0, s34, 0x2000
	s_add_u32 s26, s26, 0x40080
	v_lshl_add_u64 v[202:203], v[222:223], 0, s[10:11]
	s_addc_u32 s27, s27, 0
	s_add_i32 s34, s66, s41
	global_load_lds_dwordx4 v[202:203], off
	v_lshl_add_u64 v[202:203], s[26:27], 0, v[148:149]
	s_mov_b32 m0, s34
	s_nop 0
	global_load_lds_dwordx4 v[202:203], off
	v_lshl_add_u64 v[202:203], s[26:27], 0, v[144:145]
	s_add_i32 m0, s34, 0x2000
	s_nop 0
	global_load_lds_dwordx4 v[202:203], off
	v_lshl_add_u64 v[202:203], v[224:225], 0, s[10:11]
	s_mov_b32 m0, s52
	s_nop 0
	global_load_lds_dwordx4 v[202:203], off
	v_lshl_add_u64 v[202:203], v[226:227], 0, s[10:11]
	s_mov_b32 m0, s53
	s_nop 0
	global_load_lds_dwordx4 v[202:203], off
	s_waitcnt vmcnt(8)
	s_waitcnt lgkmcnt(0)
	s_barrier
	s_waitcnt lgkmcnt(0)
	v_mfma_f32_16x16x32_f16 v[60:63], v[104:107], v[186:189], v[60:63]
	v_mfma_f32_16x16x32_f16 v[56:59], v[112:115], v[186:189], v[56:59]
	v_mfma_f32_16x16x32_f16 v[44:47], v[104:107], v[194:197], v[44:47]
	v_mfma_f32_16x16x32_f16 v[40:43], v[112:115], v[194:197], v[40:43]
	v_mfma_f32_16x16x32_f16 v[28:31], v[104:107], v[206:209], v[28:31]
	v_mfma_f32_16x16x32_f16 v[24:27], v[112:115], v[206:209], v[24:27]
	v_mfma_f32_16x16x32_f16 v[12:15], v[104:107], v[214:217], v[12:15]
	v_mfma_f32_16x16x32_f16 v[8:11], v[112:115], v[214:217], v[8:11]
	v_mfma_f32_16x16x32_f16 v[60:63], v[108:111], v[190:193], v[60:63]
	v_mfma_f32_16x16x32_f16 v[56:59], v[116:119], v[190:193], v[56:59]
	v_mfma_f32_16x16x32_f16 v[44:47], v[108:111], v[198:201], v[44:47]
	v_mfma_f32_16x16x32_f16 v[40:43], v[116:119], v[198:201], v[40:43]
	v_mfma_f32_16x16x32_f16 v[28:31], v[108:111], v[210:213], v[28:31]
	v_mfma_f32_16x16x32_f16 v[24:27], v[116:119], v[210:213], v[24:27]
	v_mfma_f32_16x16x32_f16 v[12:15], v[108:111], v[218:221], v[12:15]
	v_mfma_f32_16x16x32_f16 v[8:11], v[116:119], v[218:221], v[8:11]
	v_mfma_f32_16x16x32_f16 v[52:55], v[160:163], v[186:189], v[52:55]
	v_mfma_f32_16x16x32_f16 v[48:51], v[178:181], v[186:189], v[48:51]
	v_mfma_f32_16x16x32_f16 v[36:39], v[160:163], v[194:197], v[36:39]
	v_mfma_f32_16x16x32_f16 v[32:35], v[178:181], v[194:197], v[32:35]
	v_mfma_f32_16x16x32_f16 v[20:23], v[160:163], v[206:209], v[20:23]
	v_mfma_f32_16x16x32_f16 v[16:19], v[178:181], v[206:209], v[16:19]
	v_mfma_f32_16x16x32_f16 v[4:7], v[160:163], v[214:217], v[4:7]
	v_mfma_f32_16x16x32_f16 v[0:3], v[178:181], v[214:217], v[0:3]
	v_mfma_f32_16x16x32_f16 v[52:55], v[164:167], v[190:193], v[52:55]
	v_mfma_f32_16x16x32_f16 v[48:51], v[182:185], v[190:193], v[48:51]
	v_mfma_f32_16x16x32_f16 v[36:39], v[164:167], v[198:201], v[36:39]
	v_mfma_f32_16x16x32_f16 v[32:35], v[182:185], v[198:201], v[32:35]
	v_mfma_f32_16x16x32_f16 v[20:23], v[164:167], v[210:213], v[20:23]
	v_mfma_f32_16x16x32_f16 v[16:19], v[182:185], v[210:213], v[16:19]
	v_mfma_f32_16x16x32_f16 v[4:7], v[164:167], v[218:221], v[4:7]
	v_mfma_f32_16x16x32_f16 v[0:3], v[182:185], v[218:221], v[0:3]
	s_barrier
	s_add_i32 s64, s64, 2
	s_add_u32 s24, s24, 0x100
	s_addc_u32 s25, s25, 0
	s_add_u32 s62, s62, 0x100
	s_addc_u32 s63, s63, 0
	s_cmp_gt_u32 s64, 13

.LBB0_1667:
	s_add_u32 s58, s24, 0x100
	s_addc_u32 s59, s25, 0
	s_mov_b32 s60, -2
	ds_read_b128 v[144:147], v169
	ds_read_b128 v[148:151], v169 offset:1024
	ds_read_b128 v[152:155], v169 offset:2048
	ds_read_b128 v[156:159], v169 offset:3072
	ds_read_b128 v[160:163], v170
	ds_read_b128 v[172:175], v170 offset:1024
	ds_read_b128 v[176:179], v170 offset:2048
	ds_read_b128 v[180:183], v170 offset:3072
	s_add_u32 s24, s22, 0x100
	s_addc_u32 s25, s23, 0
	s_cmp_eq_u32 s60, 40
	s_cselect_b32 s31, s3, s25
	s_cselect_b32 s30, s2, s24
	s_cselect_b32 s27, s21, s59
	s_cselect_b32 s26, s20, s58
	v_lshl_add_u64 v[164:165], s[22:23], 0, v[136:137]
	s_add_i32 m0, s41, 0xc000
	ds_read_b128 v[184:187], v171
	ds_read_b128 v[188:191], v171 offset:1024
	ds_read_b128 v[192:195], v171 offset:2048
	ds_read_b128 v[196:199], v171 offset:3072
	ds_read_b128 v[200:203], v171 offset:4096
	ds_read_b128 v[204:207], v171 offset:5120
	ds_read_b128 v[208:211], v171 offset:6144
	ds_read_b128 v[212:215], v171 offset:7168
	global_load_lds_dwordx4 v[164:165], off
	v_lshl_add_u64 v[164:165], s[22:23], 0, v[138:139]
	s_add_i32 m0, s41, 0xe000
	s_nop 0
	global_load_lds_dwordx4 v[164:165], off
	s_waitcnt vmcnt(8)
	s_waitcnt lgkmcnt(0)
	s_barrier
	s_waitcnt lgkmcnt(0)
	v_mfma_f32_16x16x32_f16 v[124:127], v[144:147], v[184:187], 0
	v_mfma_f32_16x16x32_f16 v[120:123], v[152:155], v[184:187], 0
	v_mfma_f32_16x16x32_f16 v[116:119], v[144:147], v[192:195], 0
	v_mfma_f32_16x16x32_f16 v[112:115], v[152:155], v[192:195], 0
	v_mfma_f32_16x16x32_f16 v[92:95], v[144:147], v[200:203], 0
	v_mfma_f32_16x16x32_f16 v[88:91], v[152:155], v[200:203], 0
	v_mfma_f32_16x16x32_f16 v[84:87], v[144:147], v[208:211], 0
	v_mfma_f32_16x16x32_f16 v[80:83], v[152:155], v[208:211], 0
	v_mfma_f32_16x16x32_f16 v[124:127], v[148:151], v[188:191], v[124:127]
	v_mfma_f32_16x16x32_f16 v[120:123], v[156:159], v[188:191], v[120:123]
	v_mfma_f32_16x16x32_f16 v[116:119], v[148:151], v[196:199], v[116:119]
	v_mfma_f32_16x16x32_f16 v[112:115], v[156:159], v[196:199], v[112:115]
	v_mfma_f32_16x16x32_f16 v[92:95], v[148:151], v[204:207], v[92:95]
	v_mfma_f32_16x16x32_f16 v[88:91], v[156:159], v[204:207], v[88:91]
	v_mfma_f32_16x16x32_f16 v[84:87], v[148:151], v[212:215], v[84:87]
	v_mfma_f32_16x16x32_f16 v[80:83], v[156:159], v[212:215], v[80:83]
	v_mfma_f32_16x16x32_f16 v[108:111], v[160:163], v[184:187], 0
	v_mfma_f32_16x16x32_f16 v[104:107], v[176:179], v[184:187], 0
	v_mfma_f32_16x16x32_f16 v[100:103], v[160:163], v[192:195], 0
	v_mfma_f32_16x16x32_f16 v[96:99], v[176:179], v[192:195], 0
	v_mfma_f32_16x16x32_f16 v[76:79], v[160:163], v[200:203], 0
	v_mfma_f32_16x16x32_f16 v[72:75], v[176:179], v[200:203], 0
	v_mfma_f32_16x16x32_f16 v[68:71], v[160:163], v[208:211], 0
	v_mfma_f32_16x16x32_f16 v[64:67], v[176:179], v[208:211], 0
	v_mfma_f32_16x16x32_f16 v[108:111], v[172:175], v[188:191], v[108:111]
	v_mfma_f32_16x16x32_f16 v[104:107], v[180:183], v[188:191], v[104:107]
	v_mfma_f32_16x16x32_f16 v[100:103], v[172:175], v[196:199], v[100:103]
	v_mfma_f32_16x16x32_f16 v[96:99], v[180:183], v[196:199], v[96:99]
	v_mfma_f32_16x16x32_f16 v[76:79], v[172:175], v[204:207], v[76:79]
	v_mfma_f32_16x16x32_f16 v[72:75], v[180:183], v[204:207], v[72:75]
	v_mfma_f32_16x16x32_f16 v[68:71], v[172:175], v[212:215], v[68:71]
	v_mfma_f32_16x16x32_f16 v[64:67], v[180:183], v[212:215], v[64:67]
	s_barrier
	s_add_i32 s22, s51, s40
	v_lshl_add_u64 v[164:165], s[26:27], 0, v[130:131]
	s_mov_b32 m0, s22
	ds_read_b128 v[184:187], v171 offset:16384
	ds_read_b128 v[188:191], v171 offset:17408
	ds_read_b128 v[192:195], v171 offset:18432
	ds_read_b128 v[196:199], v171 offset:19456
	ds_read_b128 v[200:203], v171 offset:20480
	ds_read_b128 v[204:207], v171 offset:21504
	ds_read_b128 v[208:211], v171 offset:22528
	ds_read_b128 v[212:215], v171 offset:23552
	global_load_lds_dwordx4 v[164:165], off
	s_add_i32 m0, s22, 0x2000
	s_add_u32 s22, s26, 0xb0000
	v_lshl_add_u64 v[216:217], s[26:27], 0, v[134:135]
	s_addc_u32 s23, s27, 0
	s_add_i32 s61, s52, s40
	global_load_lds_dwordx4 v[216:217], off
	v_lshl_add_u64 v[218:219], s[22:23], 0, v[130:131]
	s_mov_b32 m0, s61
	v_lshl_add_u64 v[220:221], s[30:31], 0, v[132:133]
	global_load_lds_dwordx4 v[218:219], off
	v_lshl_add_u64 v[218:219], s[22:23], 0, v[134:135]
	s_add_i32 m0, s61, 0x2000
	s_nop 0
	global_load_lds_dwordx4 v[218:219], off
	v_lshl_add_u64 v[218:219], s[30:31], 0, v[128:129]
	s_mov_b32 m0, s41
	s_nop 0
	global_load_lds_dwordx4 v[218:219], off
	s_mov_b32 m0, s42
	s_nop 0
	global_load_lds_dwordx4 v[220:221], off
	s_waitcnt vmcnt(8)
	s_waitcnt lgkmcnt(0)
	s_barrier
	s_waitcnt lgkmcnt(0)
	v_mfma_f32_16x16x32_f16 v[60:63], v[144:147], v[184:187], 0
	v_mfma_f32_16x16x32_f16 v[56:59], v[152:155], v[184:187], 0
	v_mfma_f32_16x16x32_f16 v[52:55], v[144:147], v[192:195], 0
	v_mfma_f32_16x16x32_f16 v[48:51], v[152:155], v[192:195], 0
	v_mfma_f32_16x16x32_f16 v[28:31], v[144:147], v[200:203], 0
	v_mfma_f32_16x16x32_f16 v[24:27], v[152:155], v[200:203], 0
	v_mfma_f32_16x16x32_f16 v[20:23], v[144:147], v[208:211], 0
	v_mfma_f32_16x16x32_f16 v[16:19], v[152:155], v[208:211], 0
	v_mfma_f32_16x16x32_f16 v[60:63], v[148:151], v[188:191], v[60:63]
	v_mfma_f32_16x16x32_f16 v[56:59], v[156:159], v[188:191], v[56:59]
	v_mfma_f32_16x16x32_f16 v[52:55], v[148:151], v[196:199], v[52:55]
	v_mfma_f32_16x16x32_f16 v[48:51], v[156:159], v[196:199], v[48:51]
	v_mfma_f32_16x16x32_f16 v[28:31], v[148:151], v[204:207], v[28:31]
	v_mfma_f32_16x16x32_f16 v[24:27], v[156:159], v[204:207], v[24:27]
	v_mfma_f32_16x16x32_f16 v[20:23], v[148:151], v[212:215], v[20:23]
	v_mfma_f32_16x16x32_f16 v[16:19], v[156:159], v[212:215], v[16:19]
	v_mfma_f32_16x16x32_f16 v[44:47], v[160:163], v[184:187], 0
	v_mfma_f32_16x16x32_f16 v[40:43], v[176:179], v[184:187], 0
	v_mfma_f32_16x16x32_f16 v[36:39], v[160:163], v[192:195], 0
	v_mfma_f32_16x16x32_f16 v[32:35], v[176:179], v[192:195], 0
	v_mfma_f32_16x16x32_f16 v[12:15], v[160:163], v[200:203], 0
	v_mfma_f32_16x16x32_f16 v[8:11], v[176:179], v[200:203], 0
	v_mfma_f32_16x16x32_f16 v[4:7], v[160:163], v[208:211], 0
	v_mfma_f32_16x16x32_f16 v[0:3], v[176:179], v[208:211], 0
	v_mfma_f32_16x16x32_f16 v[44:47], v[172:175], v[188:191], v[44:47]
	v_mfma_f32_16x16x32_f16 v[40:43], v[180:183], v[188:191], v[40:43]
	v_mfma_f32_16x16x32_f16 v[36:39], v[172:175], v[196:199], v[36:39]
	v_mfma_f32_16x16x32_f16 v[32:35], v[180:183], v[196:199], v[32:35]
	v_mfma_f32_16x16x32_f16 v[12:15], v[172:175], v[204:207], v[12:15]
	v_mfma_f32_16x16x32_f16 v[8:11], v[180:183], v[204:207], v[8:11]
	v_mfma_f32_16x16x32_f16 v[4:7], v[172:175], v[212:215], v[4:7]
	v_mfma_f32_16x16x32_f16 v[0:3], v[180:183], v[212:215], v[0:3]
	s_barrier
	s_add_i32 s61, 0, 0x18000
	s_add_i32 s62, 0, 0x1c000
	v_add_u32_e32 v156, s61, v167
	v_add_u32_e32 v180, s62, v167
	ds_read_b128 v[144:147], v156
	ds_read_b128 v[148:151], v156 offset:1024
	ds_read_b128 v[152:155], v156 offset:2048
	ds_read_b128 v[156:159], v156 offset:3072
	ds_read_b128 v[160:163], v180
	ds_read_b128 v[172:175], v180 offset:1024
	ds_read_b128 v[176:179], v180 offset:2048
	ds_read_b128 v[180:183], v180 offset:3072
	s_add_u32 s22, s30, 0xb0000
	s_addc_u32 s23, s31, 0
	s_mov_b32 m0, s43
	v_lshl_add_u64 v[222:223], s[22:23], 0, v[128:129]
	ds_read_b128 v[184:187], v171 offset:32768
	ds_read_b128 v[188:191], v171 offset:33792
	ds_read_b128 v[192:195], v171 offset:34816
	ds_read_b128 v[196:199], v171 offset:35840
	ds_read_b128 v[200:203], v171 offset:36864
	ds_read_b128 v[204:207], v171 offset:37888
	ds_read_b128 v[208:211], v171 offset:38912
	ds_read_b128 v[212:215], v171 offset:39936
	global_load_lds_dwordx4 v[222:223], off
	v_lshl_add_u64 v[222:223], s[22:23], 0, v[132:133]
	s_mov_b32 m0, s44
	s_nop 0
	global_load_lds_dwordx4 v[222:223], off
	s_waitcnt vmcnt(8)
	s_waitcnt lgkmcnt(0)
	s_barrier
	s_waitcnt lgkmcnt(0)
	v_mfma_f32_16x16x32_f16 v[124:127], v[144:147], v[184:187], v[124:127]
	v_mfma_f32_16x16x32_f16 v[120:123], v[152:155], v[184:187], v[120:123]
	v_mfma_f32_16x16x32_f16 v[116:119], v[144:147], v[192:195], v[116:119]
	v_mfma_f32_16x16x32_f16 v[112:115], v[152:155], v[192:195], v[112:115]
	v_mfma_f32_16x16x32_f16 v[92:95], v[144:147], v[200:203], v[92:95]
	v_mfma_f32_16x16x32_f16 v[88:91], v[152:155], v[200:203], v[88:91]
	v_mfma_f32_16x16x32_f16 v[84:87], v[144:147], v[208:211], v[84:87]
	v_mfma_f32_16x16x32_f16 v[80:83], v[152:155], v[208:211], v[80:83]
	v_mfma_f32_16x16x32_f16 v[124:127], v[148:151], v[188:191], v[124:127]
	v_mfma_f32_16x16x32_f16 v[120:123], v[156:159], v[188:191], v[120:123]
	v_mfma_f32_16x16x32_f16 v[116:119], v[148:151], v[196:199], v[116:119]
	v_mfma_f32_16x16x32_f16 v[112:115], v[156:159], v[196:199], v[112:115]
	v_mfma_f32_16x16x32_f16 v[92:95], v[148:151], v[204:207], v[92:95]
	v_mfma_f32_16x16x32_f16 v[88:91], v[156:159], v[204:207], v[88:91]
	v_mfma_f32_16x16x32_f16 v[84:87], v[148:151], v[212:215], v[84:87]
	v_mfma_f32_16x16x32_f16 v[80:83], v[156:159], v[212:215], v[80:83]
	v_mfma_f32_16x16x32_f16 v[108:111], v[160:163], v[184:187], v[108:111]
	v_mfma_f32_16x16x32_f16 v[104:107], v[176:179], v[184:187], v[104:107]
	v_mfma_f32_16x16x32_f16 v[100:103], v[160:163], v[192:195], v[100:103]
	v_mfma_f32_16x16x32_f16 v[96:99], v[176:179], v[192:195], v[96:99]
	v_mfma_f32_16x16x32_f16 v[76:79], v[160:163], v[200:203], v[76:79]
	v_mfma_f32_16x16x32_f16 v[72:75], v[176:179], v[200:203], v[72:75]
	v_mfma_f32_16x16x32_f16 v[68:71], v[160:163], v[208:211], v[68:71]
	v_mfma_f32_16x16x32_f16 v[64:67], v[176:179], v[208:211], v[64:67]
	v_mfma_f32_16x16x32_f16 v[108:111], v[172:175], v[188:191], v[108:111]
	v_mfma_f32_16x16x32_f16 v[104:107], v[180:183], v[188:191], v[104:107]
	v_mfma_f32_16x16x32_f16 v[100:103], v[172:175], v[196:199], v[100:103]
	v_mfma_f32_16x16x32_f16 v[96:99], v[180:183], v[196:199], v[96:99]
	v_mfma_f32_16x16x32_f16 v[76:79], v[172:175], v[204:207], v[76:79]
	v_mfma_f32_16x16x32_f16 v[72:75], v[180:183], v[204:207], v[72:75]
	v_mfma_f32_16x16x32_f16 v[68:71], v[172:175], v[212:215], v[68:71]
	v_mfma_f32_16x16x32_f16 v[64:67], v[180:183], v[212:215], v[64:67]
	s_barrier
	s_add_i32 s22, s61, s40
	v_lshl_add_u64 v[164:165], v[164:165], 0, s[10:11]
	s_mov_b32 m0, s22
	ds_read_b128 v[184:187], v171 offset:49152
	ds_read_b128 v[188:191], v171 offset:50176
	ds_read_b128 v[192:195], v171 offset:51200
	ds_read_b128 v[196:199], v171 offset:52224
	ds_read_b128 v[200:203], v171 offset:53248
	ds_read_b128 v[204:207], v171 offset:54272
	ds_read_b128 v[208:211], v171 offset:55296
	ds_read_b128 v[212:215], v171 offset:56320
	global_load_lds_dwordx4 v[164:165], off
	s_add_i32 m0, s22, 0x2000
	s_add_u32 s22, s26, 0xb0080
	v_lshl_add_u64 v[164:165], v[216:217], 0, s[10:11]
	s_addc_u32 s23, s27, 0
	s_add_i32 s26, s62, s40
	global_load_lds_dwordx4 v[164:165], off
	v_lshl_add_u64 v[164:165], s[22:23], 0, v[130:131]
	s_mov_b32 m0, s26
	s_nop 0
	global_load_lds_dwordx4 v[164:165], off
	v_lshl_add_u64 v[164:165], s[22:23], 0, v[134:135]
	s_add_i32 m0, s26, 0x2000
	s_nop 0
	global_load_lds_dwordx4 v[164:165], off
	v_lshl_add_u64 v[164:165], v[218:219], 0, s[10:11]
	s_mov_b32 m0, s48
	s_nop 0
	global_load_lds_dwordx4 v[164:165], off
	v_lshl_add_u64 v[164:165], v[220:221], 0, s[10:11]
	s_mov_b32 m0, s49
	s_nop 0
	global_load_lds_dwordx4 v[164:165], off
	s_waitcnt vmcnt(8)
	s_waitcnt lgkmcnt(0)
	s_barrier
	s_waitcnt lgkmcnt(0)
	v_mfma_f32_16x16x32_f16 v[60:63], v[144:147], v[184:187], v[60:63]
	v_mfma_f32_16x16x32_f16 v[56:59], v[152:155], v[184:187], v[56:59]
	v_mfma_f32_16x16x32_f16 v[52:55], v[144:147], v[192:195], v[52:55]
	v_mfma_f32_16x16x32_f16 v[48:51], v[152:155], v[192:195], v[48:51]
	v_mfma_f32_16x16x32_f16 v[28:31], v[144:147], v[200:203], v[28:31]
	v_mfma_f32_16x16x32_f16 v[24:27], v[152:155], v[200:203], v[24:27]
	v_mfma_f32_16x16x32_f16 v[20:23], v[144:147], v[208:211], v[20:23]
	v_mfma_f32_16x16x32_f16 v[16:19], v[152:155], v[208:211], v[16:19]
	v_mfma_f32_16x16x32_f16 v[60:63], v[148:151], v[188:191], v[60:63]
	v_mfma_f32_16x16x32_f16 v[56:59], v[156:159], v[188:191], v[56:59]
	v_mfma_f32_16x16x32_f16 v[52:55], v[148:151], v[196:199], v[52:55]
	v_mfma_f32_16x16x32_f16 v[48:51], v[156:159], v[196:199], v[48:51]
	v_mfma_f32_16x16x32_f16 v[28:31], v[148:151], v[204:207], v[28:31]
	v_mfma_f32_16x16x32_f16 v[24:27], v[156:159], v[204:207], v[24:27]
	v_mfma_f32_16x16x32_f16 v[20:23], v[148:151], v[212:215], v[20:23]
	v_mfma_f32_16x16x32_f16 v[16:19], v[156:159], v[212:215], v[16:19]
	v_mfma_f32_16x16x32_f16 v[44:47], v[160:163], v[184:187], v[44:47]
	v_mfma_f32_16x16x32_f16 v[40:43], v[176:179], v[184:187], v[40:43]
	v_mfma_f32_16x16x32_f16 v[36:39], v[160:163], v[192:195], v[36:39]
	v_mfma_f32_16x16x32_f16 v[32:35], v[176:179], v[192:195], v[32:35]
	v_mfma_f32_16x16x32_f16 v[12:15], v[160:163], v[200:203], v[12:15]
	v_mfma_f32_16x16x32_f16 v[8:11], v[176:179], v[200:203], v[8:11]
	v_mfma_f32_16x16x32_f16 v[4:7], v[160:163], v[208:211], v[4:7]
	v_mfma_f32_16x16x32_f16 v[0:3], v[176:179], v[208:211], v[0:3]
	v_mfma_f32_16x16x32_f16 v[44:47], v[172:175], v[188:191], v[44:47]
	v_mfma_f32_16x16x32_f16 v[40:43], v[180:183], v[188:191], v[40:43]
	v_mfma_f32_16x16x32_f16 v[36:39], v[172:175], v[196:199], v[36:39]
	v_mfma_f32_16x16x32_f16 v[32:35], v[180:183], v[196:199], v[32:35]
	v_mfma_f32_16x16x32_f16 v[12:15], v[172:175], v[204:207], v[12:15]
	v_mfma_f32_16x16x32_f16 v[8:11], v[180:183], v[204:207], v[8:11]
	v_mfma_f32_16x16x32_f16 v[4:7], v[172:175], v[212:215], v[4:7]
	v_mfma_f32_16x16x32_f16 v[0:3], v[180:183], v[212:215], v[0:3]
	s_barrier
	s_add_i32 s60, s60, 2
	s_add_u32 s58, s58, 0x100
	s_addc_u32 s59, s59, 0
	s_cmp_gt_u32 s60, 41
	s_mov_b64 s[22:23], s[24:25]
